# static s_setprio 1 for waves 4-7 at kernel entry; all per-cluster setprio flips in the 8 GEMM main loops deleted
# baseline (speedup 1.0000x reference)
; #define LAS __attribute__((address_space(3)))
; __device__ __forceinline__ unsigned xb_add(unsigned* p, unsigned v) { return __hip_atomic_fetch_add(p, v, __ATOMIC_RELAXED, __HIP_MEMORY_SCOPE_AGENT); }
; __device__ __forceinline__ unsigned xb_xcc_id() { return (unsigned)__builtin_amdgcn_s_getreg((3 << 11) | 20) & 0xFu; }
; __device__ __forceinline__ XcdBarrier xcd_barrier_post(unsigned* bar, volatile LAS unsigned* st) {
;     XcdBarrier b; b.bar = bar; b.x = xb_xcc_id(); b.st = st;
;     if (threadIdx.x == 0) (void)xb_add(&bar[XB_XCNT(b.x)], 1u);
;     return b;
; __global__ void __launch_bounds__(512, 2) mega_fwd(Params p) {
;     extern __shared__ __attribute__((aligned(16))) unsigned char shm[];
;     LAS unsigned char* lds = (LAS unsigned char*)shm;
;     cg::grid_group grid = cg::this_grid();
;     const int G = gridDim.x;
;     {
;         const int t0 = threadIdx.x;
;         if (t0 < 16) ((LAS unsigned*)(lds + LDS_BYTES - 64))[t0] = 0u;
;         __syncthreads();
;     }
;     XcdBarrier xbar = xcd_barrier_post((unsigned*)((float*)(p.ws + WS_CTL) + C_BAR), (volatile LAS unsigned*)(lds + LDS_BYTES - 32));
_Z8mega_fwd6Params:
	v_readfirstlane_b32 s101, v0
	s_and_b32 s101, s101, 0x3ff
	s_lshr_b32 s101, s101, 6
	s_cmp_ge_u32 s101, 4
	s_cbranch_scc0 .Lprio_done
	s_setprio 1
.Lprio_done:
	s_load_dwordx4 s[92:95], s[0:1], 0xc0
	s_load_dword s33, s[0:1], 0xd0
	s_add_u32 s10, s0, 0xc8
	v_and_b32_e32 v163, 0x3ff, v0
	s_addc_u32 s11, s1, 0
	v_cmp_gt_u32_e32 vcc, 16, v163
	s_and_saveexec_b64 s[4:5], vcc
	v_lshl_add_u32 v1, v163, 2, 0
	v_add_u32_e32 v1, 0x23fc0, v1
	v_mov_b32_e32 v2, 0
	ds_write_b32 v1, v2
	s_or_b64 exec, exec, s[4:5]
	s_waitcnt lgkmcnt(0)
	s_barrier
	s_add_u32 s36, s92, 0x400000
	s_getreg_b32 s3, hwreg(HW_REG_XCC_ID, 0, 4)
	s_addc_u32 s37, s93, 0
	s_and_b32 s3, s3, 15
	v_cmp_ne_u32_e64 s[8:9], 0, v163
	v_cmp_eq_u32_e64 s[22:23], 0, v163
	s_and_saveexec_b64 s[4:5], s[22:23]
	s_cbranch_execz .LBB0_5
	s_mov_b64 s[6:7], exec
	v_mbcnt_lo_u32_b32 v1, s6, 0
	v_mbcnt_hi_u32_b32 v1, s7, v1
	v_cmp_eq_u32_e32 vcc, 0, v1
	s_and_b64 s[12:13], exec, vcc
	s_mov_b64 exec, s[12:13]
	s_cbranch_execz .LBB0_5
	s_lshl_b32 s12, s3, 8
	s_bcnt1_i32_b64 s6, s[6:7]
	v_mov_b32_e32 v1, s12
	v_mov_b32_e32 v2, s6
	global_atomic_add v1, v2, s[36:37] offset:1024

; #define PG8_STAGE(bufoff, gbase, voff) do { _Pragma("unroll") for (int _i = 0; _i < 2; ++_i) \
;         __builtin_amdgcn_global_load_lds((const unsigned*)((const char*)(gbase) + (voff)[_i]), (LAS unsigned*)(lds + (bufoff) + ldsw + _i * 8192), 16, 0, 0); } while (0)
; #define PG8_LDA(dst, b, h) do { _Pragma("unroll") for (int m = 0; m < 4; ++m) _Pragma("unroll") for (int k = 0; k < 2; ++k) dst[m][k] = *(const LAS bf16x8*)(lds + PG8_SA(b, h) + aoff + m * 2048 + k * 1024); } while (0)
; #define PG8_LDB(dst, b, h) do { _Pragma("unroll") for (int n = 0; n < 2; ++n) _Pragma("unroll") for (int k = 0; k < 2; ++k) dst[n][k] = *(const LAS bf16x8*)(lds + PG8_SB(b, h) + boff + n * 2048 + k * 1024); } while (0)
; #define PG8_WAIT_V(n) asm volatile("s_waitcnt vmcnt(" #n ")" ::: "memory")
; #define PG8_WAIT_L(n) asm volatile("s_waitcnt lgkmcnt(" #n ")" ::: "memory")
; template <class Epi>
; __device__ __forceinline__ void gemm_phase(LAS unsigned char* lds, const Gemm g, const StaticOrder& S, const Epi& E) {
;     ...
;         for (int t = 0; t < nt; t += 2) {
;             const bool last = (t == nt - 2);
;             const char* a1 = cA + (size_t)(t + 1) * kstep;
;             const char* a2 = last ? nA : cA + (size_t)(t + 2) * kstep; const char* b2 = last ? nB : cB + (size_t)(t + 2) * kstep;
;             const char* a3 = a2 + kstep; const char* b3 = b2 + kstep;
;             PG8_LDB(B0, 0, 0); PG8_LDB(B1, 0, 1); PG8_SCHED; PG8_LDA(At, 0, 0); PG8_STAGE(PG8_SA(1, 1), a1 + hstepA, voffA);
;             PG8_WAIT_V(8); PG8_WAIT_L(0); PG8_BAR; PG8_MMA(0, 0, At, B0); PG8_MMA(0, 1, At, B1); PG8_BAR; PG8_SCHED;
;             PG8_LDA(At, 0, 1); PG8_STAGE(PG8_SB(0, 0), b2, voffB); PG8_STAGE(PG8_SB(0, 1), b2 + hstepB, voffB); PG8_STAGE(PG8_SA(0, 0), a2, voffA);
;             PG8_WAIT_V(8); PG8_WAIT_L(0); PG8_BAR; PG8_MMA(1, 0, At, B0); PG8_MMA(1, 1, At, B1); PG8_BAR; PG8_SCHED;
;             PG8_LDB(B0, 1, 0); PG8_LDB(B1, 1, 1); PG8_SCHED; PG8_LDA(At, 1, 0); PG8_STAGE(PG8_SA(0, 1), a2 + hstepA, voffA);
;             PG8_WAIT_V(8); PG8_WAIT_L(0); PG8_BAR; PG8_MMA(0, 0, At, B0); PG8_MMA(0, 1, At, B1); PG8_BAR; PG8_SCHED;
;             PG8_LDA(At, 1, 1); PG8_STAGE(PG8_SB(1, 0), b3, voffB); PG8_STAGE(PG8_SB(1, 1), b3 + hstepB, voffB); PG8_STAGE(PG8_SA(1, 0), a3, voffA);
;             PG8_WAIT_V(8); PG8_WAIT_L(0); PG8_BAR; PG8_MMA(1, 0, At, B0); PG8_MMA(1, 1, At, B1); PG8_BAR; PG8_SCHED;
.LBB0_2947:
	s_add_i32 s27, s6, 2
	s_add_u32 s28, s4, 0x80
	s_addc_u32 s7, s5, 0
	s_add_i32 s30, 0, 0x10000
	s_cmp_eq_u32 s96, s6
	s_cselect_b32 s7, s1, s7
	s_cselect_b32 s6, s0, s28
	v_add_u32_e32 v145, s30, v172
	s_cselect_b32 s29, s61, s9
	s_cselect_b32 s28, s60, s8
	s_add_i32 s31, 0, 0x14000
	ds_read_b128 v[146:149], v145
	ds_read_b128 v[150:153], v145 offset:1024
	ds_read_b128 v[154:157], v145 offset:2048
	ds_read_b128 v[178:181], v145 offset:3072
	v_add_u32_e32 v145, s31, v172
	ds_read_b128 v[182:185], v145
	ds_read_b128 v[186:189], v145 offset:1024
	ds_read_b128 v[190:193], v145 offset:2048
	ds_read_b128 v[194:197], v145 offset:3072
	v_lshl_add_u64 v[216:217], s[4:5], 0, v[142:143]
	s_add_i32 m0, s15, 0xc000
	ds_read_b128 v[198:201], v175
	ds_read_b128 v[202:205], v175 offset:1024
	ds_read_b128 v[206:209], v175 offset:2048
	ds_read_b128 v[222:225], v175 offset:3072
	ds_read_b128 v[226:229], v175 offset:4096
	ds_read_b128 v[230:233], v175 offset:5120
	ds_read_b128 v[234:237], v175 offset:6144
	ds_read_b128 v[238:241], v175 offset:7168
	global_load_lds_dwordx4 v[216:217], off
	v_lshl_add_u64 v[216:217], s[4:5], 0, v[140:141]
	s_add_i32 m0, s15, 0xe000
	s_nop 0
	global_load_lds_dwordx4 v[216:217], off
	s_waitcnt vmcnt(8)
	s_waitcnt lgkmcnt(0)
	s_barrier
	s_waitcnt lgkmcnt(0)
	v_mfma_f32_16x16x32_bf16 v[126:129], v[146:149], v[198:201], v[126:129]
	v_mfma_f32_16x16x32_bf16 v[122:125], v[154:157], v[198:201], v[122:125]
	v_mfma_f32_16x16x32_bf16 v[110:113], v[146:149], v[206:209], v[110:113]
	v_mfma_f32_16x16x32_bf16 v[106:109], v[154:157], v[206:209], v[106:109]
	v_mfma_f32_16x16x32_bf16 v[94:97], v[146:149], v[226:229], v[94:97]
	v_mfma_f32_16x16x32_bf16 v[90:93], v[154:157], v[226:229], v[90:93]
	v_mfma_f32_16x16x32_bf16 v[78:81], v[146:149], v[234:237], v[78:81]
	v_mfma_f32_16x16x32_bf16 v[74:77], v[154:157], v[234:237], v[74:77]
	v_mfma_f32_16x16x32_bf16 v[126:129], v[150:153], v[202:205], v[126:129]
	v_mfma_f32_16x16x32_bf16 v[122:125], v[178:181], v[202:205], v[122:125]
	v_mfma_f32_16x16x32_bf16 v[110:113], v[150:153], v[222:225], v[110:113]
	v_mfma_f32_16x16x32_bf16 v[106:109], v[178:181], v[222:225], v[106:109]
	v_mfma_f32_16x16x32_bf16 v[94:97], v[150:153], v[230:233], v[94:97]
	v_mfma_f32_16x16x32_bf16 v[90:93], v[178:181], v[230:233], v[90:93]
	v_mfma_f32_16x16x32_bf16 v[78:81], v[150:153], v[238:241], v[78:81]
	v_mfma_f32_16x16x32_bf16 v[74:77], v[178:181], v[238:241], v[74:77]
	v_mfma_f32_16x16x32_bf16 v[118:121], v[182:185], v[198:201], v[118:121]
	v_mfma_f32_16x16x32_bf16 v[114:117], v[190:193], v[198:201], v[114:117]
	v_mfma_f32_16x16x32_bf16 v[102:105], v[182:185], v[206:209], v[102:105]
	v_mfma_f32_16x16x32_bf16 v[98:101], v[190:193], v[206:209], v[98:101]
	v_mfma_f32_16x16x32_bf16 v[86:89], v[182:185], v[226:229], v[86:89]
	v_mfma_f32_16x16x32_bf16 v[82:85], v[190:193], v[226:229], v[82:85]
	v_mfma_f32_16x16x32_bf16 v[70:73], v[182:185], v[234:237], v[70:73]
	v_mfma_f32_16x16x32_bf16 v[66:69], v[190:193], v[234:237], v[66:69]
	v_mfma_f32_16x16x32_bf16 v[118:121], v[186:189], v[202:205], v[118:121]
	v_mfma_f32_16x16x32_bf16 v[114:117], v[194:197], v[202:205], v[114:117]
	v_mfma_f32_16x16x32_bf16 v[102:105], v[186:189], v[222:225], v[102:105]
	v_mfma_f32_16x16x32_bf16 v[98:101], v[194:197], v[222:225], v[98:101]
	v_mfma_f32_16x16x32_bf16 v[86:89], v[186:189], v[230:233], v[86:89]
	v_mfma_f32_16x16x32_bf16 v[82:85], v[194:197], v[230:233], v[82:85]
	v_mfma_f32_16x16x32_bf16 v[70:73], v[186:189], v[238:241], v[70:73]
	v_mfma_f32_16x16x32_bf16 v[66:69], v[194:197], v[238:241], v[66:69]
	s_barrier
	s_add_i32 s30, s30, s14
	v_lshl_add_u64 v[216:217], s[28:29], 0, v[134:135]
	s_mov_b32 m0, s30
	ds_read_b128 v[198:201], v175 offset:16384
	ds_read_b128 v[202:205], v175 offset:17408
	ds_read_b128 v[206:209], v175 offset:18432
	ds_read_b128 v[222:225], v175 offset:19456
	ds_read_b128 v[226:229], v175 offset:20480
	ds_read_b128 v[230:233], v175 offset:21504
	ds_read_b128 v[234:237], v175 offset:22528
	ds_read_b128 v[238:241], v175 offset:23552
	global_load_lds_dwordx4 v[216:217], off
	s_add_i32 m0, s30, 0x2000
	v_lshl_add_u64 v[218:219], s[28:29], 0, v[130:131]
	s_add_u32 s28, s28, s48
	s_addc_u32 s29, s29, s49
	s_add_i32 s30, s31, s14
	global_load_lds_dwordx4 v[218:219], off
	v_lshl_add_u64 v[242:243], s[28:29], 0, v[134:135]
	s_mov_b32 m0, s30
	v_lshl_add_u64 v[244:245], s[28:29], 0, v[130:131]
	global_load_lds_dwordx4 v[242:243], off
	s_add_i32 m0, s30, 0x2000
	v_lshl_add_u64 v[246:247], s[6:7], 0, v[136:137]
	global_load_lds_dwordx4 v[244:245], off
	s_mov_b32 m0, s15
	v_lshl_add_u64 v[248:249], s[6:7], 0, v[132:133]
	global_load_lds_dwordx4 v[246:247], off
	s_mov_b32 m0, s58
	s_nop 0
	global_load_lds_dwordx4 v[248:249], off
	s_waitcnt vmcnt(8)
	s_waitcnt lgkmcnt(0)
	s_barrier
; #define PG8_STAGE(bufoff, gbase, voff) do { _Pragma("unroll") for (int _i = 0; _i < 2; ++_i) \
;         __builtin_amdgcn_global_load_lds((const unsigned*)((const char*)(gbase) + (voff)[_i]), (LAS unsigned*)(lds + (bufoff) + ldsw + _i * 8192), 16, 0, 0); } while (0)
; #define PG8_LDA(dst, b, h) do { _Pragma("unroll") for (int m = 0; m < 4; ++m) _Pragma("unroll") for (int k = 0; k < 2; ++k) dst[m][k] = *(const LAS bf16x8*)(lds + PG8_SA(b, h) + aoff + m * 2048 + k * 1024); } while (0)
; #define PG8_LDB(dst, b, h) do { _Pragma("unroll") for (int n = 0; n < 2; ++n) _Pragma("unroll") for (int k = 0; k < 2; ++k) dst[n][k] = *(const LAS bf16x8*)(lds + PG8_SB(b, h) + boff + n * 2048 + k * 1024); } while (0)
; #define PG8_MMA(ai, bj, At, Bt) do { __builtin_amdgcn_s_setprio(1); _Pragma("unroll") for (int m = 0; m < 4; ++m) _Pragma("unroll") for (int n = 0; n < 2; ++n) _Pragma("unroll") for (int k = 0; k < 2; ++k) \
;         acc[ai][bj][m][n] = __builtin_amdgcn_mfma_f32_16x16x32_bf16(Bt[n][k], At[m][k], acc[ai][bj][m][n], 0, 0, 0); __builtin_amdgcn_s_setprio(0); } while (0)
; #define PG8_WAIT_V(n) asm volatile("s_waitcnt vmcnt(" #n ")" ::: "memory")
; #define PG8_WAIT_L(n) asm volatile("s_waitcnt lgkmcnt(" #n ")" ::: "memory")
; #define PG8_BAR __builtin_amdgcn_s_barrier()
; #define PG8_SCHED __builtin_amdgcn_sched_barrier(0)
; template <class Epi>
; __device__ __forceinline__ void gemm_phase(LAS unsigned char* lds, const Gemm g, const StaticOrder& S, const Epi& E) {
;     ...
;             PG8_WAIT_V(8); PG8_WAIT_L(0); PG8_BAR; PG8_MMA(0, 0, At, B0); PG8_MMA(0, 1, At, B1); PG8_BAR; PG8_SCHED;
;             PG8_LDA(At, 0, 1); PG8_STAGE(PG8_SB(0, 0), b2, voffB); PG8_STAGE(PG8_SB(0, 1), b2 + hstepB, voffB); PG8_STAGE(PG8_SA(0, 0), a2, voffA);
;             PG8_WAIT_V(8); PG8_WAIT_L(0); PG8_BAR; PG8_MMA(1, 0, At, B0); PG8_MMA(1, 1, At, B1); PG8_BAR; PG8_SCHED;
;             PG8_LDB(B0, 1, 0); PG8_LDB(B1, 1, 1); PG8_SCHED; PG8_LDA(At, 1, 0); PG8_STAGE(PG8_SA(0, 1), a2 + hstepA, voffA);
;             PG8_WAIT_V(8); PG8_WAIT_L(0); PG8_BAR; PG8_MMA(0, 0, At, B0); PG8_MMA(0, 1, At, B1); PG8_BAR; PG8_SCHED;
	s_waitcnt lgkmcnt(0)
	v_mfma_f32_16x16x32_bf16 v[60:63], v[146:149], v[198:201], v[60:63]
	v_mfma_f32_16x16x32_bf16 v[56:59], v[154:157], v[198:201], v[56:59]
	v_mfma_f32_16x16x32_bf16 v[44:47], v[146:149], v[206:209], v[44:47]
	v_mfma_f32_16x16x32_bf16 v[40:43], v[154:157], v[206:209], v[40:43]
	v_mfma_f32_16x16x32_bf16 v[28:31], v[146:149], v[226:229], v[28:31]
	v_mfma_f32_16x16x32_bf16 v[24:27], v[154:157], v[226:229], v[24:27]
	v_mfma_f32_16x16x32_bf16 v[12:15], v[146:149], v[234:237], v[12:15]
	v_mfma_f32_16x16x32_bf16 v[8:11], v[154:157], v[234:237], v[8:11]
	v_mfma_f32_16x16x32_bf16 v[60:63], v[150:153], v[202:205], v[60:63]
	v_mfma_f32_16x16x32_bf16 v[56:59], v[178:181], v[202:205], v[56:59]
	v_mfma_f32_16x16x32_bf16 v[44:47], v[150:153], v[222:225], v[44:47]
	v_mfma_f32_16x16x32_bf16 v[40:43], v[178:181], v[222:225], v[40:43]
	v_mfma_f32_16x16x32_bf16 v[28:31], v[150:153], v[230:233], v[28:31]
	v_mfma_f32_16x16x32_bf16 v[24:27], v[178:181], v[230:233], v[24:27]
	v_mfma_f32_16x16x32_bf16 v[12:15], v[150:153], v[238:241], v[12:15]
	v_mfma_f32_16x16x32_bf16 v[8:11], v[178:181], v[238:241], v[8:11]
	v_mfma_f32_16x16x32_bf16 v[52:55], v[182:185], v[198:201], v[52:55]
	v_mfma_f32_16x16x32_bf16 v[48:51], v[190:193], v[198:201], v[48:51]
	v_mfma_f32_16x16x32_bf16 v[36:39], v[182:185], v[206:209], v[36:39]
	v_mfma_f32_16x16x32_bf16 v[32:35], v[190:193], v[206:209], v[32:35]
	v_mfma_f32_16x16x32_bf16 v[20:23], v[182:185], v[226:229], v[20:23]
	v_mfma_f32_16x16x32_bf16 v[16:19], v[190:193], v[226:229], v[16:19]
	v_mfma_f32_16x16x32_bf16 v[4:7], v[182:185], v[234:237], v[4:7]
	v_mfma_f32_16x16x32_bf16 v[0:3], v[190:193], v[234:237], v[0:3]
	v_mfma_f32_16x16x32_bf16 v[52:55], v[186:189], v[202:205], v[52:55]
	v_mfma_f32_16x16x32_bf16 v[48:51], v[194:197], v[202:205], v[48:51]
	v_mfma_f32_16x16x32_bf16 v[36:39], v[186:189], v[222:225], v[36:39]
	v_mfma_f32_16x16x32_bf16 v[32:35], v[194:197], v[222:225], v[32:35]
	v_mfma_f32_16x16x32_bf16 v[20:23], v[186:189], v[230:233], v[20:23]
	v_mfma_f32_16x16x32_bf16 v[16:19], v[194:197], v[230:233], v[16:19]
	v_mfma_f32_16x16x32_bf16 v[4:7], v[186:189], v[238:241], v[4:7]
	v_mfma_f32_16x16x32_bf16 v[0:3], v[194:197], v[238:241], v[0:3]
	s_barrier
	s_add_i32 s28, 0, 0x18000
	v_add_u32_e32 v145, s28, v172
	s_add_i32 s29, 0, 0x1c000
	ds_read_b128 v[146:149], v145
	ds_read_b128 v[150:153], v145 offset:1024
	ds_read_b128 v[154:157], v145 offset:2048
	ds_read_b128 v[178:181], v145 offset:3072
	v_add_u32_e32 v145, s29, v172
	ds_read_b128 v[182:185], v145
	ds_read_b128 v[186:189], v145 offset:1024
	ds_read_b128 v[190:193], v145 offset:2048
	ds_read_b128 v[194:197], v145 offset:3072
	s_add_u32 s6, s6, s46
	s_addc_u32 s7, s7, s47
	s_mov_b32 m0, s59
	v_lshl_add_u64 v[250:251], s[6:7], 0, v[136:137]
	ds_read_b128 v[198:201], v175 offset:32768
	ds_read_b128 v[202:205], v175 offset:33792
	ds_read_b128 v[206:209], v175 offset:34816
	ds_read_b128 v[222:225], v175 offset:35840
	ds_read_b128 v[226:229], v175 offset:36864
	ds_read_b128 v[230:233], v175 offset:37888
	ds_read_b128 v[234:237], v175 offset:38912
	ds_read_b128 v[238:241], v175 offset:39936
	global_load_lds_dwordx4 v[250:251], off
	v_lshl_add_u64 v[250:251], s[6:7], 0, v[132:133]
	s_mov_b32 m0, s68
	s_nop 0
	global_load_lds_dwordx4 v[250:251], off
	s_waitcnt vmcnt(8)
	s_waitcnt lgkmcnt(0)
	s_barrier
	s_waitcnt lgkmcnt(0)
	v_mfma_f32_16x16x32_bf16 v[126:129], v[146:149], v[198:201], v[126:129]
	v_mfma_f32_16x16x32_bf16 v[122:125], v[154:157], v[198:201], v[122:125]
	v_mfma_f32_16x16x32_bf16 v[110:113], v[146:149], v[206:209], v[110:113]
	v_mfma_f32_16x16x32_bf16 v[106:109], v[154:157], v[206:209], v[106:109]
	v_mfma_f32_16x16x32_bf16 v[94:97], v[146:149], v[226:229], v[94:97]
	v_mfma_f32_16x16x32_bf16 v[90:93], v[154:157], v[226:229], v[90:93]
	v_mfma_f32_16x16x32_bf16 v[78:81], v[146:149], v[234:237], v[78:81]
	v_mfma_f32_16x16x32_bf16 v[74:77], v[154:157], v[234:237], v[74:77]
	v_mfma_f32_16x16x32_bf16 v[126:129], v[150:153], v[202:205], v[126:129]
	v_mfma_f32_16x16x32_bf16 v[122:125], v[178:181], v[202:205], v[122:125]
	v_mfma_f32_16x16x32_bf16 v[110:113], v[150:153], v[222:225], v[110:113]
	v_mfma_f32_16x16x32_bf16 v[106:109], v[178:181], v[222:225], v[106:109]
	v_mfma_f32_16x16x32_bf16 v[94:97], v[150:153], v[230:233], v[94:97]
	v_mfma_f32_16x16x32_bf16 v[90:93], v[178:181], v[230:233], v[90:93]
	v_mfma_f32_16x16x32_bf16 v[78:81], v[150:153], v[238:241], v[78:81]
	v_mfma_f32_16x16x32_bf16 v[74:77], v[178:181], v[238:241], v[74:77]
	v_mfma_f32_16x16x32_bf16 v[118:121], v[182:185], v[198:201], v[118:121]
	v_mfma_f32_16x16x32_bf16 v[114:117], v[190:193], v[198:201], v[114:117]
	v_mfma_f32_16x16x32_bf16 v[102:105], v[182:185], v[206:209], v[102:105]
	v_mfma_f32_16x16x32_bf16 v[98:101], v[190:193], v[206:209], v[98:101]
	v_mfma_f32_16x16x32_bf16 v[86:89], v[182:185], v[226:229], v[86:89]
	v_mfma_f32_16x16x32_bf16 v[82:85], v[190:193], v[226:229], v[82:85]
	v_mfma_f32_16x16x32_bf16 v[70:73], v[182:185], v[234:237], v[70:73]
	v_mfma_f32_16x16x32_bf16 v[66:69], v[190:193], v[234:237], v[66:69]
	v_mfma_f32_16x16x32_bf16 v[118:121], v[186:189], v[202:205], v[118:121]
	v_mfma_f32_16x16x32_bf16 v[114:117], v[194:197], v[202:205], v[114:117]
	v_mfma_f32_16x16x32_bf16 v[102:105], v[186:189], v[222:225], v[102:105]
	v_mfma_f32_16x16x32_bf16 v[98:101], v[194:197], v[222:225], v[98:101]
	v_mfma_f32_16x16x32_bf16 v[86:89], v[186:189], v[230:233], v[86:89]
	v_mfma_f32_16x16x32_bf16 v[82:85], v[194:197], v[230:233], v[82:85]
	v_mfma_f32_16x16x32_bf16 v[70:73], v[186:189], v[238:241], v[70:73]
	v_mfma_f32_16x16x32_bf16 v[66:69], v[194:197], v[238:241], v[66:69]
	s_barrier
; #define PG8_STAGE(bufoff, gbase, voff) do { _Pragma("unroll") for (int _i = 0; _i < 2; ++_i) \
;         __builtin_amdgcn_global_load_lds((const unsigned*)((const char*)(gbase) + (voff)[_i]), (LAS unsigned*)(lds + (bufoff) + ldsw + _i * 8192), 16, 0, 0); } while (0)
; #define PG8_LDA(dst, b, h) do { _Pragma("unroll") for (int m = 0; m < 4; ++m) _Pragma("unroll") for (int k = 0; k < 2; ++k) dst[m][k] = *(const LAS bf16x8*)(lds + PG8_SA(b, h) + aoff + m * 2048 + k * 1024); } while (0)
; #define PG8_MMA(ai, bj, At, Bt) do { __builtin_amdgcn_s_setprio(1); _Pragma("unroll") for (int m = 0; m < 4; ++m) _Pragma("unroll") for (int n = 0; n < 2; ++n) _Pragma("unroll") for (int k = 0; k < 2; ++k) \
;         acc[ai][bj][m][n] = __builtin_amdgcn_mfma_f32_16x16x32_bf16(Bt[n][k], At[m][k], acc[ai][bj][m][n], 0, 0, 0); __builtin_amdgcn_s_setprio(0); } while (0)
; #define PG8_WAIT_V(n) asm volatile("s_waitcnt vmcnt(" #n ")" ::: "memory")
; #define PG8_WAIT_L(n) asm volatile("s_waitcnt lgkmcnt(" #n ")" ::: "memory")
; #define PG8_BAR __builtin_amdgcn_s_barrier()
; #define PG8_SCHED __builtin_amdgcn_sched_barrier(0)
; template <class Epi>
; __device__ __forceinline__ void gemm_phase(LAS unsigned char* lds, const Gemm g, const StaticOrder& S, const Epi& E) {
;     ...
;             PG8_LDA(At, 1, 1); PG8_STAGE(PG8_SB(1, 0), b3, voffB); PG8_STAGE(PG8_SB(1, 1), b3 + hstepB, voffB); PG8_STAGE(PG8_SA(1, 0), a3, voffA);
;             PG8_WAIT_V(8); PG8_WAIT_L(0); PG8_BAR; PG8_MMA(1, 0, At, B0); PG8_MMA(1, 1, At, B1); PG8_BAR; PG8_SCHED;
;         }
	s_add_i32 s6, s28, s14
	v_lshl_add_u64 v[216:217], v[216:217], 0, s[82:83]
	s_mov_b32 m0, s6
	ds_read_b128 v[198:201], v175 offset:49152
	ds_read_b128 v[202:205], v175 offset:50176
	ds_read_b128 v[206:209], v175 offset:51200
	ds_read_b128 v[222:225], v175 offset:52224
	ds_read_b128 v[226:229], v175 offset:53248
	ds_read_b128 v[230:233], v175 offset:54272
	ds_read_b128 v[234:237], v175 offset:55296
	ds_read_b128 v[238:241], v175 offset:56320
	global_load_lds_dwordx4 v[216:217], off
	v_lshl_add_u64 v[216:217], v[218:219], 0, s[82:83]
	s_add_i32 m0, s6, 0x2000
	s_add_i32 s6, s29, s14
	global_load_lds_dwordx4 v[216:217], off
	v_lshl_add_u64 v[216:217], v[242:243], 0, s[82:83]
	s_mov_b32 m0, s6
	s_nop 0
	global_load_lds_dwordx4 v[216:217], off
	v_lshl_add_u64 v[216:217], v[244:245], 0, s[82:83]
	s_add_i32 m0, s6, 0x2000
	s_nop 0
	global_load_lds_dwordx4 v[216:217], off
	v_lshl_add_u64 v[216:217], v[246:247], 0, s[82:83]
	s_mov_b32 m0, s69
	s_nop 0
	global_load_lds_dwordx4 v[216:217], off
	v_lshl_add_u64 v[216:217], v[248:249], 0, s[82:83]
	s_mov_b32 m0, s84
	s_nop 0
	global_load_lds_dwordx4 v[216:217], off
	s_waitcnt vmcnt(8)
	s_waitcnt lgkmcnt(0)
	s_barrier
	s_waitcnt lgkmcnt(0)
	v_mfma_f32_16x16x32_bf16 v[60:63], v[146:149], v[198:201], v[60:63]
	v_mfma_f32_16x16x32_bf16 v[56:59], v[154:157], v[198:201], v[56:59]
	v_mfma_f32_16x16x32_bf16 v[44:47], v[146:149], v[206:209], v[44:47]
	v_mfma_f32_16x16x32_bf16 v[40:43], v[154:157], v[206:209], v[40:43]
	v_mfma_f32_16x16x32_bf16 v[28:31], v[146:149], v[226:229], v[28:31]
	v_mfma_f32_16x16x32_bf16 v[24:27], v[154:157], v[226:229], v[24:27]
	v_mfma_f32_16x16x32_bf16 v[12:15], v[146:149], v[234:237], v[12:15]
	v_mfma_f32_16x16x32_bf16 v[8:11], v[154:157], v[234:237], v[8:11]
	v_mfma_f32_16x16x32_bf16 v[60:63], v[150:153], v[202:205], v[60:63]
	v_mfma_f32_16x16x32_bf16 v[56:59], v[178:181], v[202:205], v[56:59]
	v_mfma_f32_16x16x32_bf16 v[44:47], v[150:153], v[222:225], v[44:47]
	v_mfma_f32_16x16x32_bf16 v[40:43], v[178:181], v[222:225], v[40:43]
	v_mfma_f32_16x16x32_bf16 v[28:31], v[150:153], v[230:233], v[28:31]
	v_mfma_f32_16x16x32_bf16 v[24:27], v[178:181], v[230:233], v[24:27]
	v_mfma_f32_16x16x32_bf16 v[12:15], v[150:153], v[238:241], v[12:15]
	v_mfma_f32_16x16x32_bf16 v[8:11], v[178:181], v[238:241], v[8:11]
	v_mfma_f32_16x16x32_bf16 v[52:55], v[182:185], v[198:201], v[52:55]
	v_mfma_f32_16x16x32_bf16 v[48:51], v[190:193], v[198:201], v[48:51]
	v_mfma_f32_16x16x32_bf16 v[36:39], v[182:185], v[206:209], v[36:39]
	v_mfma_f32_16x16x32_bf16 v[32:35], v[190:193], v[206:209], v[32:35]
	v_mfma_f32_16x16x32_bf16 v[20:23], v[182:185], v[226:229], v[20:23]
	v_mfma_f32_16x16x32_bf16 v[16:19], v[190:193], v[226:229], v[16:19]
	v_mfma_f32_16x16x32_bf16 v[4:7], v[182:185], v[234:237], v[4:7]
	v_mfma_f32_16x16x32_bf16 v[0:3], v[190:193], v[234:237], v[0:3]
	v_mfma_f32_16x16x32_bf16 v[52:55], v[186:189], v[202:205], v[52:55]
	v_mfma_f32_16x16x32_bf16 v[48:51], v[194:197], v[202:205], v[48:51]
	v_mfma_f32_16x16x32_bf16 v[36:39], v[186:189], v[222:225], v[36:39]
	v_mfma_f32_16x16x32_bf16 v[32:35], v[194:197], v[222:225], v[32:35]
	v_mfma_f32_16x16x32_bf16 v[20:23], v[186:189], v[230:233], v[20:23]
	v_mfma_f32_16x16x32_bf16 v[16:19], v[194:197], v[230:233], v[16:19]
	v_mfma_f32_16x16x32_bf16 v[4:7], v[186:189], v[238:241], v[4:7]
	v_mfma_f32_16x16x32_bf16 v[0:3], v[194:197], v[238:241], v[0:3]
	s_barrier
	s_add_u32 s8, s8, 0x100
	s_addc_u32 s9, s9, 0
	s_add_u32 s4, s4, 0x100
	s_addc_u32 s5, s5, 0
	s_cmp_ge_i32 s27, s20
	s_mov_b32 s6, s27
	s_cbranch_scc0 .LBB0_2947

; #define PG8_STAGE(bufoff, gbase, voff) do { _Pragma("unroll") for (int _i = 0; _i < 2; ++_i) \
;         __builtin_amdgcn_global_load_lds((const unsigned*)((const char*)(gbase) + (voff)[_i]), (LAS unsigned*)(lds + (bufoff) + ldsw + _i * 8192), 16, 0, 0); } while (0)
; #define PG8_LDA(dst, b, h) do { _Pragma("unroll") for (int m = 0; m < 4; ++m) _Pragma("unroll") for (int k = 0; k < 2; ++k) dst[m][k] = *(const LAS bf16x8*)(lds + PG8_SA(b, h) + aoff + m * 2048 + k * 1024); } while (0)
; #define PG8_LDB(dst, b, h) do { _Pragma("unroll") for (int n = 0; n < 2; ++n) _Pragma("unroll") for (int k = 0; k < 2; ++k) dst[n][k] = *(const LAS bf16x8*)(lds + PG8_SB(b, h) + boff + n * 2048 + k * 1024); } while (0)
; #define PG8_MMA(ai, bj, At, Bt) do { __builtin_amdgcn_s_setprio(1); _Pragma("unroll") for (int m = 0; m < 4; ++m) _Pragma("unroll") for (int n = 0; n < 2; ++n) _Pragma("unroll") for (int k = 0; k < 2; ++k) \
;         acc[ai][bj][m][n] = __builtin_amdgcn_mfma_f32_16x16x32_bf16(Bt[n][k], At[m][k], acc[ai][bj][m][n], 0, 0, 0); __builtin_amdgcn_s_setprio(0); } while (0)
; #define PG8_WAIT_V(n) asm volatile("s_waitcnt vmcnt(" #n ")" ::: "memory")
; #define PG8_WAIT_L(n) asm volatile("s_waitcnt lgkmcnt(" #n ")" ::: "memory")
; #define PG8_BAR __builtin_amdgcn_s_barrier()
; #define PG8_SCHED __builtin_amdgcn_sched_barrier(0)
; template <class Epi>
; __device__ __forceinline__ void gemm_phase(LAS unsigned char* lds, const Gemm g, const StaticOrder& S, const Epi& E) {
;     ...
;         for (int t = 0; t < nt; t += 2) {
;             const bool last = (t == nt - 2);
;             const char* a1 = cA + (size_t)(t + 1) * kstep;
;             const char* a2 = last ? nA : cA + (size_t)(t + 2) * kstep; const char* b2 = last ? nB : cB + (size_t)(t + 2) * kstep;
;             const char* a3 = a2 + kstep; const char* b3 = b2 + kstep;
;             PG8_LDB(B0, 0, 0); PG8_LDB(B1, 0, 1); PG8_SCHED; PG8_LDA(At, 0, 0); PG8_STAGE(PG8_SA(1, 1), a1 + hstepA, voffA);
;             PG8_WAIT_V(8); PG8_WAIT_L(0); PG8_BAR; PG8_MMA(0, 0, At, B0); PG8_MMA(0, 1, At, B1); PG8_BAR; PG8_SCHED;
;             PG8_LDA(At, 0, 1); PG8_STAGE(PG8_SB(0, 0), b2, voffB); PG8_STAGE(PG8_SB(0, 1), b2 + hstepB, voffB); PG8_STAGE(PG8_SA(0, 0), a2, voffA);
;             PG8_WAIT_V(8); PG8_WAIT_L(0); PG8_BAR; PG8_MMA(1, 0, At, B0); PG8_MMA(1, 1, At, B1); PG8_BAR; PG8_SCHED;
.LBB0_3152:
	s_add_i32 s28, s10, 2
	s_add_u32 s29, s58, 0x80
	s_addc_u32 s11, s59, 0
	s_add_i32 s34, 0, 0x10000
	s_cmp_eq_u32 s65, s10
	s_cselect_b32 s11, s1, s11
	s_cselect_b32 s10, s0, s29
	s_cselect_b32 s31, s7, s27
	s_cselect_b32 s30, s6, s26
	s_add_i32 s29, 0, 0x14000
	v_add_u32_e32 v142, s34, v181
	v_add_u32_e32 v186, s29, v181
	ds_read_b128 v[130:133], v142
	ds_read_b128 v[134:137], v142 offset:1024
	ds_read_b128 v[138:141], v142 offset:2048
	ds_read_b128 v[142:145], v142 offset:3072
	ds_read_b128 v[146:149], v186
	ds_read_b128 v[150:153], v186 offset:1024
	ds_read_b128 v[154:157], v186 offset:2048
	ds_read_b128 v[186:189], v186 offset:3072
	v_lshl_add_u64 v[202:203], s[58:59], 0, v[184:185]
	s_add_i32 m0, s21, 0xc000
	ds_read_b128 v[190:193], v204
	ds_read_b128 v[194:197], v204 offset:1024
	ds_read_b128 v[198:201], v204 offset:2048
	ds_read_b128 v[206:209], v204 offset:3072
	ds_read_b128 v[222:225], v204 offset:4096
	ds_read_b128 v[226:229], v204 offset:5120
	ds_read_b128 v[230:233], v204 offset:6144
	ds_read_b128 v[234:237], v204 offset:7168
	global_load_lds_dwordx4 v[202:203], off
	v_lshl_add_u64 v[202:203], s[58:59], 0, v[182:183]
	s_add_i32 m0, s21, 0xe000
	s_nop 0
	global_load_lds_dwordx4 v[202:203], off
	s_waitcnt vmcnt(8)
	s_waitcnt lgkmcnt(0)
	s_barrier
	s_waitcnt lgkmcnt(0)
	v_mfma_f32_16x16x32_bf16 v[126:129], v[130:133], v[190:193], v[126:129]
	v_mfma_f32_16x16x32_bf16 v[122:125], v[138:141], v[190:193], v[122:125]
	v_mfma_f32_16x16x32_bf16 v[110:113], v[130:133], v[198:201], v[110:113]
	v_mfma_f32_16x16x32_bf16 v[106:109], v[138:141], v[198:201], v[106:109]
	v_mfma_f32_16x16x32_bf16 v[94:97], v[130:133], v[222:225], v[94:97]
	v_mfma_f32_16x16x32_bf16 v[90:93], v[138:141], v[222:225], v[90:93]
	v_mfma_f32_16x16x32_bf16 v[78:81], v[130:133], v[230:233], v[78:81]
	v_mfma_f32_16x16x32_bf16 v[74:77], v[138:141], v[230:233], v[74:77]
	v_mfma_f32_16x16x32_bf16 v[126:129], v[134:137], v[194:197], v[126:129]
	v_mfma_f32_16x16x32_bf16 v[122:125], v[142:145], v[194:197], v[122:125]
	v_mfma_f32_16x16x32_bf16 v[110:113], v[134:137], v[206:209], v[110:113]
	v_mfma_f32_16x16x32_bf16 v[106:109], v[142:145], v[206:209], v[106:109]
	v_mfma_f32_16x16x32_bf16 v[94:97], v[134:137], v[226:229], v[94:97]
	v_mfma_f32_16x16x32_bf16 v[90:93], v[142:145], v[226:229], v[90:93]
	v_mfma_f32_16x16x32_bf16 v[78:81], v[134:137], v[234:237], v[78:81]
	v_mfma_f32_16x16x32_bf16 v[74:77], v[142:145], v[234:237], v[74:77]
	v_mfma_f32_16x16x32_bf16 v[118:121], v[146:149], v[190:193], v[118:121]
	v_mfma_f32_16x16x32_bf16 v[114:117], v[154:157], v[190:193], v[114:117]
	v_mfma_f32_16x16x32_bf16 v[102:105], v[146:149], v[198:201], v[102:105]
	v_mfma_f32_16x16x32_bf16 v[98:101], v[154:157], v[198:201], v[98:101]
	v_mfma_f32_16x16x32_bf16 v[86:89], v[146:149], v[222:225], v[86:89]
	v_mfma_f32_16x16x32_bf16 v[82:85], v[154:157], v[222:225], v[82:85]
	v_mfma_f32_16x16x32_bf16 v[70:73], v[146:149], v[230:233], v[70:73]
	v_mfma_f32_16x16x32_bf16 v[66:69], v[154:157], v[230:233], v[66:69]
	v_mfma_f32_16x16x32_bf16 v[118:121], v[150:153], v[194:197], v[118:121]
	v_mfma_f32_16x16x32_bf16 v[114:117], v[186:189], v[194:197], v[114:117]
	v_mfma_f32_16x16x32_bf16 v[102:105], v[150:153], v[206:209], v[102:105]
	v_mfma_f32_16x16x32_bf16 v[98:101], v[186:189], v[206:209], v[98:101]
	v_mfma_f32_16x16x32_bf16 v[86:89], v[150:153], v[226:229], v[86:89]
	v_mfma_f32_16x16x32_bf16 v[82:85], v[186:189], v[226:229], v[82:85]
	v_mfma_f32_16x16x32_bf16 v[70:73], v[150:153], v[234:237], v[70:73]
	v_mfma_f32_16x16x32_bf16 v[66:69], v[186:189], v[234:237], v[66:69]
	s_barrier
	s_add_i32 s34, s34, s20
	v_lshl_add_u64 v[202:203], s[30:31], 0, v[176:177]
	s_mov_b32 m0, s34
	ds_read_b128 v[190:193], v204 offset:16384
	ds_read_b128 v[194:197], v204 offset:17408
	ds_read_b128 v[198:201], v204 offset:18432
	ds_read_b128 v[206:209], v204 offset:19456
	ds_read_b128 v[222:225], v204 offset:20480
	ds_read_b128 v[226:229], v204 offset:21504
	ds_read_b128 v[230:233], v204 offset:22528
	ds_read_b128 v[234:237], v204 offset:23552
	global_load_lds_dwordx4 v[202:203], off
	s_add_i32 m0, s34, 0x2000
	v_lshl_add_u64 v[216:217], s[30:31], 0, v[172:173]
	s_add_u32 s30, s30, s42
	s_addc_u32 s31, s31, s43
	s_add_i32 s29, s29, s20
	global_load_lds_dwordx4 v[216:217], off
	v_lshl_add_u64 v[218:219], s[30:31], 0, v[176:177]
	s_mov_b32 m0, s29
	v_lshl_add_u64 v[238:239], s[30:31], 0, v[172:173]
	global_load_lds_dwordx4 v[218:219], off
	s_add_i32 m0, s29, 0x2000
	v_lshl_add_u64 v[240:241], s[10:11], 0, v[178:179]
	global_load_lds_dwordx4 v[238:239], off
	s_mov_b32 m0, s21
	v_lshl_add_u64 v[242:243], s[10:11], 0, v[174:175]
	global_load_lds_dwordx4 v[240:241], off
	s_mov_b32 m0, s22
	s_nop 0
	global_load_lds_dwordx4 v[242:243], off
	s_waitcnt vmcnt(8)
	s_waitcnt lgkmcnt(0)
	s_barrier
; #define PG8_STAGE(bufoff, gbase, voff) do { _Pragma("unroll") for (int _i = 0; _i < 2; ++_i) \
;         __builtin_amdgcn_global_load_lds((const unsigned*)((const char*)(gbase) + (voff)[_i]), (LAS unsigned*)(lds + (bufoff) + ldsw + _i * 8192), 16, 0, 0); } while (0)
; #define PG8_LDA(dst, b, h) do { _Pragma("unroll") for (int m = 0; m < 4; ++m) _Pragma("unroll") for (int k = 0; k < 2; ++k) dst[m][k] = *(const LAS bf16x8*)(lds + PG8_SA(b, h) + aoff + m * 2048 + k * 1024); } while (0)
; #define PG8_LDB(dst, b, h) do { _Pragma("unroll") for (int n = 0; n < 2; ++n) _Pragma("unroll") for (int k = 0; k < 2; ++k) dst[n][k] = *(const LAS bf16x8*)(lds + PG8_SB(b, h) + boff + n * 2048 + k * 1024); } while (0)
; #define PG8_MMA(ai, bj, At, Bt) do { __builtin_amdgcn_s_setprio(1); _Pragma("unroll") for (int m = 0; m < 4; ++m) _Pragma("unroll") for (int n = 0; n < 2; ++n) _Pragma("unroll") for (int k = 0; k < 2; ++k) \
;         acc[ai][bj][m][n] = __builtin_amdgcn_mfma_f32_16x16x32_bf16(Bt[n][k], At[m][k], acc[ai][bj][m][n], 0, 0, 0); __builtin_amdgcn_s_setprio(0); } while (0)
; #define PG8_WAIT_V(n) asm volatile("s_waitcnt vmcnt(" #n ")" ::: "memory")
; #define PG8_WAIT_L(n) asm volatile("s_waitcnt lgkmcnt(" #n ")" ::: "memory")
; #define PG8_BAR __builtin_amdgcn_s_barrier()
; #define PG8_SCHED __builtin_amdgcn_sched_barrier(0)
; template <class Epi>
; __device__ __forceinline__ void gemm_phase(LAS unsigned char* lds, const Gemm g, const StaticOrder& S, const Epi& E) {
;     ...
;             PG8_WAIT_V(8); PG8_WAIT_L(0); PG8_BAR; PG8_MMA(0, 0, At, B0); PG8_MMA(0, 1, At, B1); PG8_BAR; PG8_SCHED;
;             PG8_LDA(At, 0, 1); PG8_STAGE(PG8_SB(0, 0), b2, voffB); PG8_STAGE(PG8_SB(0, 1), b2 + hstepB, voffB); PG8_STAGE(PG8_SA(0, 0), a2, voffA);
;             PG8_WAIT_V(8); PG8_WAIT_L(0); PG8_BAR; PG8_MMA(1, 0, At, B0); PG8_MMA(1, 1, At, B1); PG8_BAR; PG8_SCHED;
;             PG8_LDB(B0, 1, 0); PG8_LDB(B1, 1, 1); PG8_SCHED; PG8_LDA(At, 1, 0); PG8_STAGE(PG8_SA(0, 1), a2 + hstepA, voffA);
;             PG8_WAIT_V(8); PG8_WAIT_L(0); PG8_BAR; PG8_MMA(0, 0, At, B0); PG8_MMA(0, 1, At, B1); PG8_BAR; PG8_SCHED;
	s_waitcnt lgkmcnt(0)
	v_mfma_f32_16x16x32_bf16 v[60:63], v[130:133], v[190:193], v[60:63]
	v_mfma_f32_16x16x32_bf16 v[56:59], v[138:141], v[190:193], v[56:59]
	v_mfma_f32_16x16x32_bf16 v[44:47], v[130:133], v[198:201], v[44:47]
	v_mfma_f32_16x16x32_bf16 v[40:43], v[138:141], v[198:201], v[40:43]
	v_mfma_f32_16x16x32_bf16 v[28:31], v[130:133], v[222:225], v[28:31]
	v_mfma_f32_16x16x32_bf16 v[24:27], v[138:141], v[222:225], v[24:27]
	v_mfma_f32_16x16x32_bf16 v[12:15], v[130:133], v[230:233], v[12:15]
	v_mfma_f32_16x16x32_bf16 v[8:11], v[138:141], v[230:233], v[8:11]
	v_mfma_f32_16x16x32_bf16 v[60:63], v[134:137], v[194:197], v[60:63]
	v_mfma_f32_16x16x32_bf16 v[56:59], v[142:145], v[194:197], v[56:59]
	v_mfma_f32_16x16x32_bf16 v[44:47], v[134:137], v[206:209], v[44:47]
	v_mfma_f32_16x16x32_bf16 v[40:43], v[142:145], v[206:209], v[40:43]
	v_mfma_f32_16x16x32_bf16 v[28:31], v[134:137], v[226:229], v[28:31]
	v_mfma_f32_16x16x32_bf16 v[24:27], v[142:145], v[226:229], v[24:27]
	v_mfma_f32_16x16x32_bf16 v[12:15], v[134:137], v[234:237], v[12:15]
	v_mfma_f32_16x16x32_bf16 v[8:11], v[142:145], v[234:237], v[8:11]
	v_mfma_f32_16x16x32_bf16 v[52:55], v[146:149], v[190:193], v[52:55]
	v_mfma_f32_16x16x32_bf16 v[48:51], v[154:157], v[190:193], v[48:51]
	v_mfma_f32_16x16x32_bf16 v[36:39], v[146:149], v[198:201], v[36:39]
	v_mfma_f32_16x16x32_bf16 v[32:35], v[154:157], v[198:201], v[32:35]
	v_mfma_f32_16x16x32_bf16 v[20:23], v[146:149], v[222:225], v[20:23]
	v_mfma_f32_16x16x32_bf16 v[16:19], v[154:157], v[222:225], v[16:19]
	v_mfma_f32_16x16x32_bf16 v[4:7], v[146:149], v[230:233], v[4:7]
	v_mfma_f32_16x16x32_bf16 v[0:3], v[154:157], v[230:233], v[0:3]
	v_mfma_f32_16x16x32_bf16 v[52:55], v[150:153], v[194:197], v[52:55]
	v_mfma_f32_16x16x32_bf16 v[48:51], v[186:189], v[194:197], v[48:51]
	v_mfma_f32_16x16x32_bf16 v[36:39], v[150:153], v[206:209], v[36:39]
	v_mfma_f32_16x16x32_bf16 v[32:35], v[186:189], v[206:209], v[32:35]
	v_mfma_f32_16x16x32_bf16 v[20:23], v[150:153], v[226:229], v[20:23]
	v_mfma_f32_16x16x32_bf16 v[16:19], v[186:189], v[226:229], v[16:19]
	v_mfma_f32_16x16x32_bf16 v[4:7], v[150:153], v[234:237], v[4:7]
	v_mfma_f32_16x16x32_bf16 v[0:3], v[186:189], v[234:237], v[0:3]
	s_barrier
	s_add_i32 s29, 0, 0x18000
	s_add_i32 s30, 0, 0x1c000
	v_add_u32_e32 v142, s29, v181
	v_add_u32_e32 v186, s30, v181
	ds_read_b128 v[130:133], v142
	ds_read_b128 v[134:137], v142 offset:1024
	ds_read_b128 v[138:141], v142 offset:2048
	ds_read_b128 v[142:145], v142 offset:3072
	ds_read_b128 v[146:149], v186
	ds_read_b128 v[150:153], v186 offset:1024
	ds_read_b128 v[154:157], v186 offset:2048
	ds_read_b128 v[186:189], v186 offset:3072
	s_add_u32 s10, s10, s40
	s_addc_u32 s11, s11, s41
	s_mov_b32 m0, s23
	v_lshl_add_u64 v[244:245], s[10:11], 0, v[178:179]
	ds_read_b128 v[190:193], v204 offset:32768
	ds_read_b128 v[194:197], v204 offset:33792
	ds_read_b128 v[198:201], v204 offset:34816
	ds_read_b128 v[206:209], v204 offset:35840
	ds_read_b128 v[222:225], v204 offset:36864
	ds_read_b128 v[226:229], v204 offset:37888
	ds_read_b128 v[230:233], v204 offset:38912
	ds_read_b128 v[234:237], v204 offset:39936
	global_load_lds_dwordx4 v[244:245], off
	v_lshl_add_u64 v[244:245], s[10:11], 0, v[174:175]
	s_mov_b32 m0, s24
	s_nop 0
	global_load_lds_dwordx4 v[244:245], off
	s_waitcnt vmcnt(8)
	s_waitcnt lgkmcnt(0)
	s_barrier
	s_waitcnt lgkmcnt(0)
	v_mfma_f32_16x16x32_bf16 v[126:129], v[130:133], v[190:193], v[126:129]
	v_mfma_f32_16x16x32_bf16 v[122:125], v[138:141], v[190:193], v[122:125]
	v_mfma_f32_16x16x32_bf16 v[110:113], v[130:133], v[198:201], v[110:113]
	v_mfma_f32_16x16x32_bf16 v[106:109], v[138:141], v[198:201], v[106:109]
	v_mfma_f32_16x16x32_bf16 v[94:97], v[130:133], v[222:225], v[94:97]
	v_mfma_f32_16x16x32_bf16 v[90:93], v[138:141], v[222:225], v[90:93]
	v_mfma_f32_16x16x32_bf16 v[78:81], v[130:133], v[230:233], v[78:81]
	v_mfma_f32_16x16x32_bf16 v[74:77], v[138:141], v[230:233], v[74:77]
	v_mfma_f32_16x16x32_bf16 v[126:129], v[134:137], v[194:197], v[126:129]
	v_mfma_f32_16x16x32_bf16 v[122:125], v[142:145], v[194:197], v[122:125]
	v_mfma_f32_16x16x32_bf16 v[110:113], v[134:137], v[206:209], v[110:113]
	v_mfma_f32_16x16x32_bf16 v[106:109], v[142:145], v[206:209], v[106:109]
	v_mfma_f32_16x16x32_bf16 v[94:97], v[134:137], v[226:229], v[94:97]
	v_mfma_f32_16x16x32_bf16 v[90:93], v[142:145], v[226:229], v[90:93]
	v_mfma_f32_16x16x32_bf16 v[78:81], v[134:137], v[234:237], v[78:81]
	v_mfma_f32_16x16x32_bf16 v[74:77], v[142:145], v[234:237], v[74:77]
	v_mfma_f32_16x16x32_bf16 v[118:121], v[146:149], v[190:193], v[118:121]
	v_mfma_f32_16x16x32_bf16 v[114:117], v[154:157], v[190:193], v[114:117]
	v_mfma_f32_16x16x32_bf16 v[102:105], v[146:149], v[198:201], v[102:105]
	v_mfma_f32_16x16x32_bf16 v[98:101], v[154:157], v[198:201], v[98:101]
	v_mfma_f32_16x16x32_bf16 v[86:89], v[146:149], v[222:225], v[86:89]
	v_mfma_f32_16x16x32_bf16 v[82:85], v[154:157], v[222:225], v[82:85]
	v_mfma_f32_16x16x32_bf16 v[70:73], v[146:149], v[230:233], v[70:73]
	v_mfma_f32_16x16x32_bf16 v[66:69], v[154:157], v[230:233], v[66:69]
	v_mfma_f32_16x16x32_bf16 v[118:121], v[150:153], v[194:197], v[118:121]
	v_mfma_f32_16x16x32_bf16 v[114:117], v[186:189], v[194:197], v[114:117]
	v_mfma_f32_16x16x32_bf16 v[102:105], v[150:153], v[206:209], v[102:105]
	v_mfma_f32_16x16x32_bf16 v[98:101], v[186:189], v[206:209], v[98:101]
	v_mfma_f32_16x16x32_bf16 v[86:89], v[150:153], v[226:229], v[86:89]
	v_mfma_f32_16x16x32_bf16 v[82:85], v[186:189], v[226:229], v[82:85]
	v_mfma_f32_16x16x32_bf16 v[70:73], v[150:153], v[234:237], v[70:73]
	v_mfma_f32_16x16x32_bf16 v[66:69], v[186:189], v[234:237], v[66:69]
	s_barrier
; #define PG8_STAGE(bufoff, gbase, voff) do { _Pragma("unroll") for (int _i = 0; _i < 2; ++_i) \
;         __builtin_amdgcn_global_load_lds((const unsigned*)((const char*)(gbase) + (voff)[_i]), (LAS unsigned*)(lds + (bufoff) + ldsw + _i * 8192), 16, 0, 0); } while (0)
; #define PG8_LDA(dst, b, h) do { _Pragma("unroll") for (int m = 0; m < 4; ++m) _Pragma("unroll") for (int k = 0; k < 2; ++k) dst[m][k] = *(const LAS bf16x8*)(lds + PG8_SA(b, h) + aoff + m * 2048 + k * 1024); } while (0)
; #define PG8_MMA(ai, bj, At, Bt) do { __builtin_amdgcn_s_setprio(1); _Pragma("unroll") for (int m = 0; m < 4; ++m) _Pragma("unroll") for (int n = 0; n < 2; ++n) _Pragma("unroll") for (int k = 0; k < 2; ++k) \
;         acc[ai][bj][m][n] = __builtin_amdgcn_mfma_f32_16x16x32_bf16(Bt[n][k], At[m][k], acc[ai][bj][m][n], 0, 0, 0); __builtin_amdgcn_s_setprio(0); } while (0)
; #define PG8_WAIT_V(n) asm volatile("s_waitcnt vmcnt(" #n ")" ::: "memory")
; #define PG8_WAIT_L(n) asm volatile("s_waitcnt lgkmcnt(" #n ")" ::: "memory")
; #define PG8_BAR __builtin_amdgcn_s_barrier()
; #define PG8_SCHED __builtin_amdgcn_sched_barrier(0)
; template <class Epi>
; __device__ __forceinline__ void gemm_phase(LAS unsigned char* lds, const Gemm g, const StaticOrder& S, const Epi& E) {
;     ...
;             PG8_LDA(At, 1, 1); PG8_STAGE(PG8_SB(1, 0), b3, voffB); PG8_STAGE(PG8_SB(1, 1), b3 + hstepB, voffB); PG8_STAGE(PG8_SA(1, 0), a3, voffA);
;             PG8_WAIT_V(8); PG8_WAIT_L(0); PG8_BAR; PG8_MMA(1, 0, At, B0); PG8_MMA(1, 1, At, B1); PG8_BAR; PG8_SCHED;
;         }
	s_add_i32 s10, s29, s20
	v_lshl_add_u64 v[202:203], v[202:203], 0, s[82:83]
	s_mov_b32 m0, s10
	ds_read_b128 v[190:193], v204 offset:49152
	ds_read_b128 v[194:197], v204 offset:50176
	ds_read_b128 v[198:201], v204 offset:51200
	ds_read_b128 v[206:209], v204 offset:52224
	ds_read_b128 v[222:225], v204 offset:53248
	ds_read_b128 v[226:229], v204 offset:54272
	ds_read_b128 v[230:233], v204 offset:55296
	ds_read_b128 v[234:237], v204 offset:56320
	global_load_lds_dwordx4 v[202:203], off
	v_lshl_add_u64 v[202:203], v[216:217], 0, s[82:83]
	s_add_i32 m0, s10, 0x2000
	s_add_i32 s10, s30, s20
	global_load_lds_dwordx4 v[202:203], off
	v_lshl_add_u64 v[202:203], v[218:219], 0, s[82:83]
	s_mov_b32 m0, s10
	s_nop 0
	global_load_lds_dwordx4 v[202:203], off
	v_lshl_add_u64 v[202:203], v[238:239], 0, s[82:83]
	s_add_i32 m0, s10, 0x2000
	s_nop 0
	global_load_lds_dwordx4 v[202:203], off
	v_lshl_add_u64 v[202:203], v[240:241], 0, s[82:83]
	s_mov_b32 m0, s25
	s_nop 0
	global_load_lds_dwordx4 v[202:203], off
	v_lshl_add_u64 v[202:203], v[242:243], 0, s[82:83]
	s_mov_b32 m0, s62
	s_nop 0
	global_load_lds_dwordx4 v[202:203], off
	s_waitcnt vmcnt(8)
	s_waitcnt lgkmcnt(0)
	s_barrier
	s_waitcnt lgkmcnt(0)
	v_mfma_f32_16x16x32_bf16 v[60:63], v[130:133], v[190:193], v[60:63]
	v_mfma_f32_16x16x32_bf16 v[56:59], v[138:141], v[190:193], v[56:59]
	v_mfma_f32_16x16x32_bf16 v[44:47], v[130:133], v[198:201], v[44:47]
	v_mfma_f32_16x16x32_bf16 v[40:43], v[138:141], v[198:201], v[40:43]
	v_mfma_f32_16x16x32_bf16 v[28:31], v[130:133], v[222:225], v[28:31]
	v_mfma_f32_16x16x32_bf16 v[24:27], v[138:141], v[222:225], v[24:27]
	v_mfma_f32_16x16x32_bf16 v[12:15], v[130:133], v[230:233], v[12:15]
	v_mfma_f32_16x16x32_bf16 v[8:11], v[138:141], v[230:233], v[8:11]
	v_mfma_f32_16x16x32_bf16 v[60:63], v[134:137], v[194:197], v[60:63]
	v_mfma_f32_16x16x32_bf16 v[56:59], v[142:145], v[194:197], v[56:59]
	v_mfma_f32_16x16x32_bf16 v[44:47], v[134:137], v[206:209], v[44:47]
	v_mfma_f32_16x16x32_bf16 v[40:43], v[142:145], v[206:209], v[40:43]
	v_mfma_f32_16x16x32_bf16 v[28:31], v[134:137], v[226:229], v[28:31]
	v_mfma_f32_16x16x32_bf16 v[24:27], v[142:145], v[226:229], v[24:27]
	v_mfma_f32_16x16x32_bf16 v[12:15], v[134:137], v[234:237], v[12:15]
	v_mfma_f32_16x16x32_bf16 v[8:11], v[142:145], v[234:237], v[8:11]
	v_mfma_f32_16x16x32_bf16 v[52:55], v[146:149], v[190:193], v[52:55]
	v_mfma_f32_16x16x32_bf16 v[48:51], v[154:157], v[190:193], v[48:51]
	v_mfma_f32_16x16x32_bf16 v[36:39], v[146:149], v[198:201], v[36:39]
	v_mfma_f32_16x16x32_bf16 v[32:35], v[154:157], v[198:201], v[32:35]
	v_mfma_f32_16x16x32_bf16 v[20:23], v[146:149], v[222:225], v[20:23]
	v_mfma_f32_16x16x32_bf16 v[16:19], v[154:157], v[222:225], v[16:19]
	v_mfma_f32_16x16x32_bf16 v[4:7], v[146:149], v[230:233], v[4:7]
	v_mfma_f32_16x16x32_bf16 v[0:3], v[154:157], v[230:233], v[0:3]
	v_mfma_f32_16x16x32_bf16 v[52:55], v[150:153], v[194:197], v[52:55]
	v_mfma_f32_16x16x32_bf16 v[48:51], v[186:189], v[194:197], v[48:51]
	v_mfma_f32_16x16x32_bf16 v[36:39], v[150:153], v[206:209], v[36:39]
	v_mfma_f32_16x16x32_bf16 v[32:35], v[186:189], v[206:209], v[32:35]
	v_mfma_f32_16x16x32_bf16 v[20:23], v[150:153], v[226:229], v[20:23]
	v_mfma_f32_16x16x32_bf16 v[16:19], v[186:189], v[226:229], v[16:19]
	v_mfma_f32_16x16x32_bf16 v[4:7], v[150:153], v[234:237], v[4:7]
	v_mfma_f32_16x16x32_bf16 v[0:3], v[186:189], v[234:237], v[0:3]
	s_barrier
	s_add_u32 s26, s26, 0x100
	s_addc_u32 s27, s27, 0
	s_add_u32 s58, s58, 0x100
	s_addc_u32 s59, s59, 0
	s_cmp_ge_i32 s28, s64
	s_mov_b32 s10, s28
	s_cbranch_scc0 .LBB0_3152

; #define PG8_STAGE(bufoff, gbase, voff) do { _Pragma("unroll") for (int _i = 0; _i < 2; ++_i) \
;         __builtin_amdgcn_global_load_lds((const unsigned*)((const char*)(gbase) + (voff)[_i]), (LAS unsigned*)(lds + (bufoff) + ldsw + _i * 8192), 16, 0, 0); } while (0)
; #define PG8_LDA(dst, b, h) do { _Pragma("unroll") for (int m = 0; m < 4; ++m) _Pragma("unroll") for (int k = 0; k < 2; ++k) dst[m][k] = *(const LAS bf16x8*)(lds + PG8_SA(b, h) + aoff + m * 2048 + k * 1024); } while (0)
; #define PG8_LDB(dst, b, h) do { _Pragma("unroll") for (int n = 0; n < 2; ++n) _Pragma("unroll") for (int k = 0; k < 2; ++k) dst[n][k] = *(const LAS bf16x8*)(lds + PG8_SB(b, h) + boff + n * 2048 + k * 1024); } while (0)
; #define PG8_MMA(ai, bj, At, Bt) do { __builtin_amdgcn_s_setprio(1); _Pragma("unroll") for (int m = 0; m < 4; ++m) _Pragma("unroll") for (int n = 0; n < 2; ++n) _Pragma("unroll") for (int k = 0; k < 2; ++k) \
;         acc[ai][bj][m][n] = __builtin_amdgcn_mfma_f32_16x16x32_bf16(Bt[n][k], At[m][k], acc[ai][bj][m][n], 0, 0, 0); __builtin_amdgcn_s_setprio(0); } while (0)
; #define PG8_WAIT_V(n) asm volatile("s_waitcnt vmcnt(" #n ")" ::: "memory")
; #define PG8_WAIT_L(n) asm volatile("s_waitcnt lgkmcnt(" #n ")" ::: "memory")
; #define PG8_BAR __builtin_amdgcn_s_barrier()
; #define PG8_SCHED __builtin_amdgcn_sched_barrier(0)
; template <class Epi>
; __device__ __forceinline__ void gemm_phase(LAS unsigned char* lds, const Gemm g, const StaticOrder& S, const Epi& E) {
;     ...
;         for (int t = 0; t < nt; t += 2) {
;             const bool last = (t == nt - 2);
;             const char* a1 = cA + (size_t)(t + 1) * kstep;
;             const char* a2 = last ? nA : cA + (size_t)(t + 2) * kstep; const char* b2 = last ? nB : cB + (size_t)(t + 2) * kstep;
;             const char* a3 = a2 + kstep; const char* b3 = b2 + kstep;
;             PG8_LDB(B0, 0, 0); PG8_LDB(B1, 0, 1); PG8_SCHED; PG8_LDA(At, 0, 0); PG8_STAGE(PG8_SA(1, 1), a1 + hstepA, voffA);
;             PG8_WAIT_V(8); PG8_WAIT_L(0); PG8_BAR; PG8_MMA(0, 0, At, B0); PG8_MMA(0, 1, At, B1); PG8_BAR; PG8_SCHED;
;             PG8_LDA(At, 0, 1); PG8_STAGE(PG8_SB(0, 0), b2, voffB); PG8_STAGE(PG8_SB(0, 1), b2 + hstepB, voffB); PG8_STAGE(PG8_SA(0, 0), a2, voffA);
;             PG8_WAIT_V(8); PG8_WAIT_L(0); PG8_BAR; PG8_MMA(1, 0, At, B0); PG8_MMA(1, 1, At, B1); PG8_BAR; PG8_SCHED;
.LBB0_3239:
	s_add_i32 s15, s10, 2
	s_add_u32 s44, s42, 0x80
	s_addc_u32 s11, s43, 0
	s_add_i32 s64, 0, 0x10000
	s_cmp_eq_u32 s97, s10
	s_cselect_b32 s11, s1, s11
	s_cselect_b32 s10, s0, s44
	v_add_u32_e32 v145, s64, v172
	s_cselect_b32 s45, s9, s14
	s_cselect_b32 s44, s8, s13
	s_add_i32 s65, 0, 0x14000
	ds_read_b128 v[146:149], v145
	ds_read_b128 v[150:153], v145 offset:1024
	ds_read_b128 v[154:157], v145 offset:2048
	ds_read_b128 v[178:181], v145 offset:3072
	v_add_u32_e32 v145, s65, v172
	ds_read_b128 v[182:185], v145
	ds_read_b128 v[186:189], v145 offset:1024
	ds_read_b128 v[190:193], v145 offset:2048
	ds_read_b128 v[194:197], v145 offset:3072
	v_lshl_add_u64 v[242:243], s[42:43], 0, v[142:143]
	s_add_i32 m0, s25, 0xc000
	ds_read_b128 v[198:201], v175
	ds_read_b128 v[202:205], v175 offset:1024
	ds_read_b128 v[206:209], v175 offset:2048
	ds_read_b128 v[222:225], v175 offset:3072
	ds_read_b128 v[226:229], v175 offset:4096
	ds_read_b128 v[230:233], v175 offset:5120
	ds_read_b128 v[234:237], v175 offset:6144
	ds_read_b128 v[238:241], v175 offset:7168
	global_load_lds_dwordx4 v[242:243], off
	v_lshl_add_u64 v[242:243], s[42:43], 0, v[140:141]
	s_add_i32 m0, s25, 0xe000
	s_nop 0
	global_load_lds_dwordx4 v[242:243], off
	s_waitcnt vmcnt(8)
	s_waitcnt lgkmcnt(0)
	s_barrier
	s_waitcnt lgkmcnt(0)
	v_mfma_f32_16x16x32_bf16 v[126:129], v[146:149], v[198:201], v[126:129]
	v_mfma_f32_16x16x32_bf16 v[122:125], v[154:157], v[198:201], v[122:125]
	v_mfma_f32_16x16x32_bf16 v[110:113], v[146:149], v[206:209], v[110:113]
	v_mfma_f32_16x16x32_bf16 v[106:109], v[154:157], v[206:209], v[106:109]
	v_mfma_f32_16x16x32_bf16 v[94:97], v[146:149], v[226:229], v[94:97]
	v_mfma_f32_16x16x32_bf16 v[90:93], v[154:157], v[226:229], v[90:93]
	v_mfma_f32_16x16x32_bf16 v[78:81], v[146:149], v[234:237], v[78:81]
	v_mfma_f32_16x16x32_bf16 v[74:77], v[154:157], v[234:237], v[74:77]
	v_mfma_f32_16x16x32_bf16 v[126:129], v[150:153], v[202:205], v[126:129]
	v_mfma_f32_16x16x32_bf16 v[122:125], v[178:181], v[202:205], v[122:125]
	v_mfma_f32_16x16x32_bf16 v[110:113], v[150:153], v[222:225], v[110:113]
	v_mfma_f32_16x16x32_bf16 v[106:109], v[178:181], v[222:225], v[106:109]
	v_mfma_f32_16x16x32_bf16 v[94:97], v[150:153], v[230:233], v[94:97]
	v_mfma_f32_16x16x32_bf16 v[90:93], v[178:181], v[230:233], v[90:93]
	v_mfma_f32_16x16x32_bf16 v[78:81], v[150:153], v[238:241], v[78:81]
	v_mfma_f32_16x16x32_bf16 v[74:77], v[178:181], v[238:241], v[74:77]
	v_mfma_f32_16x16x32_bf16 v[118:121], v[182:185], v[198:201], v[118:121]
	v_mfma_f32_16x16x32_bf16 v[114:117], v[190:193], v[198:201], v[114:117]
	v_mfma_f32_16x16x32_bf16 v[102:105], v[182:185], v[206:209], v[102:105]
	v_mfma_f32_16x16x32_bf16 v[98:101], v[190:193], v[206:209], v[98:101]
	v_mfma_f32_16x16x32_bf16 v[86:89], v[182:185], v[226:229], v[86:89]
	v_mfma_f32_16x16x32_bf16 v[82:85], v[190:193], v[226:229], v[82:85]
	v_mfma_f32_16x16x32_bf16 v[70:73], v[182:185], v[234:237], v[70:73]
	v_mfma_f32_16x16x32_bf16 v[66:69], v[190:193], v[234:237], v[66:69]
	v_mfma_f32_16x16x32_bf16 v[118:121], v[186:189], v[202:205], v[118:121]
	v_mfma_f32_16x16x32_bf16 v[114:117], v[194:197], v[202:205], v[114:117]
	v_mfma_f32_16x16x32_bf16 v[102:105], v[186:189], v[222:225], v[102:105]
	v_mfma_f32_16x16x32_bf16 v[98:101], v[194:197], v[222:225], v[98:101]
	v_mfma_f32_16x16x32_bf16 v[86:89], v[186:189], v[230:233], v[86:89]
	v_mfma_f32_16x16x32_bf16 v[82:85], v[194:197], v[230:233], v[82:85]
	v_mfma_f32_16x16x32_bf16 v[70:73], v[186:189], v[238:241], v[70:73]
	v_mfma_f32_16x16x32_bf16 v[66:69], v[194:197], v[238:241], v[66:69]
	s_barrier
	s_add_i32 s64, s64, s24
	v_lshl_add_u64 v[242:243], s[44:45], 0, v[134:135]
	s_mov_b32 m0, s64
	ds_read_b128 v[198:201], v175 offset:16384
	ds_read_b128 v[202:205], v175 offset:17408
	ds_read_b128 v[206:209], v175 offset:18432
	ds_read_b128 v[222:225], v175 offset:19456
	ds_read_b128 v[226:229], v175 offset:20480
	ds_read_b128 v[230:233], v175 offset:21504
	ds_read_b128 v[234:237], v175 offset:22528
	ds_read_b128 v[238:241], v175 offset:23552
	global_load_lds_dwordx4 v[242:243], off
	s_add_i32 m0, s64, 0x2000
	v_lshl_add_u64 v[244:245], s[44:45], 0, v[130:131]
	s_add_u32 s44, s44, s6
	s_addc_u32 s45, s45, s7
	s_add_i32 s64, s65, s24
	global_load_lds_dwordx4 v[244:245], off
	v_lshl_add_u64 v[246:247], s[44:45], 0, v[134:135]
	s_mov_b32 m0, s64
	v_lshl_add_u64 v[248:249], s[44:45], 0, v[130:131]
	global_load_lds_dwordx4 v[246:247], off
	s_add_i32 m0, s64, 0x2000
	v_lshl_add_u64 v[250:251], s[10:11], 0, v[136:137]
	global_load_lds_dwordx4 v[248:249], off
	s_mov_b32 m0, s25
	v_lshl_add_u64 v[216:217], s[10:11], 0, v[132:133]
	global_load_lds_dwordx4 v[250:251], off
	s_mov_b32 m0, s26
	s_nop 0
	global_load_lds_dwordx4 v[216:217], off
	s_waitcnt vmcnt(8)
	s_waitcnt lgkmcnt(0)
	s_barrier
; #define PG8_STAGE(bufoff, gbase, voff) do { _Pragma("unroll") for (int _i = 0; _i < 2; ++_i) \
;         __builtin_amdgcn_global_load_lds((const unsigned*)((const char*)(gbase) + (voff)[_i]), (LAS unsigned*)(lds + (bufoff) + ldsw + _i * 8192), 16, 0, 0); } while (0)
; #define PG8_LDA(dst, b, h) do { _Pragma("unroll") for (int m = 0; m < 4; ++m) _Pragma("unroll") for (int k = 0; k < 2; ++k) dst[m][k] = *(const LAS bf16x8*)(lds + PG8_SA(b, h) + aoff + m * 2048 + k * 1024); } while (0)
; #define PG8_LDB(dst, b, h) do { _Pragma("unroll") for (int n = 0; n < 2; ++n) _Pragma("unroll") for (int k = 0; k < 2; ++k) dst[n][k] = *(const LAS bf16x8*)(lds + PG8_SB(b, h) + boff + n * 2048 + k * 1024); } while (0)
; #define PG8_MMA(ai, bj, At, Bt) do { __builtin_amdgcn_s_setprio(1); _Pragma("unroll") for (int m = 0; m < 4; ++m) _Pragma("unroll") for (int n = 0; n < 2; ++n) _Pragma("unroll") for (int k = 0; k < 2; ++k) \
;         acc[ai][bj][m][n] = __builtin_amdgcn_mfma_f32_16x16x32_bf16(Bt[n][k], At[m][k], acc[ai][bj][m][n], 0, 0, 0); __builtin_amdgcn_s_setprio(0); } while (0)
; #define PG8_WAIT_V(n) asm volatile("s_waitcnt vmcnt(" #n ")" ::: "memory")
; #define PG8_WAIT_L(n) asm volatile("s_waitcnt lgkmcnt(" #n ")" ::: "memory")
; #define PG8_BAR __builtin_amdgcn_s_barrier()
; #define PG8_SCHED __builtin_amdgcn_sched_barrier(0)
; template <class Epi>
; __device__ __forceinline__ void gemm_phase(LAS unsigned char* lds, const Gemm g, const StaticOrder& S, const Epi& E) {
;     ...
;             PG8_WAIT_V(8); PG8_WAIT_L(0); PG8_BAR; PG8_MMA(0, 0, At, B0); PG8_MMA(0, 1, At, B1); PG8_BAR; PG8_SCHED;
;             PG8_LDA(At, 0, 1); PG8_STAGE(PG8_SB(0, 0), b2, voffB); PG8_STAGE(PG8_SB(0, 1), b2 + hstepB, voffB); PG8_STAGE(PG8_SA(0, 0), a2, voffA);
;             PG8_WAIT_V(8); PG8_WAIT_L(0); PG8_BAR; PG8_MMA(1, 0, At, B0); PG8_MMA(1, 1, At, B1); PG8_BAR; PG8_SCHED;
;             PG8_LDB(B0, 1, 0); PG8_LDB(B1, 1, 1); PG8_SCHED; PG8_LDA(At, 1, 0); PG8_STAGE(PG8_SA(0, 1), a2 + hstepA, voffA);
;             PG8_WAIT_V(8); PG8_WAIT_L(0); PG8_BAR; PG8_MMA(0, 0, At, B0); PG8_MMA(0, 1, At, B1); PG8_BAR; PG8_SCHED;
	s_waitcnt lgkmcnt(0)
	v_mfma_f32_16x16x32_bf16 v[60:63], v[146:149], v[198:201], v[60:63]
	v_mfma_f32_16x16x32_bf16 v[56:59], v[154:157], v[198:201], v[56:59]
	v_mfma_f32_16x16x32_bf16 v[44:47], v[146:149], v[206:209], v[44:47]
	v_mfma_f32_16x16x32_bf16 v[40:43], v[154:157], v[206:209], v[40:43]
	v_mfma_f32_16x16x32_bf16 v[28:31], v[146:149], v[226:229], v[28:31]
	v_mfma_f32_16x16x32_bf16 v[24:27], v[154:157], v[226:229], v[24:27]
	v_mfma_f32_16x16x32_bf16 v[12:15], v[146:149], v[234:237], v[12:15]
	v_mfma_f32_16x16x32_bf16 v[8:11], v[154:157], v[234:237], v[8:11]
	v_mfma_f32_16x16x32_bf16 v[60:63], v[150:153], v[202:205], v[60:63]
	v_mfma_f32_16x16x32_bf16 v[56:59], v[178:181], v[202:205], v[56:59]
	v_mfma_f32_16x16x32_bf16 v[44:47], v[150:153], v[222:225], v[44:47]
	v_mfma_f32_16x16x32_bf16 v[40:43], v[178:181], v[222:225], v[40:43]
	v_mfma_f32_16x16x32_bf16 v[28:31], v[150:153], v[230:233], v[28:31]
	v_mfma_f32_16x16x32_bf16 v[24:27], v[178:181], v[230:233], v[24:27]
	v_mfma_f32_16x16x32_bf16 v[12:15], v[150:153], v[238:241], v[12:15]
	v_mfma_f32_16x16x32_bf16 v[8:11], v[178:181], v[238:241], v[8:11]
	v_mfma_f32_16x16x32_bf16 v[52:55], v[182:185], v[198:201], v[52:55]
	v_mfma_f32_16x16x32_bf16 v[48:51], v[190:193], v[198:201], v[48:51]
	v_mfma_f32_16x16x32_bf16 v[36:39], v[182:185], v[206:209], v[36:39]
	v_mfma_f32_16x16x32_bf16 v[32:35], v[190:193], v[206:209], v[32:35]
	v_mfma_f32_16x16x32_bf16 v[20:23], v[182:185], v[226:229], v[20:23]
	v_mfma_f32_16x16x32_bf16 v[16:19], v[190:193], v[226:229], v[16:19]
	v_mfma_f32_16x16x32_bf16 v[4:7], v[182:185], v[234:237], v[4:7]
	v_mfma_f32_16x16x32_bf16 v[0:3], v[190:193], v[234:237], v[0:3]
	v_mfma_f32_16x16x32_bf16 v[52:55], v[186:189], v[202:205], v[52:55]
	v_mfma_f32_16x16x32_bf16 v[48:51], v[194:197], v[202:205], v[48:51]
	v_mfma_f32_16x16x32_bf16 v[36:39], v[186:189], v[222:225], v[36:39]
	v_mfma_f32_16x16x32_bf16 v[32:35], v[194:197], v[222:225], v[32:35]
	v_mfma_f32_16x16x32_bf16 v[20:23], v[186:189], v[230:233], v[20:23]
	v_mfma_f32_16x16x32_bf16 v[16:19], v[194:197], v[230:233], v[16:19]
	v_mfma_f32_16x16x32_bf16 v[4:7], v[186:189], v[238:241], v[4:7]
	v_mfma_f32_16x16x32_bf16 v[0:3], v[194:197], v[238:241], v[0:3]
	s_barrier
	s_add_i32 s44, 0, 0x18000
	v_add_u32_e32 v145, s44, v172
	s_add_i32 s45, 0, 0x1c000
	ds_read_b128 v[146:149], v145
	ds_read_b128 v[150:153], v145 offset:1024
	ds_read_b128 v[154:157], v145 offset:2048
	ds_read_b128 v[178:181], v145 offset:3072
	v_add_u32_e32 v145, s45, v172
	ds_read_b128 v[182:185], v145
	ds_read_b128 v[186:189], v145 offset:1024
	ds_read_b128 v[190:193], v145 offset:2048
	ds_read_b128 v[194:197], v145 offset:3072
	s_add_u32 s10, s10, s4
	s_addc_u32 s11, s11, s5
	s_mov_b32 m0, s27
	v_lshl_add_u64 v[218:219], s[10:11], 0, v[136:137]
	ds_read_b128 v[198:201], v175 offset:32768
	ds_read_b128 v[202:205], v175 offset:33792
	ds_read_b128 v[206:209], v175 offset:34816
	ds_read_b128 v[222:225], v175 offset:35840
	ds_read_b128 v[226:229], v175 offset:36864
	ds_read_b128 v[230:233], v175 offset:37888
	ds_read_b128 v[234:237], v175 offset:38912
	ds_read_b128 v[238:241], v175 offset:39936
	global_load_lds_dwordx4 v[218:219], off
	v_lshl_add_u64 v[218:219], s[10:11], 0, v[132:133]
	s_mov_b32 m0, s68
	s_nop 0
	global_load_lds_dwordx4 v[218:219], off
	s_waitcnt vmcnt(8)
	s_waitcnt lgkmcnt(0)
	s_barrier
	s_waitcnt lgkmcnt(0)
	v_mfma_f32_16x16x32_bf16 v[126:129], v[146:149], v[198:201], v[126:129]
	v_mfma_f32_16x16x32_bf16 v[122:125], v[154:157], v[198:201], v[122:125]
	v_mfma_f32_16x16x32_bf16 v[110:113], v[146:149], v[206:209], v[110:113]
	v_mfma_f32_16x16x32_bf16 v[106:109], v[154:157], v[206:209], v[106:109]
	v_mfma_f32_16x16x32_bf16 v[94:97], v[146:149], v[226:229], v[94:97]
	v_mfma_f32_16x16x32_bf16 v[90:93], v[154:157], v[226:229], v[90:93]
	v_mfma_f32_16x16x32_bf16 v[78:81], v[146:149], v[234:237], v[78:81]
	v_mfma_f32_16x16x32_bf16 v[74:77], v[154:157], v[234:237], v[74:77]
	v_mfma_f32_16x16x32_bf16 v[126:129], v[150:153], v[202:205], v[126:129]
	v_mfma_f32_16x16x32_bf16 v[122:125], v[178:181], v[202:205], v[122:125]
	v_mfma_f32_16x16x32_bf16 v[110:113], v[150:153], v[222:225], v[110:113]
	v_mfma_f32_16x16x32_bf16 v[106:109], v[178:181], v[222:225], v[106:109]
	v_mfma_f32_16x16x32_bf16 v[94:97], v[150:153], v[230:233], v[94:97]
	v_mfma_f32_16x16x32_bf16 v[90:93], v[178:181], v[230:233], v[90:93]
	v_mfma_f32_16x16x32_bf16 v[78:81], v[150:153], v[238:241], v[78:81]
	v_mfma_f32_16x16x32_bf16 v[74:77], v[178:181], v[238:241], v[74:77]
	v_mfma_f32_16x16x32_bf16 v[118:121], v[182:185], v[198:201], v[118:121]
	v_mfma_f32_16x16x32_bf16 v[114:117], v[190:193], v[198:201], v[114:117]
	v_mfma_f32_16x16x32_bf16 v[102:105], v[182:185], v[206:209], v[102:105]
	v_mfma_f32_16x16x32_bf16 v[98:101], v[190:193], v[206:209], v[98:101]
	v_mfma_f32_16x16x32_bf16 v[86:89], v[182:185], v[226:229], v[86:89]
	v_mfma_f32_16x16x32_bf16 v[82:85], v[190:193], v[226:229], v[82:85]
	v_mfma_f32_16x16x32_bf16 v[70:73], v[182:185], v[234:237], v[70:73]
	v_mfma_f32_16x16x32_bf16 v[66:69], v[190:193], v[234:237], v[66:69]
	v_mfma_f32_16x16x32_bf16 v[118:121], v[186:189], v[202:205], v[118:121]
	v_mfma_f32_16x16x32_bf16 v[114:117], v[194:197], v[202:205], v[114:117]
	v_mfma_f32_16x16x32_bf16 v[102:105], v[186:189], v[222:225], v[102:105]
	v_mfma_f32_16x16x32_bf16 v[98:101], v[194:197], v[222:225], v[98:101]
	v_mfma_f32_16x16x32_bf16 v[86:89], v[186:189], v[230:233], v[86:89]
	v_mfma_f32_16x16x32_bf16 v[82:85], v[194:197], v[230:233], v[82:85]
	v_mfma_f32_16x16x32_bf16 v[70:73], v[186:189], v[238:241], v[70:73]
	v_mfma_f32_16x16x32_bf16 v[66:69], v[194:197], v[238:241], v[66:69]
	s_barrier
; #define PG8_STAGE(bufoff, gbase, voff) do { _Pragma("unroll") for (int _i = 0; _i < 2; ++_i) \
;         __builtin_amdgcn_global_load_lds((const unsigned*)((const char*)(gbase) + (voff)[_i]), (LAS unsigned*)(lds + (bufoff) + ldsw + _i * 8192), 16, 0, 0); } while (0)
; #define PG8_LDA(dst, b, h) do { _Pragma("unroll") for (int m = 0; m < 4; ++m) _Pragma("unroll") for (int k = 0; k < 2; ++k) dst[m][k] = *(const LAS bf16x8*)(lds + PG8_SA(b, h) + aoff + m * 2048 + k * 1024); } while (0)
; #define PG8_MMA(ai, bj, At, Bt) do { __builtin_amdgcn_s_setprio(1); _Pragma("unroll") for (int m = 0; m < 4; ++m) _Pragma("unroll") for (int n = 0; n < 2; ++n) _Pragma("unroll") for (int k = 0; k < 2; ++k) \
;         acc[ai][bj][m][n] = __builtin_amdgcn_mfma_f32_16x16x32_bf16(Bt[n][k], At[m][k], acc[ai][bj][m][n], 0, 0, 0); __builtin_amdgcn_s_setprio(0); } while (0)
; #define PG8_WAIT_V(n) asm volatile("s_waitcnt vmcnt(" #n ")" ::: "memory")
; #define PG8_WAIT_L(n) asm volatile("s_waitcnt lgkmcnt(" #n ")" ::: "memory")
; #define PG8_BAR __builtin_amdgcn_s_barrier()
; #define PG8_SCHED __builtin_amdgcn_sched_barrier(0)
; template <class Epi>
; __device__ __forceinline__ void gemm_phase(LAS unsigned char* lds, const Gemm g, const StaticOrder& S, const Epi& E) {
;     ...
;             PG8_LDA(At, 1, 1); PG8_STAGE(PG8_SB(1, 0), b3, voffB); PG8_STAGE(PG8_SB(1, 1), b3 + hstepB, voffB); PG8_STAGE(PG8_SA(1, 0), a3, voffA);
;             PG8_WAIT_V(8); PG8_WAIT_L(0); PG8_BAR; PG8_MMA(1, 0, At, B0); PG8_MMA(1, 1, At, B1); PG8_BAR; PG8_SCHED;
;         }
	s_add_i32 s10, s44, s24
	v_lshl_add_u64 v[218:219], v[242:243], 0, s[82:83]
	s_mov_b32 m0, s10
	ds_read_b128 v[198:201], v175 offset:49152
	ds_read_b128 v[202:205], v175 offset:50176
	ds_read_b128 v[206:209], v175 offset:51200
	ds_read_b128 v[222:225], v175 offset:52224
	ds_read_b128 v[226:229], v175 offset:53248
	ds_read_b128 v[230:233], v175 offset:54272
	ds_read_b128 v[234:237], v175 offset:55296
	ds_read_b128 v[238:241], v175 offset:56320
	global_load_lds_dwordx4 v[218:219], off
	v_lshl_add_u64 v[218:219], v[244:245], 0, s[82:83]
	s_add_i32 m0, s10, 0x2000
	s_add_i32 s10, s45, s24
	global_load_lds_dwordx4 v[218:219], off
	v_lshl_add_u64 v[218:219], v[246:247], 0, s[82:83]
	s_mov_b32 m0, s10
	v_lshl_add_u64 v[216:217], v[216:217], 0, s[82:83]
	global_load_lds_dwordx4 v[218:219], off
	v_lshl_add_u64 v[218:219], v[248:249], 0, s[82:83]
	s_add_i32 m0, s10, 0x2000
	s_nop 0
	global_load_lds_dwordx4 v[218:219], off
	v_lshl_add_u64 v[218:219], v[250:251], 0, s[82:83]
	s_mov_b32 m0, s73
	s_nop 0
	global_load_lds_dwordx4 v[218:219], off
	s_mov_b32 m0, s84
	s_nop 0
	global_load_lds_dwordx4 v[216:217], off
	s_waitcnt vmcnt(8)
	s_waitcnt lgkmcnt(0)
	s_barrier
	s_waitcnt lgkmcnt(0)
	v_mfma_f32_16x16x32_bf16 v[60:63], v[146:149], v[198:201], v[60:63]
	v_mfma_f32_16x16x32_bf16 v[56:59], v[154:157], v[198:201], v[56:59]
	v_mfma_f32_16x16x32_bf16 v[44:47], v[146:149], v[206:209], v[44:47]
	v_mfma_f32_16x16x32_bf16 v[40:43], v[154:157], v[206:209], v[40:43]
	v_mfma_f32_16x16x32_bf16 v[28:31], v[146:149], v[226:229], v[28:31]
	v_mfma_f32_16x16x32_bf16 v[24:27], v[154:157], v[226:229], v[24:27]
	v_mfma_f32_16x16x32_bf16 v[12:15], v[146:149], v[234:237], v[12:15]
	v_mfma_f32_16x16x32_bf16 v[8:11], v[154:157], v[234:237], v[8:11]
	v_mfma_f32_16x16x32_bf16 v[60:63], v[150:153], v[202:205], v[60:63]
	v_mfma_f32_16x16x32_bf16 v[56:59], v[178:181], v[202:205], v[56:59]
	v_mfma_f32_16x16x32_bf16 v[44:47], v[150:153], v[222:225], v[44:47]
	v_mfma_f32_16x16x32_bf16 v[40:43], v[178:181], v[222:225], v[40:43]
	v_mfma_f32_16x16x32_bf16 v[28:31], v[150:153], v[230:233], v[28:31]
	v_mfma_f32_16x16x32_bf16 v[24:27], v[178:181], v[230:233], v[24:27]
	v_mfma_f32_16x16x32_bf16 v[12:15], v[150:153], v[238:241], v[12:15]
	v_mfma_f32_16x16x32_bf16 v[8:11], v[178:181], v[238:241], v[8:11]
	v_mfma_f32_16x16x32_bf16 v[52:55], v[182:185], v[198:201], v[52:55]
	v_mfma_f32_16x16x32_bf16 v[48:51], v[190:193], v[198:201], v[48:51]
	v_mfma_f32_16x16x32_bf16 v[36:39], v[182:185], v[206:209], v[36:39]
	v_mfma_f32_16x16x32_bf16 v[32:35], v[190:193], v[206:209], v[32:35]
	v_mfma_f32_16x16x32_bf16 v[20:23], v[182:185], v[226:229], v[20:23]
	v_mfma_f32_16x16x32_bf16 v[16:19], v[190:193], v[226:229], v[16:19]
	v_mfma_f32_16x16x32_bf16 v[4:7], v[182:185], v[234:237], v[4:7]
	v_mfma_f32_16x16x32_bf16 v[0:3], v[190:193], v[234:237], v[0:3]
	v_mfma_f32_16x16x32_bf16 v[52:55], v[186:189], v[202:205], v[52:55]
	v_mfma_f32_16x16x32_bf16 v[48:51], v[194:197], v[202:205], v[48:51]
	v_mfma_f32_16x16x32_bf16 v[36:39], v[186:189], v[222:225], v[36:39]
	v_mfma_f32_16x16x32_bf16 v[32:35], v[194:197], v[222:225], v[32:35]
	v_mfma_f32_16x16x32_bf16 v[20:23], v[186:189], v[230:233], v[20:23]
	v_mfma_f32_16x16x32_bf16 v[16:19], v[194:197], v[230:233], v[16:19]
	v_mfma_f32_16x16x32_bf16 v[4:7], v[186:189], v[238:241], v[4:7]
	v_mfma_f32_16x16x32_bf16 v[0:3], v[194:197], v[238:241], v[0:3]
	s_barrier
	s_add_u32 s13, s13, 0x100
	s_addc_u32 s14, s14, 0
	s_add_u32 s42, s42, 0x100
	s_addc_u32 s43, s43, 0
	s_cmp_ge_i32 s15, s96
	s_mov_b32 s10, s15
	s_cbranch_scc0 .LBB0_3239

; #define PG8_STAGE(bufoff, gbase, voff) do { _Pragma("unroll") for (int _i = 0; _i < 2; ++_i) \
;         __builtin_amdgcn_global_load_lds((const unsigned*)((const char*)(gbase) + (voff)[_i]), (LAS unsigned*)(lds + (bufoff) + ldsw + _i * 8192), 16, 0, 0); } while (0)
; #define PG8_LDA(dst, b, h) do { _Pragma("unroll") for (int m = 0; m < 4; ++m) _Pragma("unroll") for (int k = 0; k < 2; ++k) dst[m][k] = *(const LAS bf16x8*)(lds + PG8_SA(b, h) + aoff + m * 2048 + k * 1024); } while (0)
; #define PG8_LDB(dst, b, h) do { _Pragma("unroll") for (int n = 0; n < 2; ++n) _Pragma("unroll") for (int k = 0; k < 2; ++k) dst[n][k] = *(const LAS bf16x8*)(lds + PG8_SB(b, h) + boff + n * 2048 + k * 1024); } while (0)
; #define PG8_MMA(ai, bj, At, Bt) do { __builtin_amdgcn_s_setprio(1); _Pragma("unroll") for (int m = 0; m < 4; ++m) _Pragma("unroll") for (int n = 0; n < 2; ++n) _Pragma("unroll") for (int k = 0; k < 2; ++k) \
;         acc[ai][bj][m][n] = __builtin_amdgcn_mfma_f32_16x16x32_bf16(Bt[n][k], At[m][k], acc[ai][bj][m][n], 0, 0, 0); __builtin_amdgcn_s_setprio(0); } while (0)
; #define PG8_WAIT_V(n) asm volatile("s_waitcnt vmcnt(" #n ")" ::: "memory")
; #define PG8_WAIT_L(n) asm volatile("s_waitcnt lgkmcnt(" #n ")" ::: "memory")
; #define PG8_BAR __builtin_amdgcn_s_barrier()
; #define PG8_SCHED __builtin_amdgcn_sched_barrier(0)
; template <class Epi>
; __device__ __forceinline__ void gemm_phase(LAS unsigned char* lds, const Gemm g, const StaticOrder& S, const Epi& E) {
;     ...
;         for (int t = 0; t < nt; t += 2) {
;             const bool last = (t == nt - 2);
;             const char* a1 = cA + (size_t)(t + 1) * kstep;
;             const char* a2 = last ? nA : cA + (size_t)(t + 2) * kstep; const char* b2 = last ? nB : cB + (size_t)(t + 2) * kstep;
;             const char* a3 = a2 + kstep; const char* b3 = b2 + kstep;
;             PG8_LDB(B0, 0, 0); PG8_LDB(B1, 0, 1); PG8_SCHED; PG8_LDA(At, 0, 0); PG8_STAGE(PG8_SA(1, 1), a1 + hstepA, voffA);
;             PG8_WAIT_V(8); PG8_WAIT_L(0); PG8_BAR; PG8_MMA(0, 0, At, B0); PG8_MMA(0, 1, At, B1); PG8_BAR; PG8_SCHED;
;             PG8_LDA(At, 0, 1); PG8_STAGE(PG8_SB(0, 0), b2, voffB); PG8_STAGE(PG8_SB(0, 1), b2 + hstepB, voffB); PG8_STAGE(PG8_SA(0, 0), a2, voffA);
;             PG8_WAIT_V(8); PG8_WAIT_L(0); PG8_BAR; PG8_MMA(1, 0, At, B0); PG8_MMA(1, 1, At, B1); PG8_BAR; PG8_SCHED;
.LBB0_3352:
	s_add_i32 s58, s10, 2
	s_add_u32 s59, s0, 0x80
	s_addc_u32 s11, s1, 0
	s_add_i32 s62, 0, 0x10000
	s_cmp_eq_u32 s28, s10
	s_cselect_b32 s11, s9, s11
	s_cselect_b32 s10, s8, s59
	v_add_u32_e32 v145, s62, v177
	s_cselect_b32 s61, s53, s55
	s_cselect_b32 s60, s52, s54
	s_add_i32 s59, 0, 0x14000
	ds_read_b128 v[146:149], v145
	ds_read_b128 v[150:153], v145 offset:1024
	ds_read_b128 v[154:157], v145 offset:2048
	ds_read_b128 v[172:175], v145 offset:3072
	v_add_u32_e32 v145, s59, v177
	ds_read_b128 v[182:185], v145
	ds_read_b128 v[186:189], v145 offset:1024
	ds_read_b128 v[190:193], v145 offset:2048
	ds_read_b128 v[194:197], v145 offset:3072
	v_lshl_add_u64 v[178:179], s[0:1], 0, v[142:143]
	s_add_i32 m0, s21, 0xc000
	ds_read_b128 v[198:201], v181
	ds_read_b128 v[202:205], v181 offset:1024
	ds_read_b128 v[206:209], v181 offset:2048
	ds_read_b128 v[222:225], v181 offset:3072
	ds_read_b128 v[226:229], v181 offset:4096
	ds_read_b128 v[230:233], v181 offset:5120
	ds_read_b128 v[234:237], v181 offset:6144
	ds_read_b128 v[238:241], v181 offset:7168
	global_load_lds_dwordx4 v[178:179], off
	v_lshl_add_u64 v[178:179], s[0:1], 0, v[140:141]
	s_add_i32 m0, s21, 0xe000
	s_nop 0
	global_load_lds_dwordx4 v[178:179], off
	s_waitcnt vmcnt(8)
	s_waitcnt lgkmcnt(0)
	s_barrier
	s_waitcnt lgkmcnt(0)
	v_mfma_f32_16x16x32_bf16 v[126:129], v[146:149], v[198:201], v[126:129]
	v_mfma_f32_16x16x32_bf16 v[122:125], v[154:157], v[198:201], v[122:125]
	v_mfma_f32_16x16x32_bf16 v[110:113], v[146:149], v[206:209], v[110:113]
	v_mfma_f32_16x16x32_bf16 v[106:109], v[154:157], v[206:209], v[106:109]
	v_mfma_f32_16x16x32_bf16 v[94:97], v[146:149], v[226:229], v[94:97]
	v_mfma_f32_16x16x32_bf16 v[90:93], v[154:157], v[226:229], v[90:93]
	v_mfma_f32_16x16x32_bf16 v[78:81], v[146:149], v[234:237], v[78:81]
	v_mfma_f32_16x16x32_bf16 v[74:77], v[154:157], v[234:237], v[74:77]
	v_mfma_f32_16x16x32_bf16 v[126:129], v[150:153], v[202:205], v[126:129]
	v_mfma_f32_16x16x32_bf16 v[122:125], v[172:175], v[202:205], v[122:125]
	v_mfma_f32_16x16x32_bf16 v[110:113], v[150:153], v[222:225], v[110:113]
	v_mfma_f32_16x16x32_bf16 v[106:109], v[172:175], v[222:225], v[106:109]
	v_mfma_f32_16x16x32_bf16 v[94:97], v[150:153], v[230:233], v[94:97]
	v_mfma_f32_16x16x32_bf16 v[90:93], v[172:175], v[230:233], v[90:93]
	v_mfma_f32_16x16x32_bf16 v[78:81], v[150:153], v[238:241], v[78:81]
	v_mfma_f32_16x16x32_bf16 v[74:77], v[172:175], v[238:241], v[74:77]
	v_mfma_f32_16x16x32_bf16 v[118:121], v[182:185], v[198:201], v[118:121]
	v_mfma_f32_16x16x32_bf16 v[114:117], v[190:193], v[198:201], v[114:117]
	v_mfma_f32_16x16x32_bf16 v[102:105], v[182:185], v[206:209], v[102:105]
	v_mfma_f32_16x16x32_bf16 v[98:101], v[190:193], v[206:209], v[98:101]
	v_mfma_f32_16x16x32_bf16 v[86:89], v[182:185], v[226:229], v[86:89]
	v_mfma_f32_16x16x32_bf16 v[82:85], v[190:193], v[226:229], v[82:85]
	v_mfma_f32_16x16x32_bf16 v[70:73], v[182:185], v[234:237], v[70:73]
	v_mfma_f32_16x16x32_bf16 v[66:69], v[190:193], v[234:237], v[66:69]
	v_mfma_f32_16x16x32_bf16 v[118:121], v[186:189], v[202:205], v[118:121]
	v_mfma_f32_16x16x32_bf16 v[114:117], v[194:197], v[202:205], v[114:117]
	v_mfma_f32_16x16x32_bf16 v[102:105], v[186:189], v[222:225], v[102:105]
	v_mfma_f32_16x16x32_bf16 v[98:101], v[194:197], v[222:225], v[98:101]
	v_mfma_f32_16x16x32_bf16 v[86:89], v[186:189], v[230:233], v[86:89]
	v_mfma_f32_16x16x32_bf16 v[82:85], v[194:197], v[230:233], v[82:85]
	v_mfma_f32_16x16x32_bf16 v[70:73], v[186:189], v[238:241], v[70:73]
	v_mfma_f32_16x16x32_bf16 v[66:69], v[194:197], v[238:241], v[66:69]
	s_barrier
	s_add_i32 s62, s62, s20
	v_lshl_add_u64 v[178:179], s[60:61], 0, v[134:135]
	s_mov_b32 m0, s62
	ds_read_b128 v[198:201], v181 offset:16384
	ds_read_b128 v[202:205], v181 offset:17408
	ds_read_b128 v[206:209], v181 offset:18432
	ds_read_b128 v[222:225], v181 offset:19456
	ds_read_b128 v[226:229], v181 offset:20480
	ds_read_b128 v[230:233], v181 offset:21504
	ds_read_b128 v[234:237], v181 offset:22528
	ds_read_b128 v[238:241], v181 offset:23552
	global_load_lds_dwordx4 v[178:179], off
	s_add_i32 m0, s62, 0x2000
	v_lshl_add_u64 v[216:217], s[60:61], 0, v[130:131]
	s_add_u32 s60, s60, s38
	s_addc_u32 s61, s61, s39
	s_add_i32 s59, s59, s20
	global_load_lds_dwordx4 v[216:217], off
	v_lshl_add_u64 v[218:219], s[60:61], 0, v[134:135]
	s_mov_b32 m0, s59
	v_lshl_add_u64 v[242:243], s[60:61], 0, v[130:131]
	global_load_lds_dwordx4 v[218:219], off
	s_add_i32 m0, s59, 0x2000
	v_lshl_add_u64 v[244:245], s[10:11], 0, v[136:137]
	global_load_lds_dwordx4 v[242:243], off
	s_mov_b32 m0, s21
	v_lshl_add_u64 v[246:247], s[10:11], 0, v[132:133]
	global_load_lds_dwordx4 v[244:245], off
	s_mov_b32 m0, s22
	s_nop 0
	global_load_lds_dwordx4 v[246:247], off
	s_waitcnt vmcnt(8)
	s_waitcnt lgkmcnt(0)
	s_barrier
; #define PG8_STAGE(bufoff, gbase, voff) do { _Pragma("unroll") for (int _i = 0; _i < 2; ++_i) \
;         __builtin_amdgcn_global_load_lds((const unsigned*)((const char*)(gbase) + (voff)[_i]), (LAS unsigned*)(lds + (bufoff) + ldsw + _i * 8192), 16, 0, 0); } while (0)
; #define PG8_LDA(dst, b, h) do { _Pragma("unroll") for (int m = 0; m < 4; ++m) _Pragma("unroll") for (int k = 0; k < 2; ++k) dst[m][k] = *(const LAS bf16x8*)(lds + PG8_SA(b, h) + aoff + m * 2048 + k * 1024); } while (0)
; #define PG8_LDB(dst, b, h) do { _Pragma("unroll") for (int n = 0; n < 2; ++n) _Pragma("unroll") for (int k = 0; k < 2; ++k) dst[n][k] = *(const LAS bf16x8*)(lds + PG8_SB(b, h) + boff + n * 2048 + k * 1024); } while (0)
; #define PG8_MMA(ai, bj, At, Bt) do { __builtin_amdgcn_s_setprio(1); _Pragma("unroll") for (int m = 0; m < 4; ++m) _Pragma("unroll") for (int n = 0; n < 2; ++n) _Pragma("unroll") for (int k = 0; k < 2; ++k) \
;         acc[ai][bj][m][n] = __builtin_amdgcn_mfma_f32_16x16x32_bf16(Bt[n][k], At[m][k], acc[ai][bj][m][n], 0, 0, 0); __builtin_amdgcn_s_setprio(0); } while (0)
; #define PG8_WAIT_V(n) asm volatile("s_waitcnt vmcnt(" #n ")" ::: "memory")
; #define PG8_WAIT_L(n) asm volatile("s_waitcnt lgkmcnt(" #n ")" ::: "memory")
; #define PG8_BAR __builtin_amdgcn_s_barrier()
; #define PG8_SCHED __builtin_amdgcn_sched_barrier(0)
; template <class Epi>
; __device__ __forceinline__ void gemm_phase(LAS unsigned char* lds, const Gemm g, const StaticOrder& S, const Epi& E) {
;     ...
;             PG8_WAIT_V(8); PG8_WAIT_L(0); PG8_BAR; PG8_MMA(0, 0, At, B0); PG8_MMA(0, 1, At, B1); PG8_BAR; PG8_SCHED;
;             PG8_LDA(At, 0, 1); PG8_STAGE(PG8_SB(0, 0), b2, voffB); PG8_STAGE(PG8_SB(0, 1), b2 + hstepB, voffB); PG8_STAGE(PG8_SA(0, 0), a2, voffA);
;             PG8_WAIT_V(8); PG8_WAIT_L(0); PG8_BAR; PG8_MMA(1, 0, At, B0); PG8_MMA(1, 1, At, B1); PG8_BAR; PG8_SCHED;
;             PG8_LDB(B0, 1, 0); PG8_LDB(B1, 1, 1); PG8_SCHED; PG8_LDA(At, 1, 0); PG8_STAGE(PG8_SA(0, 1), a2 + hstepA, voffA);
;             PG8_WAIT_V(8); PG8_WAIT_L(0); PG8_BAR; PG8_MMA(0, 0, At, B0); PG8_MMA(0, 1, At, B1); PG8_BAR; PG8_SCHED;
	s_waitcnt lgkmcnt(0)
	v_mfma_f32_16x16x32_bf16 v[60:63], v[146:149], v[198:201], v[60:63]
	v_mfma_f32_16x16x32_bf16 v[56:59], v[154:157], v[198:201], v[56:59]
	v_mfma_f32_16x16x32_bf16 v[44:47], v[146:149], v[206:209], v[44:47]
	v_mfma_f32_16x16x32_bf16 v[40:43], v[154:157], v[206:209], v[40:43]
	v_mfma_f32_16x16x32_bf16 v[28:31], v[146:149], v[226:229], v[28:31]
	v_mfma_f32_16x16x32_bf16 v[24:27], v[154:157], v[226:229], v[24:27]
	v_mfma_f32_16x16x32_bf16 v[12:15], v[146:149], v[234:237], v[12:15]
	v_mfma_f32_16x16x32_bf16 v[8:11], v[154:157], v[234:237], v[8:11]
	v_mfma_f32_16x16x32_bf16 v[60:63], v[150:153], v[202:205], v[60:63]
	v_mfma_f32_16x16x32_bf16 v[56:59], v[172:175], v[202:205], v[56:59]
	v_mfma_f32_16x16x32_bf16 v[44:47], v[150:153], v[222:225], v[44:47]
	v_mfma_f32_16x16x32_bf16 v[40:43], v[172:175], v[222:225], v[40:43]
	v_mfma_f32_16x16x32_bf16 v[28:31], v[150:153], v[230:233], v[28:31]
	v_mfma_f32_16x16x32_bf16 v[24:27], v[172:175], v[230:233], v[24:27]
	v_mfma_f32_16x16x32_bf16 v[12:15], v[150:153], v[238:241], v[12:15]
	v_mfma_f32_16x16x32_bf16 v[8:11], v[172:175], v[238:241], v[8:11]
	v_mfma_f32_16x16x32_bf16 v[52:55], v[182:185], v[198:201], v[52:55]
	v_mfma_f32_16x16x32_bf16 v[48:51], v[190:193], v[198:201], v[48:51]
	v_mfma_f32_16x16x32_bf16 v[36:39], v[182:185], v[206:209], v[36:39]
	v_mfma_f32_16x16x32_bf16 v[32:35], v[190:193], v[206:209], v[32:35]
	v_mfma_f32_16x16x32_bf16 v[20:23], v[182:185], v[226:229], v[20:23]
	v_mfma_f32_16x16x32_bf16 v[16:19], v[190:193], v[226:229], v[16:19]
	v_mfma_f32_16x16x32_bf16 v[4:7], v[182:185], v[234:237], v[4:7]
	v_mfma_f32_16x16x32_bf16 v[0:3], v[190:193], v[234:237], v[0:3]
	v_mfma_f32_16x16x32_bf16 v[52:55], v[186:189], v[202:205], v[52:55]
	v_mfma_f32_16x16x32_bf16 v[48:51], v[194:197], v[202:205], v[48:51]
	v_mfma_f32_16x16x32_bf16 v[36:39], v[186:189], v[222:225], v[36:39]
	v_mfma_f32_16x16x32_bf16 v[32:35], v[194:197], v[222:225], v[32:35]
	v_mfma_f32_16x16x32_bf16 v[20:23], v[186:189], v[230:233], v[20:23]
	v_mfma_f32_16x16x32_bf16 v[16:19], v[194:197], v[230:233], v[16:19]
	v_mfma_f32_16x16x32_bf16 v[4:7], v[186:189], v[238:241], v[4:7]
	v_mfma_f32_16x16x32_bf16 v[0:3], v[194:197], v[238:241], v[0:3]
	s_barrier
	s_add_i32 s59, 0, 0x18000
	v_add_u32_e32 v145, s59, v177
	s_add_i32 s60, 0, 0x1c000
	ds_read_b128 v[146:149], v145
	ds_read_b128 v[150:153], v145 offset:1024
	ds_read_b128 v[154:157], v145 offset:2048
	ds_read_b128 v[172:175], v145 offset:3072
	v_add_u32_e32 v145, s60, v177
	ds_read_b128 v[182:185], v145
	ds_read_b128 v[186:189], v145 offset:1024
	ds_read_b128 v[190:193], v145 offset:2048
	ds_read_b128 v[194:197], v145 offset:3072
	s_add_u32 s10, s10, s6
	s_addc_u32 s11, s11, s7
	s_mov_b32 m0, s23
	v_lshl_add_u64 v[248:249], s[10:11], 0, v[136:137]
	ds_read_b128 v[198:201], v181 offset:32768
	ds_read_b128 v[202:205], v181 offset:33792
	ds_read_b128 v[206:209], v181 offset:34816
	ds_read_b128 v[222:225], v181 offset:35840
	ds_read_b128 v[226:229], v181 offset:36864
	ds_read_b128 v[230:233], v181 offset:37888
	ds_read_b128 v[234:237], v181 offset:38912
	ds_read_b128 v[238:241], v181 offset:39936
	global_load_lds_dwordx4 v[248:249], off
	v_lshl_add_u64 v[248:249], s[10:11], 0, v[132:133]
	s_mov_b32 m0, s24
	s_nop 0
	global_load_lds_dwordx4 v[248:249], off
	s_waitcnt vmcnt(8)
	s_waitcnt lgkmcnt(0)
	s_barrier
	s_waitcnt lgkmcnt(0)
	v_mfma_f32_16x16x32_bf16 v[126:129], v[146:149], v[198:201], v[126:129]
	v_mfma_f32_16x16x32_bf16 v[122:125], v[154:157], v[198:201], v[122:125]
	v_mfma_f32_16x16x32_bf16 v[110:113], v[146:149], v[206:209], v[110:113]
	v_mfma_f32_16x16x32_bf16 v[106:109], v[154:157], v[206:209], v[106:109]
	v_mfma_f32_16x16x32_bf16 v[94:97], v[146:149], v[226:229], v[94:97]
	v_mfma_f32_16x16x32_bf16 v[90:93], v[154:157], v[226:229], v[90:93]
	v_mfma_f32_16x16x32_bf16 v[78:81], v[146:149], v[234:237], v[78:81]
	v_mfma_f32_16x16x32_bf16 v[74:77], v[154:157], v[234:237], v[74:77]
	v_mfma_f32_16x16x32_bf16 v[126:129], v[150:153], v[202:205], v[126:129]
	v_mfma_f32_16x16x32_bf16 v[122:125], v[172:175], v[202:205], v[122:125]
	v_mfma_f32_16x16x32_bf16 v[110:113], v[150:153], v[222:225], v[110:113]
	v_mfma_f32_16x16x32_bf16 v[106:109], v[172:175], v[222:225], v[106:109]
	v_mfma_f32_16x16x32_bf16 v[94:97], v[150:153], v[230:233], v[94:97]
	v_mfma_f32_16x16x32_bf16 v[90:93], v[172:175], v[230:233], v[90:93]
	v_mfma_f32_16x16x32_bf16 v[78:81], v[150:153], v[238:241], v[78:81]
	v_mfma_f32_16x16x32_bf16 v[74:77], v[172:175], v[238:241], v[74:77]
	v_mfma_f32_16x16x32_bf16 v[118:121], v[182:185], v[198:201], v[118:121]
	v_mfma_f32_16x16x32_bf16 v[114:117], v[190:193], v[198:201], v[114:117]
	v_mfma_f32_16x16x32_bf16 v[102:105], v[182:185], v[206:209], v[102:105]
	v_mfma_f32_16x16x32_bf16 v[98:101], v[190:193], v[206:209], v[98:101]
	v_mfma_f32_16x16x32_bf16 v[86:89], v[182:185], v[226:229], v[86:89]
	v_mfma_f32_16x16x32_bf16 v[82:85], v[190:193], v[226:229], v[82:85]
	v_mfma_f32_16x16x32_bf16 v[70:73], v[182:185], v[234:237], v[70:73]
	v_mfma_f32_16x16x32_bf16 v[66:69], v[190:193], v[234:237], v[66:69]
	v_mfma_f32_16x16x32_bf16 v[118:121], v[186:189], v[202:205], v[118:121]
	v_mfma_f32_16x16x32_bf16 v[114:117], v[194:197], v[202:205], v[114:117]
	v_mfma_f32_16x16x32_bf16 v[102:105], v[186:189], v[222:225], v[102:105]
	v_mfma_f32_16x16x32_bf16 v[98:101], v[194:197], v[222:225], v[98:101]
	v_mfma_f32_16x16x32_bf16 v[86:89], v[186:189], v[230:233], v[86:89]
	v_mfma_f32_16x16x32_bf16 v[82:85], v[194:197], v[230:233], v[82:85]
	v_mfma_f32_16x16x32_bf16 v[70:73], v[186:189], v[238:241], v[70:73]
	v_mfma_f32_16x16x32_bf16 v[66:69], v[194:197], v[238:241], v[66:69]
	s_barrier
; #define PG8_STAGE(bufoff, gbase, voff) do { _Pragma("unroll") for (int _i = 0; _i < 2; ++_i) \
;         __builtin_amdgcn_global_load_lds((const unsigned*)((const char*)(gbase) + (voff)[_i]), (LAS unsigned*)(lds + (bufoff) + ldsw + _i * 8192), 16, 0, 0); } while (0)
; #define PG8_LDA(dst, b, h) do { _Pragma("unroll") for (int m = 0; m < 4; ++m) _Pragma("unroll") for (int k = 0; k < 2; ++k) dst[m][k] = *(const LAS bf16x8*)(lds + PG8_SA(b, h) + aoff + m * 2048 + k * 1024); } while (0)
; #define PG8_MMA(ai, bj, At, Bt) do { __builtin_amdgcn_s_setprio(1); _Pragma("unroll") for (int m = 0; m < 4; ++m) _Pragma("unroll") for (int n = 0; n < 2; ++n) _Pragma("unroll") for (int k = 0; k < 2; ++k) \
;         acc[ai][bj][m][n] = __builtin_amdgcn_mfma_f32_16x16x32_bf16(Bt[n][k], At[m][k], acc[ai][bj][m][n], 0, 0, 0); __builtin_amdgcn_s_setprio(0); } while (0)
; #define PG8_WAIT_V(n) asm volatile("s_waitcnt vmcnt(" #n ")" ::: "memory")
; #define PG8_WAIT_L(n) asm volatile("s_waitcnt lgkmcnt(" #n ")" ::: "memory")
; #define PG8_BAR __builtin_amdgcn_s_barrier()
; #define PG8_SCHED __builtin_amdgcn_sched_barrier(0)
; template <class Epi>
; __device__ __forceinline__ void gemm_phase(LAS unsigned char* lds, const Gemm g, const StaticOrder& S, const Epi& E) {
;     ...
;             PG8_LDA(At, 1, 1); PG8_STAGE(PG8_SB(1, 0), b3, voffB); PG8_STAGE(PG8_SB(1, 1), b3 + hstepB, voffB); PG8_STAGE(PG8_SA(1, 0), a3, voffA);
;             PG8_WAIT_V(8); PG8_WAIT_L(0); PG8_BAR; PG8_MMA(1, 0, At, B0); PG8_MMA(1, 1, At, B1); PG8_BAR; PG8_SCHED;
;         }
	s_add_i32 s10, s59, s20
	v_lshl_add_u64 v[178:179], v[178:179], 0, s[82:83]
	s_mov_b32 m0, s10
	ds_read_b128 v[198:201], v181 offset:49152
	ds_read_b128 v[202:205], v181 offset:50176
	ds_read_b128 v[206:209], v181 offset:51200
	ds_read_b128 v[222:225], v181 offset:52224
	ds_read_b128 v[226:229], v181 offset:53248
	ds_read_b128 v[230:233], v181 offset:54272
	ds_read_b128 v[234:237], v181 offset:55296
	ds_read_b128 v[238:241], v181 offset:56320
	global_load_lds_dwordx4 v[178:179], off
	v_lshl_add_u64 v[178:179], v[216:217], 0, s[82:83]
	s_add_i32 m0, s10, 0x2000
	s_add_i32 s10, s60, s20
	global_load_lds_dwordx4 v[178:179], off
	v_lshl_add_u64 v[178:179], v[218:219], 0, s[82:83]
	s_mov_b32 m0, s10
	s_nop 0
	global_load_lds_dwordx4 v[178:179], off
	v_lshl_add_u64 v[178:179], v[242:243], 0, s[82:83]
	s_add_i32 m0, s10, 0x2000
	s_nop 0
	global_load_lds_dwordx4 v[178:179], off
	v_lshl_add_u64 v[178:179], v[244:245], 0, s[82:83]
	s_mov_b32 m0, s25
	s_nop 0
	global_load_lds_dwordx4 v[178:179], off
	v_lshl_add_u64 v[178:179], v[246:247], 0, s[82:83]
	s_mov_b32 m0, s26
	s_nop 0
	global_load_lds_dwordx4 v[178:179], off
	s_waitcnt vmcnt(8)
	s_waitcnt lgkmcnt(0)
	s_barrier
	s_waitcnt lgkmcnt(0)
	v_mfma_f32_16x16x32_bf16 v[60:63], v[146:149], v[198:201], v[60:63]
	v_mfma_f32_16x16x32_bf16 v[56:59], v[154:157], v[198:201], v[56:59]
	v_mfma_f32_16x16x32_bf16 v[44:47], v[146:149], v[206:209], v[44:47]
	v_mfma_f32_16x16x32_bf16 v[40:43], v[154:157], v[206:209], v[40:43]
	v_mfma_f32_16x16x32_bf16 v[28:31], v[146:149], v[226:229], v[28:31]
	v_mfma_f32_16x16x32_bf16 v[24:27], v[154:157], v[226:229], v[24:27]
	v_mfma_f32_16x16x32_bf16 v[12:15], v[146:149], v[234:237], v[12:15]
	v_mfma_f32_16x16x32_bf16 v[8:11], v[154:157], v[234:237], v[8:11]
	v_mfma_f32_16x16x32_bf16 v[60:63], v[150:153], v[202:205], v[60:63]
	v_mfma_f32_16x16x32_bf16 v[56:59], v[172:175], v[202:205], v[56:59]
	v_mfma_f32_16x16x32_bf16 v[44:47], v[150:153], v[222:225], v[44:47]
	v_mfma_f32_16x16x32_bf16 v[40:43], v[172:175], v[222:225], v[40:43]
	v_mfma_f32_16x16x32_bf16 v[28:31], v[150:153], v[230:233], v[28:31]
	v_mfma_f32_16x16x32_bf16 v[24:27], v[172:175], v[230:233], v[24:27]
	v_mfma_f32_16x16x32_bf16 v[12:15], v[150:153], v[238:241], v[12:15]
	v_mfma_f32_16x16x32_bf16 v[8:11], v[172:175], v[238:241], v[8:11]
	v_mfma_f32_16x16x32_bf16 v[52:55], v[182:185], v[198:201], v[52:55]
	v_mfma_f32_16x16x32_bf16 v[48:51], v[190:193], v[198:201], v[48:51]
	v_mfma_f32_16x16x32_bf16 v[36:39], v[182:185], v[206:209], v[36:39]
	v_mfma_f32_16x16x32_bf16 v[32:35], v[190:193], v[206:209], v[32:35]
	v_mfma_f32_16x16x32_bf16 v[20:23], v[182:185], v[226:229], v[20:23]
	v_mfma_f32_16x16x32_bf16 v[16:19], v[190:193], v[226:229], v[16:19]
	v_mfma_f32_16x16x32_bf16 v[4:7], v[182:185], v[234:237], v[4:7]
	v_mfma_f32_16x16x32_bf16 v[0:3], v[190:193], v[234:237], v[0:3]
	v_mfma_f32_16x16x32_bf16 v[52:55], v[186:189], v[202:205], v[52:55]
	v_mfma_f32_16x16x32_bf16 v[48:51], v[194:197], v[202:205], v[48:51]
	v_mfma_f32_16x16x32_bf16 v[36:39], v[186:189], v[222:225], v[36:39]
	v_mfma_f32_16x16x32_bf16 v[32:35], v[194:197], v[222:225], v[32:35]
	v_mfma_f32_16x16x32_bf16 v[20:23], v[186:189], v[230:233], v[20:23]
	v_mfma_f32_16x16x32_bf16 v[16:19], v[194:197], v[230:233], v[16:19]
	v_mfma_f32_16x16x32_bf16 v[4:7], v[186:189], v[238:241], v[4:7]
	v_mfma_f32_16x16x32_bf16 v[0:3], v[194:197], v[238:241], v[0:3]
	s_barrier
	s_add_u32 s54, s54, 0x100
	s_addc_u32 s55, s55, 0
	s_add_u32 s0, s0, 0x100
	s_addc_u32 s1, s1, 0
	s_cmp_ge_i32 s58, s27
	s_mov_b32 s10, s58
	s_cbranch_scc0 .LBB0_3352

; #define PG8_STAGE(bufoff, gbase, voff) do { _Pragma("unroll") for (int _i = 0; _i < 2; ++_i) \
;         __builtin_amdgcn_global_load_lds((const unsigned*)((const char*)(gbase) + (voff)[_i]), (LAS unsigned*)(lds + (bufoff) + ldsw + _i * 8192), 16, 0, 0); } while (0)
; #define PG8_LDA(dst, b, h) do { _Pragma("unroll") for (int m = 0; m < 4; ++m) _Pragma("unroll") for (int k = 0; k < 2; ++k) dst[m][k] = *(const LAS bf16x8*)(lds + PG8_SA(b, h) + aoff + m * 2048 + k * 1024); } while (0)
; #define PG8_LDB(dst, b, h) do { _Pragma("unroll") for (int n = 0; n < 2; ++n) _Pragma("unroll") for (int k = 0; k < 2; ++k) dst[n][k] = *(const LAS bf16x8*)(lds + PG8_SB(b, h) + boff + n * 2048 + k * 1024); } while (0)
; #define PG8_MMA(ai, bj, At, Bt) do { __builtin_amdgcn_s_setprio(1); _Pragma("unroll") for (int m = 0; m < 4; ++m) _Pragma("unroll") for (int n = 0; n < 2; ++n) _Pragma("unroll") for (int k = 0; k < 2; ++k) \
;         acc[ai][bj][m][n] = __builtin_amdgcn_mfma_f32_16x16x32_bf16(Bt[n][k], At[m][k], acc[ai][bj][m][n], 0, 0, 0); __builtin_amdgcn_s_setprio(0); } while (0)
; #define PG8_WAIT_V(n) asm volatile("s_waitcnt vmcnt(" #n ")" ::: "memory")
; #define PG8_WAIT_L(n) asm volatile("s_waitcnt lgkmcnt(" #n ")" ::: "memory")
; #define PG8_BAR __builtin_amdgcn_s_barrier()
; #define PG8_SCHED __builtin_amdgcn_sched_barrier(0)
; template <class Epi>
; __device__ __forceinline__ void gemm_phase(LAS unsigned char* lds, const Gemm g, const StaticOrder& S, const Epi& E) {
;     ...
;         for (int t = 0; t < nt; t += 2) {
;             const bool last = (t == nt - 2);
;             const char* a1 = cA + (size_t)(t + 1) * kstep;
;             const char* a2 = last ? nA : cA + (size_t)(t + 2) * kstep; const char* b2 = last ? nB : cB + (size_t)(t + 2) * kstep;
;             const char* a3 = a2 + kstep; const char* b3 = b2 + kstep;
;             PG8_LDB(B0, 0, 0); PG8_LDB(B1, 0, 1); PG8_SCHED; PG8_LDA(At, 0, 0); PG8_STAGE(PG8_SA(1, 1), a1 + hstepA, voffA);
;             PG8_WAIT_V(8); PG8_WAIT_L(0); PG8_BAR; PG8_MMA(0, 0, At, B0); PG8_MMA(0, 1, At, B1); PG8_BAR; PG8_SCHED;
;             PG8_LDA(At, 0, 1); PG8_STAGE(PG8_SB(0, 0), b2, voffB); PG8_STAGE(PG8_SB(0, 1), b2 + hstepB, voffB); PG8_STAGE(PG8_SA(0, 0), a2, voffA);
;             PG8_WAIT_V(8); PG8_WAIT_L(0); PG8_BAR; PG8_MMA(1, 0, At, B0); PG8_MMA(1, 1, At, B1); PG8_BAR; PG8_SCHED;
.LBB0_3377:
	s_add_i32 s30, s8, 2
	s_add_u32 s31, s0, 0x80
	s_addc_u32 s9, s1, 0
	s_add_i32 s40, 0, 0x10000
	s_cmp_eq_u32 s64, s8
	s_cselect_b32 s9, s5, s9
	s_cselect_b32 s8, s4, s31
	s_cselect_b32 s35, s61, s29
	s_cselect_b32 s34, s60, s11
	s_add_i32 s31, 0, 0x14000
	v_add_u32_e32 v172, s40, v139
	v_add_u32_e32 v188, s31, v139
	ds_read_b128 v[146:149], v172
	ds_read_b128 v[150:153], v172 offset:1024
	ds_read_b128 v[154:157], v172 offset:2048
	ds_read_b128 v[172:175], v172 offset:3072
	ds_read_b128 v[176:179], v188
	ds_read_b128 v[180:183], v188 offset:1024
	ds_read_b128 v[184:187], v188 offset:2048
	ds_read_b128 v[188:191], v188 offset:3072
	v_lshl_add_u64 v[216:217], s[0:1], 0, v[144:145]
	s_add_i32 m0, s21, 0xc000
	ds_read_b128 v[192:195], v200
	ds_read_b128 v[196:199], v200 offset:1024
	ds_read_b128 v[202:205], v200 offset:2048
	ds_read_b128 v[206:209], v200 offset:3072
	ds_read_b128 v[222:225], v200 offset:4096
	ds_read_b128 v[226:229], v200 offset:5120
	ds_read_b128 v[230:233], v200 offset:6144
	ds_read_b128 v[234:237], v200 offset:7168
	global_load_lds_dwordx4 v[216:217], off
	v_lshl_add_u64 v[216:217], s[0:1], 0, v[142:143]
	s_add_i32 m0, s21, 0xe000
	s_nop 0
	global_load_lds_dwordx4 v[216:217], off
	s_waitcnt vmcnt(8)
	s_waitcnt lgkmcnt(0)
	s_barrier
	s_waitcnt lgkmcnt(0)
	v_mfma_f32_16x16x32_bf16 v[126:129], v[146:149], v[192:195], v[126:129]
	v_mfma_f32_16x16x32_bf16 v[122:125], v[154:157], v[192:195], v[122:125]
	v_mfma_f32_16x16x32_bf16 v[110:113], v[146:149], v[202:205], v[110:113]
	v_mfma_f32_16x16x32_bf16 v[106:109], v[154:157], v[202:205], v[106:109]
	v_mfma_f32_16x16x32_bf16 v[94:97], v[146:149], v[222:225], v[94:97]
	v_mfma_f32_16x16x32_bf16 v[90:93], v[154:157], v[222:225], v[90:93]
	v_mfma_f32_16x16x32_bf16 v[78:81], v[146:149], v[230:233], v[78:81]
	v_mfma_f32_16x16x32_bf16 v[74:77], v[154:157], v[230:233], v[74:77]
	v_mfma_f32_16x16x32_bf16 v[126:129], v[150:153], v[196:199], v[126:129]
	v_mfma_f32_16x16x32_bf16 v[122:125], v[172:175], v[196:199], v[122:125]
	v_mfma_f32_16x16x32_bf16 v[110:113], v[150:153], v[206:209], v[110:113]
	v_mfma_f32_16x16x32_bf16 v[106:109], v[172:175], v[206:209], v[106:109]
	v_mfma_f32_16x16x32_bf16 v[94:97], v[150:153], v[226:229], v[94:97]
	v_mfma_f32_16x16x32_bf16 v[90:93], v[172:175], v[226:229], v[90:93]
	v_mfma_f32_16x16x32_bf16 v[78:81], v[150:153], v[234:237], v[78:81]
	v_mfma_f32_16x16x32_bf16 v[74:77], v[172:175], v[234:237], v[74:77]
	v_mfma_f32_16x16x32_bf16 v[118:121], v[176:179], v[192:195], v[118:121]
	v_mfma_f32_16x16x32_bf16 v[114:117], v[184:187], v[192:195], v[114:117]
	v_mfma_f32_16x16x32_bf16 v[102:105], v[176:179], v[202:205], v[102:105]
	v_mfma_f32_16x16x32_bf16 v[98:101], v[184:187], v[202:205], v[98:101]
	v_mfma_f32_16x16x32_bf16 v[86:89], v[176:179], v[222:225], v[86:89]
	v_mfma_f32_16x16x32_bf16 v[82:85], v[184:187], v[222:225], v[82:85]
	v_mfma_f32_16x16x32_bf16 v[70:73], v[176:179], v[230:233], v[70:73]
	v_mfma_f32_16x16x32_bf16 v[66:69], v[184:187], v[230:233], v[66:69]
	v_mfma_f32_16x16x32_bf16 v[118:121], v[180:183], v[196:199], v[118:121]
	v_mfma_f32_16x16x32_bf16 v[114:117], v[188:191], v[196:199], v[114:117]
	v_mfma_f32_16x16x32_bf16 v[102:105], v[180:183], v[206:209], v[102:105]
	v_mfma_f32_16x16x32_bf16 v[98:101], v[188:191], v[206:209], v[98:101]
	v_mfma_f32_16x16x32_bf16 v[86:89], v[180:183], v[226:229], v[86:89]
	v_mfma_f32_16x16x32_bf16 v[82:85], v[188:191], v[226:229], v[82:85]
	v_mfma_f32_16x16x32_bf16 v[70:73], v[180:183], v[234:237], v[70:73]
	v_mfma_f32_16x16x32_bf16 v[66:69], v[188:191], v[234:237], v[66:69]
	s_barrier
	s_add_i32 s40, s40, s20
	v_lshl_add_u64 v[216:217], s[34:35], 0, v[134:135]
	s_mov_b32 m0, s40
	ds_read_b128 v[192:195], v200 offset:16384
	ds_read_b128 v[196:199], v200 offset:17408
	ds_read_b128 v[202:205], v200 offset:18432
	ds_read_b128 v[206:209], v200 offset:19456
	ds_read_b128 v[222:225], v200 offset:20480
	ds_read_b128 v[226:229], v200 offset:21504
	ds_read_b128 v[230:233], v200 offset:22528
	ds_read_b128 v[234:237], v200 offset:23552
	global_load_lds_dwordx4 v[216:217], off
	s_add_i32 m0, s40, 0x2000
	v_lshl_add_u64 v[218:219], s[34:35], 0, v[130:131]
	s_add_u32 s34, s34, s36
	s_addc_u32 s35, s35, s37
	s_add_i32 s31, s31, s20
	global_load_lds_dwordx4 v[218:219], off
	v_lshl_add_u64 v[238:239], s[34:35], 0, v[134:135]
	s_mov_b32 m0, s31
	v_lshl_add_u64 v[240:241], s[34:35], 0, v[130:131]
	global_load_lds_dwordx4 v[238:239], off
	s_add_i32 m0, s31, 0x2000
	v_lshl_add_u64 v[242:243], s[8:9], 0, v[136:137]
	global_load_lds_dwordx4 v[240:241], off
	s_mov_b32 m0, s21
	v_lshl_add_u64 v[244:245], s[8:9], 0, v[132:133]
	global_load_lds_dwordx4 v[242:243], off
	s_mov_b32 m0, s22
	s_nop 0
	global_load_lds_dwordx4 v[244:245], off
	s_waitcnt vmcnt(8)
	s_waitcnt lgkmcnt(0)
	s_barrier
; #define PG8_STAGE(bufoff, gbase, voff) do { _Pragma("unroll") for (int _i = 0; _i < 2; ++_i) \
;         __builtin_amdgcn_global_load_lds((const unsigned*)((const char*)(gbase) + (voff)[_i]), (LAS unsigned*)(lds + (bufoff) + ldsw + _i * 8192), 16, 0, 0); } while (0)
; #define PG8_LDA(dst, b, h) do { _Pragma("unroll") for (int m = 0; m < 4; ++m) _Pragma("unroll") for (int k = 0; k < 2; ++k) dst[m][k] = *(const LAS bf16x8*)(lds + PG8_SA(b, h) + aoff + m * 2048 + k * 1024); } while (0)
; #define PG8_LDB(dst, b, h) do { _Pragma("unroll") for (int n = 0; n < 2; ++n) _Pragma("unroll") for (int k = 0; k < 2; ++k) dst[n][k] = *(const LAS bf16x8*)(lds + PG8_SB(b, h) + boff + n * 2048 + k * 1024); } while (0)
; #define PG8_MMA(ai, bj, At, Bt) do { __builtin_amdgcn_s_setprio(1); _Pragma("unroll") for (int m = 0; m < 4; ++m) _Pragma("unroll") for (int n = 0; n < 2; ++n) _Pragma("unroll") for (int k = 0; k < 2; ++k) \
;         acc[ai][bj][m][n] = __builtin_amdgcn_mfma_f32_16x16x32_bf16(Bt[n][k], At[m][k], acc[ai][bj][m][n], 0, 0, 0); __builtin_amdgcn_s_setprio(0); } while (0)
; #define PG8_WAIT_V(n) asm volatile("s_waitcnt vmcnt(" #n ")" ::: "memory")
; #define PG8_WAIT_L(n) asm volatile("s_waitcnt lgkmcnt(" #n ")" ::: "memory")
; #define PG8_BAR __builtin_amdgcn_s_barrier()
; #define PG8_SCHED __builtin_amdgcn_sched_barrier(0)
; template <class Epi>
; __device__ __forceinline__ void gemm_phase(LAS unsigned char* lds, const Gemm g, const StaticOrder& S, const Epi& E) {
;     ...
;             PG8_WAIT_V(8); PG8_WAIT_L(0); PG8_BAR; PG8_MMA(0, 0, At, B0); PG8_MMA(0, 1, At, B1); PG8_BAR; PG8_SCHED;
;             PG8_LDA(At, 0, 1); PG8_STAGE(PG8_SB(0, 0), b2, voffB); PG8_STAGE(PG8_SB(0, 1), b2 + hstepB, voffB); PG8_STAGE(PG8_SA(0, 0), a2, voffA);
;             PG8_WAIT_V(8); PG8_WAIT_L(0); PG8_BAR; PG8_MMA(1, 0, At, B0); PG8_MMA(1, 1, At, B1); PG8_BAR; PG8_SCHED;
;             PG8_LDB(B0, 1, 0); PG8_LDB(B1, 1, 1); PG8_SCHED; PG8_LDA(At, 1, 0); PG8_STAGE(PG8_SA(0, 1), a2 + hstepA, voffA);
;             PG8_WAIT_V(8); PG8_WAIT_L(0); PG8_BAR; PG8_MMA(0, 0, At, B0); PG8_MMA(0, 1, At, B1); PG8_BAR; PG8_SCHED;
	s_waitcnt lgkmcnt(0)
	v_mfma_f32_16x16x32_bf16 v[60:63], v[146:149], v[192:195], v[60:63]
	v_mfma_f32_16x16x32_bf16 v[56:59], v[154:157], v[192:195], v[56:59]
	v_mfma_f32_16x16x32_bf16 v[44:47], v[146:149], v[202:205], v[44:47]
	v_mfma_f32_16x16x32_bf16 v[40:43], v[154:157], v[202:205], v[40:43]
	v_mfma_f32_16x16x32_bf16 v[28:31], v[146:149], v[222:225], v[28:31]
	v_mfma_f32_16x16x32_bf16 v[24:27], v[154:157], v[222:225], v[24:27]
	v_mfma_f32_16x16x32_bf16 v[12:15], v[146:149], v[230:233], v[12:15]
	v_mfma_f32_16x16x32_bf16 v[8:11], v[154:157], v[230:233], v[8:11]
	v_mfma_f32_16x16x32_bf16 v[60:63], v[150:153], v[196:199], v[60:63]
	v_mfma_f32_16x16x32_bf16 v[56:59], v[172:175], v[196:199], v[56:59]
	v_mfma_f32_16x16x32_bf16 v[44:47], v[150:153], v[206:209], v[44:47]
	v_mfma_f32_16x16x32_bf16 v[40:43], v[172:175], v[206:209], v[40:43]
	v_mfma_f32_16x16x32_bf16 v[28:31], v[150:153], v[226:229], v[28:31]
	v_mfma_f32_16x16x32_bf16 v[24:27], v[172:175], v[226:229], v[24:27]
	v_mfma_f32_16x16x32_bf16 v[12:15], v[150:153], v[234:237], v[12:15]
	v_mfma_f32_16x16x32_bf16 v[8:11], v[172:175], v[234:237], v[8:11]
	v_mfma_f32_16x16x32_bf16 v[52:55], v[176:179], v[192:195], v[52:55]
	v_mfma_f32_16x16x32_bf16 v[48:51], v[184:187], v[192:195], v[48:51]
	v_mfma_f32_16x16x32_bf16 v[36:39], v[176:179], v[202:205], v[36:39]
	v_mfma_f32_16x16x32_bf16 v[32:35], v[184:187], v[202:205], v[32:35]
	v_mfma_f32_16x16x32_bf16 v[20:23], v[176:179], v[222:225], v[20:23]
	v_mfma_f32_16x16x32_bf16 v[16:19], v[184:187], v[222:225], v[16:19]
	v_mfma_f32_16x16x32_bf16 v[4:7], v[176:179], v[230:233], v[4:7]
	v_mfma_f32_16x16x32_bf16 v[0:3], v[184:187], v[230:233], v[0:3]
	v_mfma_f32_16x16x32_bf16 v[52:55], v[180:183], v[196:199], v[52:55]
	v_mfma_f32_16x16x32_bf16 v[48:51], v[188:191], v[196:199], v[48:51]
	v_mfma_f32_16x16x32_bf16 v[36:39], v[180:183], v[206:209], v[36:39]
	v_mfma_f32_16x16x32_bf16 v[32:35], v[188:191], v[206:209], v[32:35]
	v_mfma_f32_16x16x32_bf16 v[20:23], v[180:183], v[226:229], v[20:23]
	v_mfma_f32_16x16x32_bf16 v[16:19], v[188:191], v[226:229], v[16:19]
	v_mfma_f32_16x16x32_bf16 v[4:7], v[180:183], v[234:237], v[4:7]
	v_mfma_f32_16x16x32_bf16 v[0:3], v[188:191], v[234:237], v[0:3]
	s_barrier
	s_add_i32 s31, 0, 0x18000
	s_add_i32 s34, 0, 0x1c000
	v_add_u32_e32 v172, s31, v139
	v_add_u32_e32 v188, s34, v139
	ds_read_b128 v[146:149], v172
	ds_read_b128 v[150:153], v172 offset:1024
	ds_read_b128 v[154:157], v172 offset:2048
	ds_read_b128 v[172:175], v172 offset:3072
	ds_read_b128 v[176:179], v188
	ds_read_b128 v[180:183], v188 offset:1024
	ds_read_b128 v[184:187], v188 offset:2048
	ds_read_b128 v[188:191], v188 offset:3072
	s_add_u32 s8, s8, s6
	s_addc_u32 s9, s9, s7
	s_mov_b32 m0, s23
	v_lshl_add_u64 v[246:247], s[8:9], 0, v[136:137]
	ds_read_b128 v[192:195], v200 offset:32768
	ds_read_b128 v[196:199], v200 offset:33792
	ds_read_b128 v[202:205], v200 offset:34816
	ds_read_b128 v[206:209], v200 offset:35840
	ds_read_b128 v[222:225], v200 offset:36864
	ds_read_b128 v[226:229], v200 offset:37888
	ds_read_b128 v[230:233], v200 offset:38912
	ds_read_b128 v[234:237], v200 offset:39936
	global_load_lds_dwordx4 v[246:247], off
	v_lshl_add_u64 v[246:247], s[8:9], 0, v[132:133]
	s_mov_b32 m0, s24
	s_nop 0
	global_load_lds_dwordx4 v[246:247], off
	s_waitcnt vmcnt(8)
	s_waitcnt lgkmcnt(0)
	s_barrier
	s_waitcnt lgkmcnt(0)
	v_mfma_f32_16x16x32_bf16 v[126:129], v[146:149], v[192:195], v[126:129]
	v_mfma_f32_16x16x32_bf16 v[122:125], v[154:157], v[192:195], v[122:125]
	v_mfma_f32_16x16x32_bf16 v[110:113], v[146:149], v[202:205], v[110:113]
	v_mfma_f32_16x16x32_bf16 v[106:109], v[154:157], v[202:205], v[106:109]
	v_mfma_f32_16x16x32_bf16 v[94:97], v[146:149], v[222:225], v[94:97]
	v_mfma_f32_16x16x32_bf16 v[90:93], v[154:157], v[222:225], v[90:93]
	v_mfma_f32_16x16x32_bf16 v[78:81], v[146:149], v[230:233], v[78:81]
	v_mfma_f32_16x16x32_bf16 v[74:77], v[154:157], v[230:233], v[74:77]
	v_mfma_f32_16x16x32_bf16 v[126:129], v[150:153], v[196:199], v[126:129]
	v_mfma_f32_16x16x32_bf16 v[122:125], v[172:175], v[196:199], v[122:125]
	v_mfma_f32_16x16x32_bf16 v[110:113], v[150:153], v[206:209], v[110:113]
	v_mfma_f32_16x16x32_bf16 v[106:109], v[172:175], v[206:209], v[106:109]
	v_mfma_f32_16x16x32_bf16 v[94:97], v[150:153], v[226:229], v[94:97]
	v_mfma_f32_16x16x32_bf16 v[90:93], v[172:175], v[226:229], v[90:93]
	v_mfma_f32_16x16x32_bf16 v[78:81], v[150:153], v[234:237], v[78:81]
	v_mfma_f32_16x16x32_bf16 v[74:77], v[172:175], v[234:237], v[74:77]
	v_mfma_f32_16x16x32_bf16 v[118:121], v[176:179], v[192:195], v[118:121]
	v_mfma_f32_16x16x32_bf16 v[114:117], v[184:187], v[192:195], v[114:117]
	v_mfma_f32_16x16x32_bf16 v[102:105], v[176:179], v[202:205], v[102:105]
	v_mfma_f32_16x16x32_bf16 v[98:101], v[184:187], v[202:205], v[98:101]
	v_mfma_f32_16x16x32_bf16 v[86:89], v[176:179], v[222:225], v[86:89]
	v_mfma_f32_16x16x32_bf16 v[82:85], v[184:187], v[222:225], v[82:85]
	v_mfma_f32_16x16x32_bf16 v[70:73], v[176:179], v[230:233], v[70:73]
	v_mfma_f32_16x16x32_bf16 v[66:69], v[184:187], v[230:233], v[66:69]
	v_mfma_f32_16x16x32_bf16 v[118:121], v[180:183], v[196:199], v[118:121]
	v_mfma_f32_16x16x32_bf16 v[114:117], v[188:191], v[196:199], v[114:117]
	v_mfma_f32_16x16x32_bf16 v[102:105], v[180:183], v[206:209], v[102:105]
	v_mfma_f32_16x16x32_bf16 v[98:101], v[188:191], v[206:209], v[98:101]
	v_mfma_f32_16x16x32_bf16 v[86:89], v[180:183], v[226:229], v[86:89]
	v_mfma_f32_16x16x32_bf16 v[82:85], v[188:191], v[226:229], v[82:85]
	v_mfma_f32_16x16x32_bf16 v[70:73], v[180:183], v[234:237], v[70:73]
	v_mfma_f32_16x16x32_bf16 v[66:69], v[188:191], v[234:237], v[66:69]
	s_barrier
; #define PG8_STAGE(bufoff, gbase, voff) do { _Pragma("unroll") for (int _i = 0; _i < 2; ++_i) \
;         __builtin_amdgcn_global_load_lds((const unsigned*)((const char*)(gbase) + (voff)[_i]), (LAS unsigned*)(lds + (bufoff) + ldsw + _i * 8192), 16, 0, 0); } while (0)
; #define PG8_LDA(dst, b, h) do { _Pragma("unroll") for (int m = 0; m < 4; ++m) _Pragma("unroll") for (int k = 0; k < 2; ++k) dst[m][k] = *(const LAS bf16x8*)(lds + PG8_SA(b, h) + aoff + m * 2048 + k * 1024); } while (0)
; #define PG8_MMA(ai, bj, At, Bt) do { __builtin_amdgcn_s_setprio(1); _Pragma("unroll") for (int m = 0; m < 4; ++m) _Pragma("unroll") for (int n = 0; n < 2; ++n) _Pragma("unroll") for (int k = 0; k < 2; ++k) \
;         acc[ai][bj][m][n] = __builtin_amdgcn_mfma_f32_16x16x32_bf16(Bt[n][k], At[m][k], acc[ai][bj][m][n], 0, 0, 0); __builtin_amdgcn_s_setprio(0); } while (0)
; #define PG8_WAIT_V(n) asm volatile("s_waitcnt vmcnt(" #n ")" ::: "memory")
; #define PG8_WAIT_L(n) asm volatile("s_waitcnt lgkmcnt(" #n ")" ::: "memory")
; #define PG8_BAR __builtin_amdgcn_s_barrier()
; #define PG8_SCHED __builtin_amdgcn_sched_barrier(0)
; template <class Epi>
; __device__ __forceinline__ void gemm_phase(LAS unsigned char* lds, const Gemm g, const StaticOrder& S, const Epi& E) {
;     ...
;             PG8_LDA(At, 1, 1); PG8_STAGE(PG8_SB(1, 0), b3, voffB); PG8_STAGE(PG8_SB(1, 1), b3 + hstepB, voffB); PG8_STAGE(PG8_SA(1, 0), a3, voffA);
;             PG8_WAIT_V(8); PG8_WAIT_L(0); PG8_BAR; PG8_MMA(1, 0, At, B0); PG8_MMA(1, 1, At, B1); PG8_BAR; PG8_SCHED;
;         }
	s_add_i32 s8, s31, s20
	v_lshl_add_u64 v[216:217], v[216:217], 0, s[82:83]
	s_mov_b32 m0, s8
	ds_read_b128 v[192:195], v200 offset:49152
	ds_read_b128 v[196:199], v200 offset:50176
	ds_read_b128 v[202:205], v200 offset:51200
	ds_read_b128 v[206:209], v200 offset:52224
	ds_read_b128 v[222:225], v200 offset:53248
	ds_read_b128 v[226:229], v200 offset:54272
	ds_read_b128 v[230:233], v200 offset:55296
	ds_read_b128 v[234:237], v200 offset:56320
	global_load_lds_dwordx4 v[216:217], off
	v_lshl_add_u64 v[216:217], v[218:219], 0, s[82:83]
	s_add_i32 m0, s8, 0x2000
	s_add_i32 s8, s34, s20
	global_load_lds_dwordx4 v[216:217], off
	v_lshl_add_u64 v[216:217], v[238:239], 0, s[82:83]
	s_mov_b32 m0, s8
	s_nop 0
	global_load_lds_dwordx4 v[216:217], off
	v_lshl_add_u64 v[216:217], v[240:241], 0, s[82:83]
	s_add_i32 m0, s8, 0x2000
	s_nop 0
	global_load_lds_dwordx4 v[216:217], off
	v_lshl_add_u64 v[216:217], v[242:243], 0, s[82:83]
	s_mov_b32 m0, s25
	s_nop 0
	global_load_lds_dwordx4 v[216:217], off
	v_lshl_add_u64 v[216:217], v[244:245], 0, s[82:83]
	s_mov_b32 m0, s26
	s_nop 0
	global_load_lds_dwordx4 v[216:217], off
	s_waitcnt vmcnt(8)
	s_waitcnt lgkmcnt(0)
	s_barrier
	s_waitcnt lgkmcnt(0)
	v_mfma_f32_16x16x32_bf16 v[60:63], v[146:149], v[192:195], v[60:63]
	v_mfma_f32_16x16x32_bf16 v[56:59], v[154:157], v[192:195], v[56:59]
	v_mfma_f32_16x16x32_bf16 v[44:47], v[146:149], v[202:205], v[44:47]
	v_mfma_f32_16x16x32_bf16 v[40:43], v[154:157], v[202:205], v[40:43]
	v_mfma_f32_16x16x32_bf16 v[28:31], v[146:149], v[222:225], v[28:31]
	v_mfma_f32_16x16x32_bf16 v[24:27], v[154:157], v[222:225], v[24:27]
	v_mfma_f32_16x16x32_bf16 v[12:15], v[146:149], v[230:233], v[12:15]
	v_mfma_f32_16x16x32_bf16 v[8:11], v[154:157], v[230:233], v[8:11]
	v_mfma_f32_16x16x32_bf16 v[60:63], v[150:153], v[196:199], v[60:63]
	v_mfma_f32_16x16x32_bf16 v[56:59], v[172:175], v[196:199], v[56:59]
	v_mfma_f32_16x16x32_bf16 v[44:47], v[150:153], v[206:209], v[44:47]
	v_mfma_f32_16x16x32_bf16 v[40:43], v[172:175], v[206:209], v[40:43]
	v_mfma_f32_16x16x32_bf16 v[28:31], v[150:153], v[226:229], v[28:31]
	v_mfma_f32_16x16x32_bf16 v[24:27], v[172:175], v[226:229], v[24:27]
	v_mfma_f32_16x16x32_bf16 v[12:15], v[150:153], v[234:237], v[12:15]
	v_mfma_f32_16x16x32_bf16 v[8:11], v[172:175], v[234:237], v[8:11]
	v_mfma_f32_16x16x32_bf16 v[52:55], v[176:179], v[192:195], v[52:55]
	v_mfma_f32_16x16x32_bf16 v[48:51], v[184:187], v[192:195], v[48:51]
	v_mfma_f32_16x16x32_bf16 v[36:39], v[176:179], v[202:205], v[36:39]
	v_mfma_f32_16x16x32_bf16 v[32:35], v[184:187], v[202:205], v[32:35]
	v_mfma_f32_16x16x32_bf16 v[20:23], v[176:179], v[222:225], v[20:23]
	v_mfma_f32_16x16x32_bf16 v[16:19], v[184:187], v[222:225], v[16:19]
	v_mfma_f32_16x16x32_bf16 v[4:7], v[176:179], v[230:233], v[4:7]
	v_mfma_f32_16x16x32_bf16 v[0:3], v[184:187], v[230:233], v[0:3]
	v_mfma_f32_16x16x32_bf16 v[52:55], v[180:183], v[196:199], v[52:55]
	v_mfma_f32_16x16x32_bf16 v[48:51], v[188:191], v[196:199], v[48:51]
	v_mfma_f32_16x16x32_bf16 v[36:39], v[180:183], v[206:209], v[36:39]
	v_mfma_f32_16x16x32_bf16 v[32:35], v[188:191], v[206:209], v[32:35]
	v_mfma_f32_16x16x32_bf16 v[20:23], v[180:183], v[226:229], v[20:23]
	v_mfma_f32_16x16x32_bf16 v[16:19], v[188:191], v[226:229], v[16:19]
	v_mfma_f32_16x16x32_bf16 v[4:7], v[180:183], v[234:237], v[4:7]
	v_mfma_f32_16x16x32_bf16 v[0:3], v[188:191], v[234:237], v[0:3]
	s_barrier
	s_add_u32 s11, s11, 0x100
	s_addc_u32 s29, s29, 0
	s_add_u32 s0, s0, 0x100
	s_addc_u32 s1, s1, 0
	s_cmp_ge_i32 s30, s27
	s_mov_b32 s8, s30
	s_cbranch_scc0 .LBB0_3377
	s_movk_i32 s34, 0xff80
	s_mov_b32 s35, -1

; #define PG8_STAGE(bufoff, gbase, voff) do { _Pragma("unroll") for (int _i = 0; _i < 2; ++_i) \
;         __builtin_amdgcn_global_load_lds((const unsigned*)((const char*)(gbase) + (voff)[_i]), (LAS unsigned*)(lds + (bufoff) + ldsw + _i * 8192), 16, 0, 0); } while (0)
; #define PG8_LDA(dst, b, h) do { _Pragma("unroll") for (int m = 0; m < 4; ++m) _Pragma("unroll") for (int k = 0; k < 2; ++k) dst[m][k] = *(const LAS bf16x8*)(lds + PG8_SA(b, h) + aoff + m * 2048 + k * 1024); } while (0)
; #define PG8_LDB(dst, b, h) do { _Pragma("unroll") for (int n = 0; n < 2; ++n) _Pragma("unroll") for (int k = 0; k < 2; ++k) dst[n][k] = *(const LAS bf16x8*)(lds + PG8_SB(b, h) + boff + n * 2048 + k * 1024); } while (0)
; #define PG8_MMA(ai, bj, At, Bt) do { __builtin_amdgcn_s_setprio(1); _Pragma("unroll") for (int m = 0; m < 4; ++m) _Pragma("unroll") for (int n = 0; n < 2; ++n) _Pragma("unroll") for (int k = 0; k < 2; ++k) \
;         acc[ai][bj][m][n] = __builtin_amdgcn_mfma_f32_16x16x32_bf16(Bt[n][k], At[m][k], acc[ai][bj][m][n], 0, 0, 0); __builtin_amdgcn_s_setprio(0); } while (0)
; #define PG8_WAIT_V(n) asm volatile("s_waitcnt vmcnt(" #n ")" ::: "memory")
; #define PG8_WAIT_L(n) asm volatile("s_waitcnt lgkmcnt(" #n ")" ::: "memory")
; #define PG8_BAR __builtin_amdgcn_s_barrier()
; #define PG8_SCHED __builtin_amdgcn_sched_barrier(0)
; template <class Epi>
; __device__ __forceinline__ void gemm_phase(LAS unsigned char* lds, const Gemm g, const StaticOrder& S, const Epi& E) {
;     ...
;         for (int t = 0; t < nt; t += 2) {
;             const bool last = (t == nt - 2);
;             const char* a1 = cA + (size_t)(t + 1) * kstep;
;             const char* a2 = last ? nA : cA + (size_t)(t + 2) * kstep; const char* b2 = last ? nB : cB + (size_t)(t + 2) * kstep;
;             const char* a3 = a2 + kstep; const char* b3 = b2 + kstep;
;             PG8_LDB(B0, 0, 0); PG8_LDB(B1, 0, 1); PG8_SCHED; PG8_LDA(At, 0, 0); PG8_STAGE(PG8_SA(1, 1), a1 + hstepA, voffA);
;             PG8_WAIT_V(8); PG8_WAIT_L(0); PG8_BAR; PG8_MMA(0, 0, At, B0); PG8_MMA(0, 1, At, B1); PG8_BAR; PG8_SCHED;
;             PG8_LDA(At, 0, 1); PG8_STAGE(PG8_SB(0, 0), b2, voffB); PG8_STAGE(PG8_SB(0, 1), b2 + hstepB, voffB); PG8_STAGE(PG8_SA(0, 0), a2, voffA);
;             PG8_WAIT_V(8); PG8_WAIT_L(0); PG8_BAR; PG8_MMA(1, 0, At, B0); PG8_MMA(1, 1, At, B1); PG8_BAR; PG8_SCHED;
.LBB0_3848:
	s_add_i32 s30, s10, 2
	s_add_u32 s31, s8, 0x80
	s_addc_u32 s11, s9, 0
	s_add_i32 s58, 0, 0x10000
	s_cmp_eq_u32 s62, s10
	s_cselect_b32 s11, s1, s11
	s_cselect_b32 s10, s0, s31
	v_add_u32_e32 v145, s58, v154
	s_cselect_b32 s35, s7, s29
	s_cselect_b32 s34, s6, s28
	s_add_i32 s31, 0, 0x14000
	ds_read_b128 v[146:149], v145
	ds_read_b128 v[150:153], v145 offset:1024
	ds_read_b128 v[174:177], v145 offset:2048
	ds_read_b128 v[178:181], v145 offset:3072
	v_add_u32_e32 v145, s31, v154
	ds_read_b128 v[182:185], v145
	ds_read_b128 v[186:189], v145 offset:1024
	ds_read_b128 v[190:193], v145 offset:2048
	ds_read_b128 v[194:197], v145 offset:3072
	v_lshl_add_u64 v[216:217], s[8:9], 0, v[142:143]
	s_add_i32 m0, s21, 0xc000
	ds_read_b128 v[198:201], v157
	ds_read_b128 v[202:205], v157 offset:1024
	ds_read_b128 v[206:209], v157 offset:2048
	ds_read_b128 v[222:225], v157 offset:3072
	ds_read_b128 v[226:229], v157 offset:4096
	ds_read_b128 v[230:233], v157 offset:5120
	ds_read_b128 v[234:237], v157 offset:6144
	ds_read_b128 v[238:241], v157 offset:7168
	global_load_lds_dwordx4 v[216:217], off
	v_lshl_add_u64 v[216:217], s[8:9], 0, v[140:141]
	s_add_i32 m0, s21, 0xe000
	s_nop 0
	global_load_lds_dwordx4 v[216:217], off
	s_waitcnt vmcnt(8)
	s_waitcnt lgkmcnt(0)
	s_barrier
	s_waitcnt lgkmcnt(0)
	v_mfma_f32_16x16x32_bf16 v[126:129], v[146:149], v[198:201], v[126:129]
	v_mfma_f32_16x16x32_bf16 v[118:121], v[174:177], v[198:201], v[118:121]
	v_mfma_f32_16x16x32_bf16 v[110:113], v[146:149], v[206:209], v[110:113]
	v_mfma_f32_16x16x32_bf16 v[102:105], v[174:177], v[206:209], v[102:105]
	v_mfma_f32_16x16x32_bf16 v[94:97], v[146:149], v[226:229], v[94:97]
	v_mfma_f32_16x16x32_bf16 v[86:89], v[174:177], v[226:229], v[86:89]
	v_mfma_f32_16x16x32_bf16 v[78:81], v[146:149], v[234:237], v[78:81]
	v_mfma_f32_16x16x32_bf16 v[70:73], v[174:177], v[234:237], v[70:73]
	v_mfma_f32_16x16x32_bf16 v[126:129], v[150:153], v[202:205], v[126:129]
	v_mfma_f32_16x16x32_bf16 v[118:121], v[178:181], v[202:205], v[118:121]
	v_mfma_f32_16x16x32_bf16 v[110:113], v[150:153], v[222:225], v[110:113]
	v_mfma_f32_16x16x32_bf16 v[102:105], v[178:181], v[222:225], v[102:105]
	v_mfma_f32_16x16x32_bf16 v[94:97], v[150:153], v[230:233], v[94:97]
	v_mfma_f32_16x16x32_bf16 v[86:89], v[178:181], v[230:233], v[86:89]
	v_mfma_f32_16x16x32_bf16 v[78:81], v[150:153], v[238:241], v[78:81]
	v_mfma_f32_16x16x32_bf16 v[70:73], v[178:181], v[238:241], v[70:73]
	v_mfma_f32_16x16x32_bf16 v[122:125], v[182:185], v[198:201], v[122:125]
	v_mfma_f32_16x16x32_bf16 v[114:117], v[190:193], v[198:201], v[114:117]
	v_mfma_f32_16x16x32_bf16 v[106:109], v[182:185], v[206:209], v[106:109]
	v_mfma_f32_16x16x32_bf16 v[98:101], v[190:193], v[206:209], v[98:101]
	v_mfma_f32_16x16x32_bf16 v[90:93], v[182:185], v[226:229], v[90:93]
	v_mfma_f32_16x16x32_bf16 v[82:85], v[190:193], v[226:229], v[82:85]
	v_mfma_f32_16x16x32_bf16 v[74:77], v[182:185], v[234:237], v[74:77]
	v_mfma_f32_16x16x32_bf16 v[66:69], v[190:193], v[234:237], v[66:69]
	v_mfma_f32_16x16x32_bf16 v[122:125], v[186:189], v[202:205], v[122:125]
	v_mfma_f32_16x16x32_bf16 v[114:117], v[194:197], v[202:205], v[114:117]
	v_mfma_f32_16x16x32_bf16 v[106:109], v[186:189], v[222:225], v[106:109]
	v_mfma_f32_16x16x32_bf16 v[98:101], v[194:197], v[222:225], v[98:101]
	v_mfma_f32_16x16x32_bf16 v[90:93], v[186:189], v[230:233], v[90:93]
	v_mfma_f32_16x16x32_bf16 v[82:85], v[194:197], v[230:233], v[82:85]
	v_mfma_f32_16x16x32_bf16 v[74:77], v[186:189], v[238:241], v[74:77]
	v_mfma_f32_16x16x32_bf16 v[66:69], v[194:197], v[238:241], v[66:69]
	s_barrier
	s_add_i32 s58, s58, s20
	v_lshl_add_u64 v[216:217], s[34:35], 0, v[134:135]
	s_mov_b32 m0, s58
	ds_read_b128 v[198:201], v157 offset:16384
	ds_read_b128 v[202:205], v157 offset:17408
	ds_read_b128 v[206:209], v157 offset:18432
	ds_read_b128 v[222:225], v157 offset:19456
	ds_read_b128 v[226:229], v157 offset:20480
	ds_read_b128 v[230:233], v157 offset:21504
	ds_read_b128 v[234:237], v157 offset:22528
	ds_read_b128 v[238:241], v157 offset:23552
	global_load_lds_dwordx4 v[216:217], off
	s_add_i32 m0, s58, 0x2000
	v_lshl_add_u64 v[218:219], s[34:35], 0, v[130:131]
	s_add_u32 s34, s34, s42
	s_addc_u32 s35, s35, s43
	s_add_i32 s31, s31, s20
	global_load_lds_dwordx4 v[218:219], off
	v_lshl_add_u64 v[242:243], s[34:35], 0, v[134:135]
	s_mov_b32 m0, s31
	v_lshl_add_u64 v[244:245], s[34:35], 0, v[130:131]
	global_load_lds_dwordx4 v[242:243], off
	s_add_i32 m0, s31, 0x2000
	v_lshl_add_u64 v[246:247], s[10:11], 0, v[136:137]
	global_load_lds_dwordx4 v[244:245], off
	s_mov_b32 m0, s21
	v_lshl_add_u64 v[248:249], s[10:11], 0, v[132:133]
	global_load_lds_dwordx4 v[246:247], off
	s_mov_b32 m0, s22
	s_nop 0
	global_load_lds_dwordx4 v[248:249], off
	s_waitcnt vmcnt(8)
	s_waitcnt lgkmcnt(0)
	s_barrier
; #define PG8_STAGE(bufoff, gbase, voff) do { _Pragma("unroll") for (int _i = 0; _i < 2; ++_i) \
;         __builtin_amdgcn_global_load_lds((const unsigned*)((const char*)(gbase) + (voff)[_i]), (LAS unsigned*)(lds + (bufoff) + ldsw + _i * 8192), 16, 0, 0); } while (0)
; #define PG8_LDA(dst, b, h) do { _Pragma("unroll") for (int m = 0; m < 4; ++m) _Pragma("unroll") for (int k = 0; k < 2; ++k) dst[m][k] = *(const LAS bf16x8*)(lds + PG8_SA(b, h) + aoff + m * 2048 + k * 1024); } while (0)
; #define PG8_LDB(dst, b, h) do { _Pragma("unroll") for (int n = 0; n < 2; ++n) _Pragma("unroll") for (int k = 0; k < 2; ++k) dst[n][k] = *(const LAS bf16x8*)(lds + PG8_SB(b, h) + boff + n * 2048 + k * 1024); } while (0)
; #define PG8_MMA(ai, bj, At, Bt) do { __builtin_amdgcn_s_setprio(1); _Pragma("unroll") for (int m = 0; m < 4; ++m) _Pragma("unroll") for (int n = 0; n < 2; ++n) _Pragma("unroll") for (int k = 0; k < 2; ++k) \
;         acc[ai][bj][m][n] = __builtin_amdgcn_mfma_f32_16x16x32_bf16(Bt[n][k], At[m][k], acc[ai][bj][m][n], 0, 0, 0); __builtin_amdgcn_s_setprio(0); } while (0)
; #define PG8_WAIT_V(n) asm volatile("s_waitcnt vmcnt(" #n ")" ::: "memory")
; #define PG8_WAIT_L(n) asm volatile("s_waitcnt lgkmcnt(" #n ")" ::: "memory")
; #define PG8_BAR __builtin_amdgcn_s_barrier()
; #define PG8_SCHED __builtin_amdgcn_sched_barrier(0)
; template <class Epi>
; __device__ __forceinline__ void gemm_phase(LAS unsigned char* lds, const Gemm g, const StaticOrder& S, const Epi& E) {
;     ...
;             PG8_WAIT_V(8); PG8_WAIT_L(0); PG8_BAR; PG8_MMA(0, 0, At, B0); PG8_MMA(0, 1, At, B1); PG8_BAR; PG8_SCHED;
;             PG8_LDA(At, 0, 1); PG8_STAGE(PG8_SB(0, 0), b2, voffB); PG8_STAGE(PG8_SB(0, 1), b2 + hstepB, voffB); PG8_STAGE(PG8_SA(0, 0), a2, voffA);
;             PG8_WAIT_V(8); PG8_WAIT_L(0); PG8_BAR; PG8_MMA(1, 0, At, B0); PG8_MMA(1, 1, At, B1); PG8_BAR; PG8_SCHED;
;             PG8_LDB(B0, 1, 0); PG8_LDB(B1, 1, 1); PG8_SCHED; PG8_LDA(At, 1, 0); PG8_STAGE(PG8_SA(0, 1), a2 + hstepA, voffA);
;             PG8_WAIT_V(8); PG8_WAIT_L(0); PG8_BAR; PG8_MMA(0, 0, At, B0); PG8_MMA(0, 1, At, B1); PG8_BAR; PG8_SCHED;
	s_waitcnt lgkmcnt(0)
	v_mfma_f32_16x16x32_bf16 v[60:63], v[146:149], v[198:201], v[60:63]
	v_mfma_f32_16x16x32_bf16 v[52:55], v[174:177], v[198:201], v[52:55]
	v_mfma_f32_16x16x32_bf16 v[44:47], v[146:149], v[206:209], v[44:47]
	v_mfma_f32_16x16x32_bf16 v[36:39], v[174:177], v[206:209], v[36:39]
	v_mfma_f32_16x16x32_bf16 v[28:31], v[146:149], v[226:229], v[28:31]
	v_mfma_f32_16x16x32_bf16 v[20:23], v[174:177], v[226:229], v[20:23]
	v_mfma_f32_16x16x32_bf16 v[12:15], v[146:149], v[234:237], v[12:15]
	v_mfma_f32_16x16x32_bf16 v[4:7], v[174:177], v[234:237], v[4:7]
	v_mfma_f32_16x16x32_bf16 v[60:63], v[150:153], v[202:205], v[60:63]
	v_mfma_f32_16x16x32_bf16 v[52:55], v[178:181], v[202:205], v[52:55]
	v_mfma_f32_16x16x32_bf16 v[44:47], v[150:153], v[222:225], v[44:47]
	v_mfma_f32_16x16x32_bf16 v[36:39], v[178:181], v[222:225], v[36:39]
	v_mfma_f32_16x16x32_bf16 v[28:31], v[150:153], v[230:233], v[28:31]
	v_mfma_f32_16x16x32_bf16 v[20:23], v[178:181], v[230:233], v[20:23]
	v_mfma_f32_16x16x32_bf16 v[12:15], v[150:153], v[238:241], v[12:15]
	v_mfma_f32_16x16x32_bf16 v[4:7], v[178:181], v[238:241], v[4:7]
	v_mfma_f32_16x16x32_bf16 v[56:59], v[182:185], v[198:201], v[56:59]
	v_mfma_f32_16x16x32_bf16 v[48:51], v[190:193], v[198:201], v[48:51]
	v_mfma_f32_16x16x32_bf16 v[40:43], v[182:185], v[206:209], v[40:43]
	v_mfma_f32_16x16x32_bf16 v[32:35], v[190:193], v[206:209], v[32:35]
	v_mfma_f32_16x16x32_bf16 v[24:27], v[182:185], v[226:229], v[24:27]
	v_mfma_f32_16x16x32_bf16 v[16:19], v[190:193], v[226:229], v[16:19]
	v_mfma_f32_16x16x32_bf16 v[8:11], v[182:185], v[234:237], v[8:11]
	v_mfma_f32_16x16x32_bf16 v[0:3], v[190:193], v[234:237], v[0:3]
	v_mfma_f32_16x16x32_bf16 v[56:59], v[186:189], v[202:205], v[56:59]
	v_mfma_f32_16x16x32_bf16 v[48:51], v[194:197], v[202:205], v[48:51]
	v_mfma_f32_16x16x32_bf16 v[40:43], v[186:189], v[222:225], v[40:43]
	v_mfma_f32_16x16x32_bf16 v[32:35], v[194:197], v[222:225], v[32:35]
	v_mfma_f32_16x16x32_bf16 v[24:27], v[186:189], v[230:233], v[24:27]
	v_mfma_f32_16x16x32_bf16 v[16:19], v[194:197], v[230:233], v[16:19]
	v_mfma_f32_16x16x32_bf16 v[8:11], v[186:189], v[238:241], v[8:11]
	v_mfma_f32_16x16x32_bf16 v[0:3], v[194:197], v[238:241], v[0:3]
	s_barrier
	s_add_i32 s31, 0, 0x18000
	v_add_u32_e32 v145, s31, v154
	s_add_i32 s34, 0, 0x1c000
	ds_read_b128 v[146:149], v145
	ds_read_b128 v[150:153], v145 offset:1024
	ds_read_b128 v[174:177], v145 offset:2048
	ds_read_b128 v[178:181], v145 offset:3072
	v_add_u32_e32 v145, s34, v154
	ds_read_b128 v[182:185], v145
	ds_read_b128 v[186:189], v145 offset:1024
	ds_read_b128 v[190:193], v145 offset:2048
	ds_read_b128 v[194:197], v145 offset:3072
	s_add_u32 s10, s10, s4
	s_addc_u32 s11, s11, s5
	s_mov_b32 m0, s23
	v_lshl_add_u64 v[250:251], s[10:11], 0, v[136:137]
	ds_read_b128 v[198:201], v157 offset:32768
	ds_read_b128 v[202:205], v157 offset:33792
	ds_read_b128 v[206:209], v157 offset:34816
	ds_read_b128 v[222:225], v157 offset:35840
	ds_read_b128 v[226:229], v157 offset:36864
	ds_read_b128 v[230:233], v157 offset:37888
	ds_read_b128 v[234:237], v157 offset:38912
	ds_read_b128 v[238:241], v157 offset:39936
	global_load_lds_dwordx4 v[250:251], off
	v_lshl_add_u64 v[250:251], s[10:11], 0, v[132:133]
	s_mov_b32 m0, s24
	s_nop 0
	global_load_lds_dwordx4 v[250:251], off
	s_waitcnt vmcnt(8)
	s_waitcnt lgkmcnt(0)
	s_barrier
	s_waitcnt lgkmcnt(0)
	v_mfma_f32_16x16x32_bf16 v[126:129], v[146:149], v[198:201], v[126:129]
	v_mfma_f32_16x16x32_bf16 v[118:121], v[174:177], v[198:201], v[118:121]
	v_mfma_f32_16x16x32_bf16 v[110:113], v[146:149], v[206:209], v[110:113]
	v_mfma_f32_16x16x32_bf16 v[102:105], v[174:177], v[206:209], v[102:105]
	v_mfma_f32_16x16x32_bf16 v[94:97], v[146:149], v[226:229], v[94:97]
	v_mfma_f32_16x16x32_bf16 v[86:89], v[174:177], v[226:229], v[86:89]
	v_mfma_f32_16x16x32_bf16 v[78:81], v[146:149], v[234:237], v[78:81]
	v_mfma_f32_16x16x32_bf16 v[70:73], v[174:177], v[234:237], v[70:73]
	v_mfma_f32_16x16x32_bf16 v[126:129], v[150:153], v[202:205], v[126:129]
	v_mfma_f32_16x16x32_bf16 v[118:121], v[178:181], v[202:205], v[118:121]
	v_mfma_f32_16x16x32_bf16 v[110:113], v[150:153], v[222:225], v[110:113]
	v_mfma_f32_16x16x32_bf16 v[102:105], v[178:181], v[222:225], v[102:105]
	v_mfma_f32_16x16x32_bf16 v[94:97], v[150:153], v[230:233], v[94:97]
	v_mfma_f32_16x16x32_bf16 v[86:89], v[178:181], v[230:233], v[86:89]
	v_mfma_f32_16x16x32_bf16 v[78:81], v[150:153], v[238:241], v[78:81]
	v_mfma_f32_16x16x32_bf16 v[70:73], v[178:181], v[238:241], v[70:73]
	v_mfma_f32_16x16x32_bf16 v[122:125], v[182:185], v[198:201], v[122:125]
	v_mfma_f32_16x16x32_bf16 v[114:117], v[190:193], v[198:201], v[114:117]
	v_mfma_f32_16x16x32_bf16 v[106:109], v[182:185], v[206:209], v[106:109]
	v_mfma_f32_16x16x32_bf16 v[98:101], v[190:193], v[206:209], v[98:101]
	v_mfma_f32_16x16x32_bf16 v[90:93], v[182:185], v[226:229], v[90:93]
	v_mfma_f32_16x16x32_bf16 v[82:85], v[190:193], v[226:229], v[82:85]
	v_mfma_f32_16x16x32_bf16 v[74:77], v[182:185], v[234:237], v[74:77]
	v_mfma_f32_16x16x32_bf16 v[66:69], v[190:193], v[234:237], v[66:69]
	v_mfma_f32_16x16x32_bf16 v[122:125], v[186:189], v[202:205], v[122:125]
	v_mfma_f32_16x16x32_bf16 v[114:117], v[194:197], v[202:205], v[114:117]
	v_mfma_f32_16x16x32_bf16 v[106:109], v[186:189], v[222:225], v[106:109]
	v_mfma_f32_16x16x32_bf16 v[98:101], v[194:197], v[222:225], v[98:101]
	v_mfma_f32_16x16x32_bf16 v[90:93], v[186:189], v[230:233], v[90:93]
	v_mfma_f32_16x16x32_bf16 v[82:85], v[194:197], v[230:233], v[82:85]
	v_mfma_f32_16x16x32_bf16 v[74:77], v[186:189], v[238:241], v[74:77]
	v_mfma_f32_16x16x32_bf16 v[66:69], v[194:197], v[238:241], v[66:69]
	s_barrier
; #define PG8_STAGE(bufoff, gbase, voff) do { _Pragma("unroll") for (int _i = 0; _i < 2; ++_i) \
;         __builtin_amdgcn_global_load_lds((const unsigned*)((const char*)(gbase) + (voff)[_i]), (LAS unsigned*)(lds + (bufoff) + ldsw + _i * 8192), 16, 0, 0); } while (0)
; #define PG8_LDA(dst, b, h) do { _Pragma("unroll") for (int m = 0; m < 4; ++m) _Pragma("unroll") for (int k = 0; k < 2; ++k) dst[m][k] = *(const LAS bf16x8*)(lds + PG8_SA(b, h) + aoff + m * 2048 + k * 1024); } while (0)
; #define PG8_MMA(ai, bj, At, Bt) do { __builtin_amdgcn_s_setprio(1); _Pragma("unroll") for (int m = 0; m < 4; ++m) _Pragma("unroll") for (int n = 0; n < 2; ++n) _Pragma("unroll") for (int k = 0; k < 2; ++k) \
;         acc[ai][bj][m][n] = __builtin_amdgcn_mfma_f32_16x16x32_bf16(Bt[n][k], At[m][k], acc[ai][bj][m][n], 0, 0, 0); __builtin_amdgcn_s_setprio(0); } while (0)
; #define PG8_WAIT_V(n) asm volatile("s_waitcnt vmcnt(" #n ")" ::: "memory")
; #define PG8_WAIT_L(n) asm volatile("s_waitcnt lgkmcnt(" #n ")" ::: "memory")
; #define PG8_BAR __builtin_amdgcn_s_barrier()
; #define PG8_SCHED __builtin_amdgcn_sched_barrier(0)
; template <class Epi>
; __device__ __forceinline__ void gemm_phase(LAS unsigned char* lds, const Gemm g, const StaticOrder& S, const Epi& E) {
;     ...
;             PG8_LDA(At, 1, 1); PG8_STAGE(PG8_SB(1, 0), b3, voffB); PG8_STAGE(PG8_SB(1, 1), b3 + hstepB, voffB); PG8_STAGE(PG8_SA(1, 0), a3, voffA);
;             PG8_WAIT_V(8); PG8_WAIT_L(0); PG8_BAR; PG8_MMA(1, 0, At, B0); PG8_MMA(1, 1, At, B1); PG8_BAR; PG8_SCHED;
;         }
	s_add_i32 s10, s31, s20
	v_lshl_add_u64 v[216:217], v[216:217], 0, s[82:83]
	s_mov_b32 m0, s10
	ds_read_b128 v[198:201], v157 offset:49152
	ds_read_b128 v[202:205], v157 offset:50176
	ds_read_b128 v[206:209], v157 offset:51200
	ds_read_b128 v[222:225], v157 offset:52224
	ds_read_b128 v[226:229], v157 offset:53248
	ds_read_b128 v[230:233], v157 offset:54272
	ds_read_b128 v[234:237], v157 offset:55296
	ds_read_b128 v[238:241], v157 offset:56320
	global_load_lds_dwordx4 v[216:217], off
	v_lshl_add_u64 v[216:217], v[218:219], 0, s[82:83]
	s_add_i32 m0, s10, 0x2000
	s_add_i32 s10, s34, s20
	global_load_lds_dwordx4 v[216:217], off
	v_lshl_add_u64 v[216:217], v[242:243], 0, s[82:83]
	s_mov_b32 m0, s10
	s_nop 0
	global_load_lds_dwordx4 v[216:217], off
	v_lshl_add_u64 v[216:217], v[244:245], 0, s[82:83]
	s_add_i32 m0, s10, 0x2000
	s_nop 0
	global_load_lds_dwordx4 v[216:217], off
	v_lshl_add_u64 v[216:217], v[246:247], 0, s[82:83]
	s_mov_b32 m0, s25
	s_nop 0
	global_load_lds_dwordx4 v[216:217], off
	v_lshl_add_u64 v[216:217], v[248:249], 0, s[82:83]
	s_mov_b32 m0, s60
	s_nop 0
	global_load_lds_dwordx4 v[216:217], off
	s_waitcnt vmcnt(8)
	s_waitcnt lgkmcnt(0)
	s_barrier
	s_waitcnt lgkmcnt(0)
	v_mfma_f32_16x16x32_bf16 v[60:63], v[146:149], v[198:201], v[60:63]
	v_mfma_f32_16x16x32_bf16 v[52:55], v[174:177], v[198:201], v[52:55]
	v_mfma_f32_16x16x32_bf16 v[44:47], v[146:149], v[206:209], v[44:47]
	v_mfma_f32_16x16x32_bf16 v[36:39], v[174:177], v[206:209], v[36:39]
	v_mfma_f32_16x16x32_bf16 v[28:31], v[146:149], v[226:229], v[28:31]
	v_mfma_f32_16x16x32_bf16 v[20:23], v[174:177], v[226:229], v[20:23]
	v_mfma_f32_16x16x32_bf16 v[12:15], v[146:149], v[234:237], v[12:15]
	v_mfma_f32_16x16x32_bf16 v[4:7], v[174:177], v[234:237], v[4:7]
	v_mfma_f32_16x16x32_bf16 v[60:63], v[150:153], v[202:205], v[60:63]
	v_mfma_f32_16x16x32_bf16 v[52:55], v[178:181], v[202:205], v[52:55]
	v_mfma_f32_16x16x32_bf16 v[44:47], v[150:153], v[222:225], v[44:47]
	v_mfma_f32_16x16x32_bf16 v[36:39], v[178:181], v[222:225], v[36:39]
	v_mfma_f32_16x16x32_bf16 v[28:31], v[150:153], v[230:233], v[28:31]
	v_mfma_f32_16x16x32_bf16 v[20:23], v[178:181], v[230:233], v[20:23]
	v_mfma_f32_16x16x32_bf16 v[12:15], v[150:153], v[238:241], v[12:15]
	v_mfma_f32_16x16x32_bf16 v[4:7], v[178:181], v[238:241], v[4:7]
	v_mfma_f32_16x16x32_bf16 v[56:59], v[182:185], v[198:201], v[56:59]
	v_mfma_f32_16x16x32_bf16 v[48:51], v[190:193], v[198:201], v[48:51]
	v_mfma_f32_16x16x32_bf16 v[40:43], v[182:185], v[206:209], v[40:43]
	v_mfma_f32_16x16x32_bf16 v[32:35], v[190:193], v[206:209], v[32:35]
	v_mfma_f32_16x16x32_bf16 v[24:27], v[182:185], v[226:229], v[24:27]
	v_mfma_f32_16x16x32_bf16 v[16:19], v[190:193], v[226:229], v[16:19]
	v_mfma_f32_16x16x32_bf16 v[8:11], v[182:185], v[234:237], v[8:11]
	v_mfma_f32_16x16x32_bf16 v[0:3], v[190:193], v[234:237], v[0:3]
	v_mfma_f32_16x16x32_bf16 v[56:59], v[186:189], v[202:205], v[56:59]
	v_mfma_f32_16x16x32_bf16 v[48:51], v[194:197], v[202:205], v[48:51]
	v_mfma_f32_16x16x32_bf16 v[40:43], v[186:189], v[222:225], v[40:43]
	v_mfma_f32_16x16x32_bf16 v[32:35], v[194:197], v[222:225], v[32:35]
	v_mfma_f32_16x16x32_bf16 v[24:27], v[186:189], v[230:233], v[24:27]
	v_mfma_f32_16x16x32_bf16 v[16:19], v[194:197], v[230:233], v[16:19]
	v_mfma_f32_16x16x32_bf16 v[8:11], v[186:189], v[238:241], v[8:11]
	v_mfma_f32_16x16x32_bf16 v[0:3], v[194:197], v[238:241], v[0:3]
	s_barrier
	s_add_u32 s28, s28, 0x100
	s_addc_u32 s29, s29, 0
	s_add_u32 s8, s8, 0x100
	s_addc_u32 s9, s9, 0
	s_cmp_ge_i32 s30, s61
	s_mov_b32 s10, s30
	s_cbranch_scc0 .LBB0_3848

; #define PG8_STAGE(bufoff, gbase, voff) do { _Pragma("unroll") for (int _i = 0; _i < 2; ++_i) \
;         __builtin_amdgcn_global_load_lds((const unsigned*)((const char*)(gbase) + (voff)[_i]), (LAS unsigned*)(lds + (bufoff) + ldsw + _i * 8192), 16, 0, 0); } while (0)
; #define PG8_LDA(dst, b, h) do { _Pragma("unroll") for (int m = 0; m < 4; ++m) _Pragma("unroll") for (int k = 0; k < 2; ++k) dst[m][k] = *(const LAS bf16x8*)(lds + PG8_SA(b, h) + aoff + m * 2048 + k * 1024); } while (0)
; #define PG8_LDB(dst, b, h) do { _Pragma("unroll") for (int n = 0; n < 2; ++n) _Pragma("unroll") for (int k = 0; k < 2; ++k) dst[n][k] = *(const LAS bf16x8*)(lds + PG8_SB(b, h) + boff + n * 2048 + k * 1024); } while (0)
; #define PG8_MMA(ai, bj, At, Bt) do { __builtin_amdgcn_s_setprio(1); _Pragma("unroll") for (int m = 0; m < 4; ++m) _Pragma("unroll") for (int n = 0; n < 2; ++n) _Pragma("unroll") for (int k = 0; k < 2; ++k) \
;         acc[ai][bj][m][n] = __builtin_amdgcn_mfma_f32_16x16x32_bf16(Bt[n][k], At[m][k], acc[ai][bj][m][n], 0, 0, 0); __builtin_amdgcn_s_setprio(0); } while (0)
; #define PG8_WAIT_V(n) asm volatile("s_waitcnt vmcnt(" #n ")" ::: "memory")
; #define PG8_WAIT_L(n) asm volatile("s_waitcnt lgkmcnt(" #n ")" ::: "memory")
; #define PG8_BAR __builtin_amdgcn_s_barrier()
; #define PG8_SCHED __builtin_amdgcn_sched_barrier(0)
; template <class Epi>
; __device__ __forceinline__ void gemm_phase(LAS unsigned char* lds, const Gemm g, const StaticOrder& S, const Epi& E) {
;     ...
;         for (int t = 0; t < nt; t += 2) {
;             const bool last = (t == nt - 2);
;             const char* a1 = cA + (size_t)(t + 1) * kstep;
;             const char* a2 = last ? nA : cA + (size_t)(t + 2) * kstep; const char* b2 = last ? nB : cB + (size_t)(t + 2) * kstep;
;             const char* a3 = a2 + kstep; const char* b3 = b2 + kstep;
;             PG8_LDB(B0, 0, 0); PG8_LDB(B1, 0, 1); PG8_SCHED; PG8_LDA(At, 0, 0); PG8_STAGE(PG8_SA(1, 1), a1 + hstepA, voffA);
;             PG8_WAIT_V(8); PG8_WAIT_L(0); PG8_BAR; PG8_MMA(0, 0, At, B0); PG8_MMA(0, 1, At, B1); PG8_BAR; PG8_SCHED;
;             PG8_LDA(At, 0, 1); PG8_STAGE(PG8_SB(0, 0), b2, voffB); PG8_STAGE(PG8_SB(0, 1), b2 + hstepB, voffB); PG8_STAGE(PG8_SA(0, 0), a2, voffA);
;             PG8_WAIT_V(8); PG8_WAIT_L(0); PG8_BAR; PG8_MMA(1, 0, At, B0); PG8_MMA(1, 1, At, B1); PG8_BAR; PG8_SCHED;
.LBB0_3925:
	s_add_i32 s29, s10, 2
	s_add_u32 s30, s38, 0x80
	s_addc_u32 s11, s39, 0
	s_add_i32 s34, 0, 0x10000
	s_cmp_eq_u32 s96, s10
	s_cselect_b32 s11, s1, s11
	s_cselect_b32 s10, s0, s30
	s_cselect_b32 s31, s69, s28
	s_cselect_b32 s30, s68, s27
	s_add_i32 s35, 0, 0x14000
	v_add_u32_e32 v142, s34, v181
	v_add_u32_e32 v186, s35, v181
	ds_read_b128 v[130:133], v142
	ds_read_b128 v[134:137], v142 offset:1024
	ds_read_b128 v[138:141], v142 offset:2048
	ds_read_b128 v[142:145], v142 offset:3072
	ds_read_b128 v[146:149], v186
	ds_read_b128 v[150:153], v186 offset:1024
	ds_read_b128 v[154:157], v186 offset:2048
	ds_read_b128 v[186:189], v186 offset:3072
	v_lshl_add_u64 v[202:203], s[38:39], 0, v[184:185]
	s_add_i32 m0, s21, 0xc000
	ds_read_b128 v[190:193], v204
	ds_read_b128 v[194:197], v204 offset:1024
	ds_read_b128 v[198:201], v204 offset:2048
	ds_read_b128 v[206:209], v204 offset:3072
	ds_read_b128 v[222:225], v204 offset:4096
	ds_read_b128 v[226:229], v204 offset:5120
	ds_read_b128 v[230:233], v204 offset:6144
	ds_read_b128 v[234:237], v204 offset:7168
	global_load_lds_dwordx4 v[202:203], off
	v_lshl_add_u64 v[202:203], s[38:39], 0, v[182:183]
	s_add_i32 m0, s21, 0xe000
	s_nop 0
	global_load_lds_dwordx4 v[202:203], off
	s_waitcnt vmcnt(8)
	s_waitcnt lgkmcnt(0)
	s_barrier
	s_waitcnt lgkmcnt(0)
	v_mfma_f32_16x16x32_bf16 v[122:125], v[130:133], v[190:193], v[122:125]
	v_mfma_f32_16x16x32_bf16 v[126:129], v[138:141], v[190:193], v[126:129]
	v_mfma_f32_16x16x32_bf16 v[110:113], v[130:133], v[198:201], v[110:113]
	v_mfma_f32_16x16x32_bf16 v[106:109], v[138:141], v[198:201], v[106:109]
	v_mfma_f32_16x16x32_bf16 v[94:97], v[130:133], v[222:225], v[94:97]
	v_mfma_f32_16x16x32_bf16 v[90:93], v[138:141], v[222:225], v[90:93]
	v_mfma_f32_16x16x32_bf16 v[78:81], v[130:133], v[230:233], v[78:81]
	v_mfma_f32_16x16x32_bf16 v[74:77], v[138:141], v[230:233], v[74:77]
	v_mfma_f32_16x16x32_bf16 v[122:125], v[134:137], v[194:197], v[122:125]
	v_mfma_f32_16x16x32_bf16 v[126:129], v[142:145], v[194:197], v[126:129]
	v_mfma_f32_16x16x32_bf16 v[110:113], v[134:137], v[206:209], v[110:113]
	v_mfma_f32_16x16x32_bf16 v[106:109], v[142:145], v[206:209], v[106:109]
	v_mfma_f32_16x16x32_bf16 v[94:97], v[134:137], v[226:229], v[94:97]
	v_mfma_f32_16x16x32_bf16 v[90:93], v[142:145], v[226:229], v[90:93]
	v_mfma_f32_16x16x32_bf16 v[78:81], v[134:137], v[234:237], v[78:81]
	v_mfma_f32_16x16x32_bf16 v[74:77], v[142:145], v[234:237], v[74:77]
	v_mfma_f32_16x16x32_bf16 v[118:121], v[146:149], v[190:193], v[118:121]
	v_mfma_f32_16x16x32_bf16 v[114:117], v[154:157], v[190:193], v[114:117]
	v_mfma_f32_16x16x32_bf16 v[102:105], v[146:149], v[198:201], v[102:105]
	v_mfma_f32_16x16x32_bf16 v[98:101], v[154:157], v[198:201], v[98:101]
	v_mfma_f32_16x16x32_bf16 v[86:89], v[146:149], v[222:225], v[86:89]
	v_mfma_f32_16x16x32_bf16 v[82:85], v[154:157], v[222:225], v[82:85]
	v_mfma_f32_16x16x32_bf16 v[70:73], v[146:149], v[230:233], v[70:73]
	v_mfma_f32_16x16x32_bf16 v[66:69], v[154:157], v[230:233], v[66:69]
	v_mfma_f32_16x16x32_bf16 v[118:121], v[150:153], v[194:197], v[118:121]
	v_mfma_f32_16x16x32_bf16 v[114:117], v[186:189], v[194:197], v[114:117]
	v_mfma_f32_16x16x32_bf16 v[102:105], v[150:153], v[206:209], v[102:105]
	v_mfma_f32_16x16x32_bf16 v[98:101], v[186:189], v[206:209], v[98:101]
	v_mfma_f32_16x16x32_bf16 v[86:89], v[150:153], v[226:229], v[86:89]
	v_mfma_f32_16x16x32_bf16 v[82:85], v[186:189], v[226:229], v[82:85]
	v_mfma_f32_16x16x32_bf16 v[70:73], v[150:153], v[234:237], v[70:73]
	v_mfma_f32_16x16x32_bf16 v[66:69], v[186:189], v[234:237], v[66:69]
	s_barrier
	s_add_i32 s34, s34, s20
	v_lshl_add_u64 v[202:203], s[30:31], 0, v[176:177]
	s_mov_b32 m0, s34
	ds_read_b128 v[190:193], v204 offset:16384
	ds_read_b128 v[194:197], v204 offset:17408
	ds_read_b128 v[198:201], v204 offset:18432
	ds_read_b128 v[206:209], v204 offset:19456
	ds_read_b128 v[222:225], v204 offset:20480
	ds_read_b128 v[226:229], v204 offset:21504
	ds_read_b128 v[230:233], v204 offset:22528
	ds_read_b128 v[234:237], v204 offset:23552
	global_load_lds_dwordx4 v[202:203], off
	s_add_i32 m0, s34, 0x2000
	v_lshl_add_u64 v[216:217], s[30:31], 0, v[172:173]
	s_add_u32 s30, s30, s46
	s_addc_u32 s31, s31, s47
	s_add_i32 s34, s35, s20
	global_load_lds_dwordx4 v[216:217], off
	v_lshl_add_u64 v[218:219], s[30:31], 0, v[176:177]
	s_mov_b32 m0, s34
	v_lshl_add_u64 v[238:239], s[30:31], 0, v[172:173]
	global_load_lds_dwordx4 v[218:219], off
	s_add_i32 m0, s34, 0x2000
	v_lshl_add_u64 v[240:241], s[10:11], 0, v[178:179]
	global_load_lds_dwordx4 v[238:239], off
	s_mov_b32 m0, s21
	v_lshl_add_u64 v[242:243], s[10:11], 0, v[174:175]
	global_load_lds_dwordx4 v[240:241], off
	s_mov_b32 m0, s22
	s_nop 0
	global_load_lds_dwordx4 v[242:243], off
	s_waitcnt vmcnt(8)
	s_waitcnt lgkmcnt(0)
	s_barrier
; #define PG8_STAGE(bufoff, gbase, voff) do { _Pragma("unroll") for (int _i = 0; _i < 2; ++_i) \
;         __builtin_amdgcn_global_load_lds((const unsigned*)((const char*)(gbase) + (voff)[_i]), (LAS unsigned*)(lds + (bufoff) + ldsw + _i * 8192), 16, 0, 0); } while (0)
; #define PG8_LDA(dst, b, h) do { _Pragma("unroll") for (int m = 0; m < 4; ++m) _Pragma("unroll") for (int k = 0; k < 2; ++k) dst[m][k] = *(const LAS bf16x8*)(lds + PG8_SA(b, h) + aoff + m * 2048 + k * 1024); } while (0)
; #define PG8_LDB(dst, b, h) do { _Pragma("unroll") for (int n = 0; n < 2; ++n) _Pragma("unroll") for (int k = 0; k < 2; ++k) dst[n][k] = *(const LAS bf16x8*)(lds + PG8_SB(b, h) + boff + n * 2048 + k * 1024); } while (0)
; #define PG8_MMA(ai, bj, At, Bt) do { __builtin_amdgcn_s_setprio(1); _Pragma("unroll") for (int m = 0; m < 4; ++m) _Pragma("unroll") for (int n = 0; n < 2; ++n) _Pragma("unroll") for (int k = 0; k < 2; ++k) \
;         acc[ai][bj][m][n] = __builtin_amdgcn_mfma_f32_16x16x32_bf16(Bt[n][k], At[m][k], acc[ai][bj][m][n], 0, 0, 0); __builtin_amdgcn_s_setprio(0); } while (0)
; #define PG8_WAIT_V(n) asm volatile("s_waitcnt vmcnt(" #n ")" ::: "memory")
; #define PG8_WAIT_L(n) asm volatile("s_waitcnt lgkmcnt(" #n ")" ::: "memory")
; #define PG8_BAR __builtin_amdgcn_s_barrier()
; #define PG8_SCHED __builtin_amdgcn_sched_barrier(0)
; template <class Epi>
; __device__ __forceinline__ void gemm_phase(LAS unsigned char* lds, const Gemm g, const StaticOrder& S, const Epi& E) {
;     ...
;             PG8_WAIT_V(8); PG8_WAIT_L(0); PG8_BAR; PG8_MMA(0, 0, At, B0); PG8_MMA(0, 1, At, B1); PG8_BAR; PG8_SCHED;
;             PG8_LDA(At, 0, 1); PG8_STAGE(PG8_SB(0, 0), b2, voffB); PG8_STAGE(PG8_SB(0, 1), b2 + hstepB, voffB); PG8_STAGE(PG8_SA(0, 0), a2, voffA);
;             PG8_WAIT_V(8); PG8_WAIT_L(0); PG8_BAR; PG8_MMA(1, 0, At, B0); PG8_MMA(1, 1, At, B1); PG8_BAR; PG8_SCHED;
;             PG8_LDB(B0, 1, 0); PG8_LDB(B1, 1, 1); PG8_SCHED; PG8_LDA(At, 1, 0); PG8_STAGE(PG8_SA(0, 1), a2 + hstepA, voffA);
;             PG8_WAIT_V(8); PG8_WAIT_L(0); PG8_BAR; PG8_MMA(0, 0, At, B0); PG8_MMA(0, 1, At, B1); PG8_BAR; PG8_SCHED;
	s_waitcnt lgkmcnt(0)
	v_mfma_f32_16x16x32_bf16 v[60:63], v[130:133], v[190:193], v[60:63]
	v_mfma_f32_16x16x32_bf16 v[56:59], v[138:141], v[190:193], v[56:59]
	v_mfma_f32_16x16x32_bf16 v[44:47], v[130:133], v[198:201], v[44:47]
	v_mfma_f32_16x16x32_bf16 v[40:43], v[138:141], v[198:201], v[40:43]
	v_mfma_f32_16x16x32_bf16 v[28:31], v[130:133], v[222:225], v[28:31]
	v_mfma_f32_16x16x32_bf16 v[24:27], v[138:141], v[222:225], v[24:27]
	v_mfma_f32_16x16x32_bf16 v[12:15], v[130:133], v[230:233], v[12:15]
	v_mfma_f32_16x16x32_bf16 v[8:11], v[138:141], v[230:233], v[8:11]
	v_mfma_f32_16x16x32_bf16 v[60:63], v[134:137], v[194:197], v[60:63]
	v_mfma_f32_16x16x32_bf16 v[56:59], v[142:145], v[194:197], v[56:59]
	v_mfma_f32_16x16x32_bf16 v[44:47], v[134:137], v[206:209], v[44:47]
	v_mfma_f32_16x16x32_bf16 v[40:43], v[142:145], v[206:209], v[40:43]
	v_mfma_f32_16x16x32_bf16 v[28:31], v[134:137], v[226:229], v[28:31]
	v_mfma_f32_16x16x32_bf16 v[24:27], v[142:145], v[226:229], v[24:27]
	v_mfma_f32_16x16x32_bf16 v[12:15], v[134:137], v[234:237], v[12:15]
	v_mfma_f32_16x16x32_bf16 v[8:11], v[142:145], v[234:237], v[8:11]
	v_mfma_f32_16x16x32_bf16 v[52:55], v[146:149], v[190:193], v[52:55]
	v_mfma_f32_16x16x32_bf16 v[48:51], v[154:157], v[190:193], v[48:51]
	v_mfma_f32_16x16x32_bf16 v[36:39], v[146:149], v[198:201], v[36:39]
	v_mfma_f32_16x16x32_bf16 v[32:35], v[154:157], v[198:201], v[32:35]
	v_mfma_f32_16x16x32_bf16 v[20:23], v[146:149], v[222:225], v[20:23]
	v_mfma_f32_16x16x32_bf16 v[16:19], v[154:157], v[222:225], v[16:19]
	v_mfma_f32_16x16x32_bf16 v[4:7], v[146:149], v[230:233], v[4:7]
	v_mfma_f32_16x16x32_bf16 v[0:3], v[154:157], v[230:233], v[0:3]
	v_mfma_f32_16x16x32_bf16 v[52:55], v[150:153], v[194:197], v[52:55]
	v_mfma_f32_16x16x32_bf16 v[48:51], v[186:189], v[194:197], v[48:51]
	v_mfma_f32_16x16x32_bf16 v[36:39], v[150:153], v[206:209], v[36:39]
	v_mfma_f32_16x16x32_bf16 v[32:35], v[186:189], v[206:209], v[32:35]
	v_mfma_f32_16x16x32_bf16 v[20:23], v[150:153], v[226:229], v[20:23]
	v_mfma_f32_16x16x32_bf16 v[16:19], v[186:189], v[226:229], v[16:19]
	v_mfma_f32_16x16x32_bf16 v[4:7], v[150:153], v[234:237], v[4:7]
	v_mfma_f32_16x16x32_bf16 v[0:3], v[186:189], v[234:237], v[0:3]
	s_barrier
	s_add_i32 s30, 0, 0x18000
	s_add_i32 s31, 0, 0x1c000
	v_add_u32_e32 v142, s30, v181
	v_add_u32_e32 v186, s31, v181
	ds_read_b128 v[130:133], v142
	ds_read_b128 v[134:137], v142 offset:1024
	ds_read_b128 v[138:141], v142 offset:2048
	ds_read_b128 v[142:145], v142 offset:3072
	ds_read_b128 v[146:149], v186
	ds_read_b128 v[150:153], v186 offset:1024
	ds_read_b128 v[154:157], v186 offset:2048
	ds_read_b128 v[186:189], v186 offset:3072
	s_add_u32 s10, s10, s44
	s_addc_u32 s11, s11, s45
	s_mov_b32 m0, s23
	v_lshl_add_u64 v[244:245], s[10:11], 0, v[178:179]
	ds_read_b128 v[190:193], v204 offset:32768
	ds_read_b128 v[194:197], v204 offset:33792
	ds_read_b128 v[198:201], v204 offset:34816
	ds_read_b128 v[206:209], v204 offset:35840
	ds_read_b128 v[222:225], v204 offset:36864
	ds_read_b128 v[226:229], v204 offset:37888
	ds_read_b128 v[230:233], v204 offset:38912
	ds_read_b128 v[234:237], v204 offset:39936
	global_load_lds_dwordx4 v[244:245], off
	v_lshl_add_u64 v[244:245], s[10:11], 0, v[174:175]
	s_mov_b32 m0, s24
	s_nop 0
	global_load_lds_dwordx4 v[244:245], off
	s_waitcnt vmcnt(8)
	s_waitcnt lgkmcnt(0)
	s_barrier
	s_waitcnt lgkmcnt(0)
	v_mfma_f32_16x16x32_bf16 v[122:125], v[130:133], v[190:193], v[122:125]
	v_mfma_f32_16x16x32_bf16 v[126:129], v[138:141], v[190:193], v[126:129]
	v_mfma_f32_16x16x32_bf16 v[110:113], v[130:133], v[198:201], v[110:113]
	v_mfma_f32_16x16x32_bf16 v[106:109], v[138:141], v[198:201], v[106:109]
	v_mfma_f32_16x16x32_bf16 v[94:97], v[130:133], v[222:225], v[94:97]
	v_mfma_f32_16x16x32_bf16 v[90:93], v[138:141], v[222:225], v[90:93]
	v_mfma_f32_16x16x32_bf16 v[78:81], v[130:133], v[230:233], v[78:81]
	v_mfma_f32_16x16x32_bf16 v[74:77], v[138:141], v[230:233], v[74:77]
	v_mfma_f32_16x16x32_bf16 v[122:125], v[134:137], v[194:197], v[122:125]
	v_mfma_f32_16x16x32_bf16 v[126:129], v[142:145], v[194:197], v[126:129]
	v_mfma_f32_16x16x32_bf16 v[110:113], v[134:137], v[206:209], v[110:113]
	v_mfma_f32_16x16x32_bf16 v[106:109], v[142:145], v[206:209], v[106:109]
	v_mfma_f32_16x16x32_bf16 v[94:97], v[134:137], v[226:229], v[94:97]
	v_mfma_f32_16x16x32_bf16 v[90:93], v[142:145], v[226:229], v[90:93]
	v_mfma_f32_16x16x32_bf16 v[78:81], v[134:137], v[234:237], v[78:81]
	v_mfma_f32_16x16x32_bf16 v[74:77], v[142:145], v[234:237], v[74:77]
	v_mfma_f32_16x16x32_bf16 v[118:121], v[146:149], v[190:193], v[118:121]
	v_mfma_f32_16x16x32_bf16 v[114:117], v[154:157], v[190:193], v[114:117]
	v_mfma_f32_16x16x32_bf16 v[102:105], v[146:149], v[198:201], v[102:105]
	v_mfma_f32_16x16x32_bf16 v[98:101], v[154:157], v[198:201], v[98:101]
	v_mfma_f32_16x16x32_bf16 v[86:89], v[146:149], v[222:225], v[86:89]
	v_mfma_f32_16x16x32_bf16 v[82:85], v[154:157], v[222:225], v[82:85]
	v_mfma_f32_16x16x32_bf16 v[70:73], v[146:149], v[230:233], v[70:73]
	v_mfma_f32_16x16x32_bf16 v[66:69], v[154:157], v[230:233], v[66:69]
	v_mfma_f32_16x16x32_bf16 v[118:121], v[150:153], v[194:197], v[118:121]
	v_mfma_f32_16x16x32_bf16 v[114:117], v[186:189], v[194:197], v[114:117]
	v_mfma_f32_16x16x32_bf16 v[102:105], v[150:153], v[206:209], v[102:105]
	v_mfma_f32_16x16x32_bf16 v[98:101], v[186:189], v[206:209], v[98:101]
	v_mfma_f32_16x16x32_bf16 v[86:89], v[150:153], v[226:229], v[86:89]
	v_mfma_f32_16x16x32_bf16 v[82:85], v[186:189], v[226:229], v[82:85]
	v_mfma_f32_16x16x32_bf16 v[70:73], v[150:153], v[234:237], v[70:73]
	v_mfma_f32_16x16x32_bf16 v[66:69], v[186:189], v[234:237], v[66:69]
	s_barrier
; #define PG8_STAGE(bufoff, gbase, voff) do { _Pragma("unroll") for (int _i = 0; _i < 2; ++_i) \
;         __builtin_amdgcn_global_load_lds((const unsigned*)((const char*)(gbase) + (voff)[_i]), (LAS unsigned*)(lds + (bufoff) + ldsw + _i * 8192), 16, 0, 0); } while (0)
; #define PG8_LDA(dst, b, h) do { _Pragma("unroll") for (int m = 0; m < 4; ++m) _Pragma("unroll") for (int k = 0; k < 2; ++k) dst[m][k] = *(const LAS bf16x8*)(lds + PG8_SA(b, h) + aoff + m * 2048 + k * 1024); } while (0)
; #define PG8_MMA(ai, bj, At, Bt) do { __builtin_amdgcn_s_setprio(1); _Pragma("unroll") for (int m = 0; m < 4; ++m) _Pragma("unroll") for (int n = 0; n < 2; ++n) _Pragma("unroll") for (int k = 0; k < 2; ++k) \
;         acc[ai][bj][m][n] = __builtin_amdgcn_mfma_f32_16x16x32_bf16(Bt[n][k], At[m][k], acc[ai][bj][m][n], 0, 0, 0); __builtin_amdgcn_s_setprio(0); } while (0)
; #define PG8_WAIT_V(n) asm volatile("s_waitcnt vmcnt(" #n ")" ::: "memory")
; #define PG8_WAIT_L(n) asm volatile("s_waitcnt lgkmcnt(" #n ")" ::: "memory")
; #define PG8_BAR __builtin_amdgcn_s_barrier()
; #define PG8_SCHED __builtin_amdgcn_sched_barrier(0)
; template <class Epi>
; __device__ __forceinline__ void gemm_phase(LAS unsigned char* lds, const Gemm g, const StaticOrder& S, const Epi& E) {
;     ...
;             PG8_LDA(At, 1, 1); PG8_STAGE(PG8_SB(1, 0), b3, voffB); PG8_STAGE(PG8_SB(1, 1), b3 + hstepB, voffB); PG8_STAGE(PG8_SA(1, 0), a3, voffA);
;             PG8_WAIT_V(8); PG8_WAIT_L(0); PG8_BAR; PG8_MMA(1, 0, At, B0); PG8_MMA(1, 1, At, B1); PG8_BAR; PG8_SCHED;
;         }
	s_add_i32 s10, s30, s20
	v_lshl_add_u64 v[202:203], v[202:203], 0, s[82:83]
	s_mov_b32 m0, s10
	ds_read_b128 v[190:193], v204 offset:49152
	ds_read_b128 v[194:197], v204 offset:50176
	ds_read_b128 v[198:201], v204 offset:51200
	ds_read_b128 v[206:209], v204 offset:52224
	ds_read_b128 v[222:225], v204 offset:53248
	ds_read_b128 v[226:229], v204 offset:54272
	ds_read_b128 v[230:233], v204 offset:55296
	ds_read_b128 v[234:237], v204 offset:56320
	global_load_lds_dwordx4 v[202:203], off
	v_lshl_add_u64 v[202:203], v[216:217], 0, s[82:83]
	s_add_i32 m0, s10, 0x2000
	s_add_i32 s10, s31, s20
	global_load_lds_dwordx4 v[202:203], off
	v_lshl_add_u64 v[202:203], v[218:219], 0, s[82:83]
	s_mov_b32 m0, s10
	s_nop 0
	global_load_lds_dwordx4 v[202:203], off
	v_lshl_add_u64 v[202:203], v[238:239], 0, s[82:83]
	s_add_i32 m0, s10, 0x2000
	s_nop 0
	global_load_lds_dwordx4 v[202:203], off
	v_lshl_add_u64 v[202:203], v[240:241], 0, s[82:83]
	s_mov_b32 m0, s25
	s_nop 0
	global_load_lds_dwordx4 v[202:203], off
	v_lshl_add_u64 v[202:203], v[242:243], 0, s[82:83]
	s_mov_b32 m0, s72
	s_nop 0
	global_load_lds_dwordx4 v[202:203], off
	s_waitcnt vmcnt(8)
	s_waitcnt lgkmcnt(0)
	s_barrier
	s_waitcnt lgkmcnt(0)
	v_mfma_f32_16x16x32_bf16 v[60:63], v[130:133], v[190:193], v[60:63]
	v_mfma_f32_16x16x32_bf16 v[56:59], v[138:141], v[190:193], v[56:59]
	v_mfma_f32_16x16x32_bf16 v[44:47], v[130:133], v[198:201], v[44:47]
	v_mfma_f32_16x16x32_bf16 v[40:43], v[138:141], v[198:201], v[40:43]
	v_mfma_f32_16x16x32_bf16 v[28:31], v[130:133], v[222:225], v[28:31]
	v_mfma_f32_16x16x32_bf16 v[24:27], v[138:141], v[222:225], v[24:27]
	v_mfma_f32_16x16x32_bf16 v[12:15], v[130:133], v[230:233], v[12:15]
	v_mfma_f32_16x16x32_bf16 v[8:11], v[138:141], v[230:233], v[8:11]
	v_mfma_f32_16x16x32_bf16 v[60:63], v[134:137], v[194:197], v[60:63]
	v_mfma_f32_16x16x32_bf16 v[56:59], v[142:145], v[194:197], v[56:59]
	v_mfma_f32_16x16x32_bf16 v[44:47], v[134:137], v[206:209], v[44:47]
	v_mfma_f32_16x16x32_bf16 v[40:43], v[142:145], v[206:209], v[40:43]
	v_mfma_f32_16x16x32_bf16 v[28:31], v[134:137], v[226:229], v[28:31]
	v_mfma_f32_16x16x32_bf16 v[24:27], v[142:145], v[226:229], v[24:27]
	v_mfma_f32_16x16x32_bf16 v[12:15], v[134:137], v[234:237], v[12:15]
	v_mfma_f32_16x16x32_bf16 v[8:11], v[142:145], v[234:237], v[8:11]
	v_mfma_f32_16x16x32_bf16 v[52:55], v[146:149], v[190:193], v[52:55]
	v_mfma_f32_16x16x32_bf16 v[48:51], v[154:157], v[190:193], v[48:51]
	v_mfma_f32_16x16x32_bf16 v[36:39], v[146:149], v[198:201], v[36:39]
	v_mfma_f32_16x16x32_bf16 v[32:35], v[154:157], v[198:201], v[32:35]
	v_mfma_f32_16x16x32_bf16 v[20:23], v[146:149], v[222:225], v[20:23]
	v_mfma_f32_16x16x32_bf16 v[16:19], v[154:157], v[222:225], v[16:19]
	v_mfma_f32_16x16x32_bf16 v[4:7], v[146:149], v[230:233], v[4:7]
	v_mfma_f32_16x16x32_bf16 v[0:3], v[154:157], v[230:233], v[0:3]
	v_mfma_f32_16x16x32_bf16 v[52:55], v[150:153], v[194:197], v[52:55]
	v_mfma_f32_16x16x32_bf16 v[48:51], v[186:189], v[194:197], v[48:51]
	v_mfma_f32_16x16x32_bf16 v[36:39], v[150:153], v[206:209], v[36:39]
	v_mfma_f32_16x16x32_bf16 v[32:35], v[186:189], v[206:209], v[32:35]
	v_mfma_f32_16x16x32_bf16 v[20:23], v[150:153], v[226:229], v[20:23]
	v_mfma_f32_16x16x32_bf16 v[16:19], v[186:189], v[226:229], v[16:19]
	v_mfma_f32_16x16x32_bf16 v[4:7], v[150:153], v[234:237], v[4:7]
	v_mfma_f32_16x16x32_bf16 v[0:3], v[186:189], v[234:237], v[0:3]
	s_barrier
	s_add_u32 s27, s27, 0x100
	s_addc_u32 s28, s28, 0
	s_add_u32 s38, s38, 0x100
	s_addc_u32 s39, s39, 0
	s_cmp_ge_i32 s29, s85
	s_mov_b32 s10, s29
	s_cbranch_scc0 .LBB0_3925
